# v29 + first K-loop iteration peeled with SrcC=0 (no accumulator zeroing) + buffer-1 B fragment reads via immediate offsets (2 VALU adds per iteration removed)
# speedup vs baseline: 1.0214x; 1.0032x over previous
; #define PG8_STAGE(bufoff, gbase, voff) do { _Pragma("unroll") for (int _i = 0; _i < 2; ++_i) \
;         __builtin_amdgcn_global_load_lds((const unsigned*)((const char*)(gbase) + (voff)[_i]), (PG8_LAS unsigned*)(lds + (bufoff) + ldsw + _i * 8192), 16, 0, 0); } while (0)
; #define PG8_LDA(dst, b, h) do { _Pragma("unroll") for (int m = 0; m < 4; ++m) _Pragma("unroll") for (int k = 0; k < 2; ++k) dst[m][k] = *(const PG8_LAS bf16x8*)(lds + PG8_SA(b, h) + aoff + m * 2048 + k * 1024); } while (0)
; #define PG8_LDB(dst, b, h) do { _Pragma("unroll") for (int n = 0; n < 2; ++n) _Pragma("unroll") for (int k = 0; k < 2; ++k) dst[n][k] = *(const PG8_LAS bf16x8*)(lds + PG8_SB(b, h) + boff + n * 2048 + k * 1024); } while (0)
; #define PG8_WAIT_V(n) asm volatile("s_waitcnt vmcnt(" #n ")" ::: "memory")
; #define PG8_WAIT_L(n) asm volatile("s_waitcnt lgkmcnt(" #n ")" ::: "memory")
; #define PG8_BAR __builtin_amdgcn_s_barrier()
; #define PG8_SCHED __builtin_amdgcn_sched_barrier(0)
; template <class Epi, class Sched, bool ALIGN_EPI = false, bool SP2 = false, bool A_TILED = false>
; __device__ __forceinline__ void gemm_phase(PG8_LAS unsigned char* lds, const Gemm g, const Sched& S, const Epi& E) {
;     ...
;     for (;;) {
;         const bool has_next = S.next(ui + 1, nxt);
;         const char* nA = has_next ? (const char*)g.A + (size_t)nxt.pm * tstepA : cA; const char* nB = has_next ? (const char*)g.Bt + (size_t)nxt.pn * tstepB : cB;
;         for (int t = 0; t < nt; t += 2) {
;             const bool last = (t == nt - 2);
;             const char* a1 = cA + (size_t)(t + 1) * kstepA;
;             const char* a2 = last ? nA : cA + (size_t)(t + 2) * kstepA; const char* b2 = last ? nB : cB + (size_t)(t + 2) * kstepB;
;             const char* a3 = a2 + kstepA; const char* b3 = b2 + kstepB;
;             if (last && has_next) S.a_ready(nxt);
;             if constexpr (SP2) {
;             PG8_LDB(B0, 0, 0); PG8_LDB(B1, 0, 1); PG8_SCHED; PG8_LDA(At, 0, 0); PG8_STAGE(PG8_SA(1, 1), a1 + hstepA, voffA);
;             PG8_WAIT_V(8); PG8_WAIT_L(0); PG8_BAR; PG8_MMA(0, 0, At, B0); PG8_MMA(0, 1, At, B1); PG8_BAR; PG8_SCHED;
;             PG8_LDA(At, 0, 1); PG8_STAGE(PG8_SB(0, 0), b2, voffB); PG8_STAGE(PG8_SB(0, 1), b2 + hstepB, voffB); PG8_STAGE(PG8_SA(0, 0), a2, voffA);
;             PG8_WAIT_V(8); PG8_WAIT_L(0); PG8_BAR; PG8_MMA(1, 0, At, B0); PG8_MMA(1, 1, At, B1); PG8_BAR; PG8_SCHED;
.LBB0_194:
	s_ashr_i32 s15, s14, 31
	s_lshl_b64 s[16:17], s[14:15], 21
	s_add_u32 s16, s78, s16
	s_addc_u32 s17, s79, s17
	s_and_b64 s[18:19], s[0:1], exec
	s_cselect_b32 s15, s17, s23
	s_cselect_b32 s59, s16, s22
	s_ashr_i32 s13, s12, 31
	s_lshl_b64 s[18:19], s[12:13], 21
	s_add_u32 s18, s3, s18
	s_addc_u32 s19, s33, s19
	s_and_b64 s[28:29], s[0:1], exec
	s_cselect_b32 s13, s19, s27
	s_cselect_b32 s62, s18, s26
	s_add_u32 s22, s22, 0xc000
	s_addc_u32 s23, s23, 0
	s_add_u32 s63, s26, 0x10000
	v_mov_b32_e32 v2, 0
	s_addc_u32 s69, s27, 0
	s_mov_b32 s70, -2
	ds_read_b128 v[168:171], v164
	ds_read_b128 v[172:175], v164 offset:1024
	ds_read_b128 v[176:179], v164 offset:2048
	ds_read_b128 v[180:183], v164 offset:3072
	ds_read_b128 v[184:187], v165
	ds_read_b128 v[188:191], v165 offset:1024
	ds_read_b128 v[192:195], v165 offset:2048
	ds_read_b128 v[196:199], v165 offset:3072
	s_add_u32 s26, s22, 0x4000
	s_addc_u32 s27, s23, 0
	s_cmp_eq_u32 s70, 60
	s_cselect_b32 s30, s59, s26
	s_cselect_b32 s31, s15, s27
	s_cselect_b32 s28, s62, s63
	s_cselect_b32 s29, s13, s69
	s_add_u32 s26, s30, 0x8000
	s_addc_u32 s27, s31, 0
	s_add_i32 m0, s36, 0xc000
	ds_read_b128 v[200:203], v166
	ds_read_b128 v[204:207], v166 offset:1024
	ds_read_b128 v[208:211], v166 offset:2048
	ds_read_b128 v[212:215], v166 offset:3072
	ds_read_b128 v[216:219], v166 offset:4096
	ds_read_b128 v[220:223], v166 offset:5120
	ds_read_b128 v[224:227], v166 offset:6144
	ds_read_b128 v[228:231], v166 offset:7168
	global_load_lds_dwordx4 v156, s[22:23]
	s_add_i32 m0, s36, 0xe000
	s_nop 0
	global_load_lds_dwordx4 v158, s[22:23]
	s_waitcnt vmcnt(8)
	s_waitcnt lgkmcnt(0)
	s_setprio 1
	s_barrier
	v_mfma_f32_16x16x32_bf16 v[126:129], v[168:171], v[200:203], 0
	v_mfma_f32_16x16x32_bf16 v[126:129], v[172:175], v[204:207], v[126:129]
	v_mfma_f32_16x16x32_bf16 v[118:121], v[176:179], v[200:203], 0
	v_mfma_f32_16x16x32_bf16 v[118:121], v[180:183], v[204:207], v[118:121]
	v_mfma_f32_16x16x32_bf16 v[122:125], v[184:187], v[200:203], 0
	v_mfma_f32_16x16x32_bf16 v[122:125], v[188:191], v[204:207], v[122:125]
	v_mfma_f32_16x16x32_bf16 v[114:117], v[192:195], v[200:203], 0
	v_mfma_f32_16x16x32_bf16 v[114:117], v[196:199], v[204:207], v[114:117]
	v_mfma_f32_16x16x32_bf16 v[110:113], v[168:171], v[208:211], 0
	v_mfma_f32_16x16x32_bf16 v[110:113], v[172:175], v[212:215], v[110:113]
	v_mfma_f32_16x16x32_bf16 v[102:105], v[176:179], v[208:211], 0
	v_mfma_f32_16x16x32_bf16 v[102:105], v[180:183], v[212:215], v[102:105]
	v_mfma_f32_16x16x32_bf16 v[106:109], v[184:187], v[208:211], 0
	v_mfma_f32_16x16x32_bf16 v[106:109], v[188:191], v[212:215], v[106:109]
	v_mfma_f32_16x16x32_bf16 v[98:101], v[192:195], v[208:211], 0
	v_mfma_f32_16x16x32_bf16 v[98:101], v[196:199], v[212:215], v[98:101]
	v_mfma_f32_16x16x32_bf16 v[94:97], v[168:171], v[216:219], 0
	v_mfma_f32_16x16x32_bf16 v[94:97], v[172:175], v[220:223], v[94:97]
	v_mfma_f32_16x16x32_bf16 v[86:89], v[176:179], v[216:219], 0
	v_mfma_f32_16x16x32_bf16 v[86:89], v[180:183], v[220:223], v[86:89]
	v_mfma_f32_16x16x32_bf16 v[90:93], v[184:187], v[216:219], 0
	v_mfma_f32_16x16x32_bf16 v[90:93], v[188:191], v[220:223], v[90:93]
	v_mfma_f32_16x16x32_bf16 v[82:85], v[192:195], v[216:219], 0
	v_mfma_f32_16x16x32_bf16 v[82:85], v[196:199], v[220:223], v[82:85]
	v_mfma_f32_16x16x32_bf16 v[78:81], v[168:171], v[224:227], 0
	v_mfma_f32_16x16x32_bf16 v[78:81], v[172:175], v[228:231], v[78:81]
	v_mfma_f32_16x16x32_bf16 v[70:73], v[176:179], v[224:227], 0
	v_mfma_f32_16x16x32_bf16 v[70:73], v[180:183], v[228:231], v[70:73]
	v_mfma_f32_16x16x32_bf16 v[74:77], v[184:187], v[224:227], 0
	v_mfma_f32_16x16x32_bf16 v[74:77], v[188:191], v[228:231], v[74:77]
	v_mfma_f32_16x16x32_bf16 v[66:69], v[192:195], v[224:227], 0
	v_mfma_f32_16x16x32_bf16 v[66:69], v[196:199], v[228:231], v[66:69]
	s_barrier
	s_setprio 0
	s_add_i32 s71, s45, s34
	s_mov_b32 m0, s71
	ds_read_b128 v[200:203], v166 offset:16384
	ds_read_b128 v[204:207], v166 offset:17408
	ds_read_b128 v[208:211], v166 offset:18432
	ds_read_b128 v[212:215], v166 offset:19456
	ds_read_b128 v[216:219], v166 offset:20480
	ds_read_b128 v[220:223], v166 offset:21504
	ds_read_b128 v[224:227], v166 offset:22528
	ds_read_b128 v[228:231], v166 offset:23552
	global_load_lds_dwordx4 v132, s[28:29]
	s_add_i32 m0, s71, 0x2000
	s_add_u32 s72, s28, 0x4000
	s_addc_u32 s73, s29, 0
	s_add_i32 s71, s58, s34
	global_load_lds_dwordx4 v136, s[28:29]
	s_mov_b32 m0, s71
	s_nop 0
	global_load_lds_dwordx4 v132, s[72:73]
	s_add_i32 m0, s71, 0x2000
	s_nop 0
	global_load_lds_dwordx4 v136, s[72:73]
	s_mov_b32 m0, s36
	s_nop 0
	global_load_lds_dwordx4 v130, s[30:31]
	s_mov_b32 m0, s37
	s_nop 0
	global_load_lds_dwordx4 v134, s[30:31]
	s_waitcnt vmcnt(8)
	s_waitcnt lgkmcnt(0)
	s_setprio 1
	s_barrier
; #define PG8_STAGE(bufoff, gbase, voff) do { _Pragma("unroll") for (int _i = 0; _i < 2; ++_i) \
;         __builtin_amdgcn_global_load_lds((const unsigned*)((const char*)(gbase) + (voff)[_i]), (PG8_LAS unsigned*)(lds + (bufoff) + ldsw + _i * 8192), 16, 0, 0); } while (0)
; #define PG8_LDA(dst, b, h) do { _Pragma("unroll") for (int m = 0; m < 4; ++m) _Pragma("unroll") for (int k = 0; k < 2; ++k) dst[m][k] = *(const PG8_LAS bf16x8*)(lds + PG8_SA(b, h) + aoff + m * 2048 + k * 1024); } while (0)
; #define PG8_LDB(dst, b, h) do { _Pragma("unroll") for (int n = 0; n < 2; ++n) _Pragma("unroll") for (int k = 0; k < 2; ++k) dst[n][k] = *(const PG8_LAS bf16x8*)(lds + PG8_SB(b, h) + boff + n * 2048 + k * 1024); } while (0)
; #define PG8_MMA(ai, bj, At, Bt) do { __builtin_amdgcn_s_setprio(1); _Pragma("unroll") for (int m = 0; m < 4; ++m) _Pragma("unroll") for (int n = 0; n < 2; ++n) _Pragma("unroll") for (int k = 0; k < 2; ++k) \
;         acc[ai][bj][m][n] = __builtin_amdgcn_mfma_f32_16x16x32_bf16(Bt[n][k], At[m][k], acc[ai][bj][m][n], 0, 0, 0); __builtin_amdgcn_s_setprio(0); } while (0)
; #define PG8_WAIT_V(n) asm volatile("s_waitcnt vmcnt(" #n ")" ::: "memory")
; #define PG8_WAIT_L(n) asm volatile("s_waitcnt lgkmcnt(" #n ")" ::: "memory")
; #define PG8_BAR __builtin_amdgcn_s_barrier()
; #define PG8_SCHED __builtin_amdgcn_sched_barrier(0)
; template <class Epi, class Sched, bool ALIGN_EPI = false, bool SP2 = false, bool A_TILED = false>
; __device__ __forceinline__ void gemm_phase(PG8_LAS unsigned char* lds, const Gemm g, const Sched& S, const Epi& E) {
;     ...
;             PG8_WAIT_V(8); PG8_WAIT_L(0); PG8_BAR; PG8_MMA(1, 0, At, B0); PG8_MMA(1, 1, At, B1); PG8_BAR; PG8_SCHED;
;             PG8_LDB(B0, 1, 0); PG8_LDB(B1, 1, 1); PG8_SCHED; PG8_LDA(At, 1, 0); PG8_STAGE(PG8_SA(0, 1), a2 + hstepA, voffA);
;             PG8_WAIT_V(8); PG8_WAIT_L(0); PG8_BAR; PG8_MMA(0, 0, At, B0); PG8_MMA(0, 1, At, B1); PG8_BAR; PG8_SCHED;
	v_mfma_f32_16x16x32_bf16 v[62:65], v[168:171], v[200:203], 0
	v_mfma_f32_16x16x32_bf16 v[62:65], v[172:175], v[204:207], v[62:65]
	v_mfma_f32_16x16x32_bf16 v[54:57], v[176:179], v[200:203], 0
	v_mfma_f32_16x16x32_bf16 v[54:57], v[180:183], v[204:207], v[54:57]
	v_mfma_f32_16x16x32_bf16 v[58:61], v[184:187], v[200:203], 0
	v_mfma_f32_16x16x32_bf16 v[58:61], v[188:191], v[204:207], v[58:61]
	v_mfma_f32_16x16x32_bf16 v[50:53], v[192:195], v[200:203], 0
	v_mfma_f32_16x16x32_bf16 v[50:53], v[196:199], v[204:207], v[50:53]
	v_mfma_f32_16x16x32_bf16 v[46:49], v[168:171], v[208:211], 0
	v_mfma_f32_16x16x32_bf16 v[46:49], v[172:175], v[212:215], v[46:49]
	v_mfma_f32_16x16x32_bf16 v[38:41], v[176:179], v[208:211], 0
	v_mfma_f32_16x16x32_bf16 v[38:41], v[180:183], v[212:215], v[38:41]
	v_mfma_f32_16x16x32_bf16 v[42:45], v[184:187], v[208:211], 0
	v_mfma_f32_16x16x32_bf16 v[42:45], v[188:191], v[212:215], v[42:45]
	v_mfma_f32_16x16x32_bf16 v[34:37], v[192:195], v[208:211], 0
	v_mfma_f32_16x16x32_bf16 v[34:37], v[196:199], v[212:215], v[34:37]
	v_mfma_f32_16x16x32_bf16 v[30:33], v[168:171], v[216:219], 0
	v_mfma_f32_16x16x32_bf16 v[30:33], v[172:175], v[220:223], v[30:33]
	v_mfma_f32_16x16x32_bf16 v[22:25], v[176:179], v[216:219], 0
	v_mfma_f32_16x16x32_bf16 v[22:25], v[180:183], v[220:223], v[22:25]
	v_mfma_f32_16x16x32_bf16 v[26:29], v[184:187], v[216:219], 0
	v_mfma_f32_16x16x32_bf16 v[26:29], v[188:191], v[220:223], v[26:29]
	v_mfma_f32_16x16x32_bf16 v[18:21], v[192:195], v[216:219], 0
	v_mfma_f32_16x16x32_bf16 v[18:21], v[196:199], v[220:223], v[18:21]
	v_mfma_f32_16x16x32_bf16 v[14:17], v[168:171], v[224:227], 0
	v_mfma_f32_16x16x32_bf16 v[14:17], v[172:175], v[228:231], v[14:17]
	v_mfma_f32_16x16x32_bf16 v[6:9], v[176:179], v[224:227], 0
	v_mfma_f32_16x16x32_bf16 v[6:9], v[180:183], v[228:231], v[6:9]
	v_mfma_f32_16x16x32_bf16 v[10:13], v[184:187], v[224:227], 0
	v_mfma_f32_16x16x32_bf16 v[10:13], v[188:191], v[228:231], v[10:13]
	v_mfma_f32_16x16x32_bf16 v[2:5], v[192:195], v[224:227], 0
	v_mfma_f32_16x16x32_bf16 v[2:5], v[196:199], v[228:231], v[2:5]
	s_barrier
	s_setprio 0
	s_add_i32 s71, 0, 0x18000
	s_add_i32 s72, 0, 0x1c000
	ds_read_b128 v[168:171], v164 offset:32768
	ds_read_b128 v[172:175], v164 offset:33792
	ds_read_b128 v[176:179], v164 offset:34816
	ds_read_b128 v[180:183], v164 offset:35840
	ds_read_b128 v[184:187], v164 offset:49152
	ds_read_b128 v[188:191], v164 offset:50176
	ds_read_b128 v[192:195], v164 offset:51200
	ds_read_b128 v[196:199], v164 offset:52224
	s_add_u32 s30, s30, 0x4000
	s_addc_u32 s31, s31, 0
	s_mov_b32 m0, s38
	ds_read_b128 v[200:203], v166 offset:32768
	ds_read_b128 v[204:207], v166 offset:33792
	ds_read_b128 v[208:211], v166 offset:34816
	ds_read_b128 v[212:215], v166 offset:35840
	ds_read_b128 v[216:219], v166 offset:36864
	ds_read_b128 v[220:223], v166 offset:37888
	ds_read_b128 v[224:227], v166 offset:38912
	ds_read_b128 v[228:231], v166 offset:39936
	global_load_lds_dwordx4 v130, s[30:31]
	s_mov_b32 m0, s39
	s_nop 0
	global_load_lds_dwordx4 v134, s[30:31]
	s_waitcnt vmcnt(8)
	s_waitcnt lgkmcnt(0)
	s_setprio 1
	s_barrier
	v_mfma_f32_16x16x32_bf16 v[126:129], v[168:171], v[200:203], v[126:129]
	v_mfma_f32_16x16x32_bf16 v[126:129], v[172:175], v[204:207], v[126:129]
	v_mfma_f32_16x16x32_bf16 v[118:121], v[176:179], v[200:203], v[118:121]
	v_mfma_f32_16x16x32_bf16 v[118:121], v[180:183], v[204:207], v[118:121]
	v_mfma_f32_16x16x32_bf16 v[122:125], v[184:187], v[200:203], v[122:125]
	v_mfma_f32_16x16x32_bf16 v[122:125], v[188:191], v[204:207], v[122:125]
	v_mfma_f32_16x16x32_bf16 v[114:117], v[192:195], v[200:203], v[114:117]
	v_mfma_f32_16x16x32_bf16 v[114:117], v[196:199], v[204:207], v[114:117]
	v_mfma_f32_16x16x32_bf16 v[110:113], v[168:171], v[208:211], v[110:113]
	v_mfma_f32_16x16x32_bf16 v[110:113], v[172:175], v[212:215], v[110:113]
	v_mfma_f32_16x16x32_bf16 v[102:105], v[176:179], v[208:211], v[102:105]
	v_mfma_f32_16x16x32_bf16 v[102:105], v[180:183], v[212:215], v[102:105]
	v_mfma_f32_16x16x32_bf16 v[106:109], v[184:187], v[208:211], v[106:109]
	v_mfma_f32_16x16x32_bf16 v[106:109], v[188:191], v[212:215], v[106:109]
	v_mfma_f32_16x16x32_bf16 v[98:101], v[192:195], v[208:211], v[98:101]
	v_mfma_f32_16x16x32_bf16 v[98:101], v[196:199], v[212:215], v[98:101]
	v_mfma_f32_16x16x32_bf16 v[94:97], v[168:171], v[216:219], v[94:97]
	v_mfma_f32_16x16x32_bf16 v[94:97], v[172:175], v[220:223], v[94:97]
	v_mfma_f32_16x16x32_bf16 v[86:89], v[176:179], v[216:219], v[86:89]
	v_mfma_f32_16x16x32_bf16 v[86:89], v[180:183], v[220:223], v[86:89]
	v_mfma_f32_16x16x32_bf16 v[90:93], v[184:187], v[216:219], v[90:93]
	v_mfma_f32_16x16x32_bf16 v[90:93], v[188:191], v[220:223], v[90:93]
	v_mfma_f32_16x16x32_bf16 v[82:85], v[192:195], v[216:219], v[82:85]
	v_mfma_f32_16x16x32_bf16 v[82:85], v[196:199], v[220:223], v[82:85]
	v_mfma_f32_16x16x32_bf16 v[78:81], v[168:171], v[224:227], v[78:81]
	v_mfma_f32_16x16x32_bf16 v[78:81], v[172:175], v[228:231], v[78:81]
	v_mfma_f32_16x16x32_bf16 v[70:73], v[176:179], v[224:227], v[70:73]
	v_mfma_f32_16x16x32_bf16 v[70:73], v[180:183], v[228:231], v[70:73]
	v_mfma_f32_16x16x32_bf16 v[74:77], v[184:187], v[224:227], v[74:77]
	v_mfma_f32_16x16x32_bf16 v[74:77], v[188:191], v[228:231], v[74:77]
	v_mfma_f32_16x16x32_bf16 v[66:69], v[192:195], v[224:227], v[66:69]
	v_mfma_f32_16x16x32_bf16 v[66:69], v[196:199], v[228:231], v[66:69]
	s_barrier
; #define PG8_STAGE(bufoff, gbase, voff) do { _Pragma("unroll") for (int _i = 0; _i < 2; ++_i) \
;         __builtin_amdgcn_global_load_lds((const unsigned*)((const char*)(gbase) + (voff)[_i]), (PG8_LAS unsigned*)(lds + (bufoff) + ldsw + _i * 8192), 16, 0, 0); } while (0)
; #define PG8_LDA(dst, b, h) do { _Pragma("unroll") for (int m = 0; m < 4; ++m) _Pragma("unroll") for (int k = 0; k < 2; ++k) dst[m][k] = *(const PG8_LAS bf16x8*)(lds + PG8_SA(b, h) + aoff + m * 2048 + k * 1024); } while (0)
; #define PG8_WAIT_V(n) asm volatile("s_waitcnt vmcnt(" #n ")" ::: "memory")
; #define PG8_WAIT_L(n) asm volatile("s_waitcnt lgkmcnt(" #n ")" ::: "memory")
; #define PG8_BAR __builtin_amdgcn_s_barrier()
; template <class Epi, class Sched, bool ALIGN_EPI = false, bool SP2 = false, bool A_TILED = false>
; __device__ __forceinline__ void gemm_phase(PG8_LAS unsigned char* lds, const Gemm g, const Sched& S, const Epi& E) {
;     ...
;         for (int t = 0; t < nt; t += 2) {
;             const bool last = (t == nt - 2);
;             const char* a1 = cA + (size_t)(t + 1) * kstepA;
;             const char* a2 = last ? nA : cA + (size_t)(t + 2) * kstepA; const char* b2 = last ? nB : cB + (size_t)(t + 2) * kstepB;
;             const char* a3 = a2 + kstepA; const char* b3 = b2 + kstepB;
;             if (last && has_next) S.a_ready(nxt);
;             if constexpr (SP2) {
;             PG8_LDB(B0, 0, 0); PG8_LDB(B1, 0, 1); PG8_SCHED; PG8_LDA(At, 0, 0); PG8_STAGE(PG8_SA(1, 1), a1 + hstepA, voffA);
;             PG8_WAIT_V(8); PG8_WAIT_L(0); PG8_BAR; PG8_MMA(0, 0, At, B0); PG8_MMA(0, 1, At, B1); PG8_BAR; PG8_SCHED;
;             PG8_LDA(At, 0, 1); PG8_STAGE(PG8_SB(0, 0), b2, voffB); PG8_STAGE(PG8_SB(0, 1), b2 + hstepB, voffB); PG8_STAGE(PG8_SA(0, 0), a2, voffA);
;             PG8_WAIT_V(8); PG8_WAIT_L(0); PG8_BAR; PG8_MMA(1, 0, At, B0); PG8_MMA(1, 1, At, B1); PG8_BAR; PG8_SCHED;
;             PG8_LDB(B0, 1, 0); PG8_LDB(B1, 1, 1); PG8_SCHED; PG8_LDA(At, 1, 0); PG8_STAGE(PG8_SA(0, 1), a2 + hstepA, voffA);
;             PG8_WAIT_V(8); PG8_WAIT_L(0); PG8_BAR; PG8_MMA(0, 0, At, B0); PG8_MMA(0, 1, At, B1); PG8_BAR; PG8_SCHED;
;             PG8_LDA(At, 1, 1); PG8_STAGE(PG8_SB(1, 0), b3, voffB); PG8_STAGE(PG8_SB(1, 1), b3 + hstepB, voffB); PG8_STAGE(PG8_SA(1, 0), a3, voffA);
;             PG8_WAIT_V(8); PG8_WAIT_L(0); PG8_BAR; PG8_MMA(1, 0, At, B0); PG8_MMA(1, 1, At, B1); PG8_BAR; PG8_SCHED;
	s_setprio 0
	s_add_u32 s30, s28, 0x8000
	s_addc_u32 s31, s29, 0
	s_add_i32 s71, s71, s34
	s_mov_b32 m0, s71
	ds_read_b128 v[200:203], v166 offset:49152
	ds_read_b128 v[204:207], v166 offset:50176
	ds_read_b128 v[208:211], v166 offset:51200
	ds_read_b128 v[212:215], v166 offset:52224
	ds_read_b128 v[216:219], v166 offset:53248
	ds_read_b128 v[220:223], v166 offset:54272
	ds_read_b128 v[224:227], v166 offset:55296
	ds_read_b128 v[228:231], v166 offset:56320
	global_load_lds_dwordx4 v132, s[30:31]
	s_add_i32 m0, s71, 0x2000
	s_add_u32 s28, s28, 0xc000
	v_lshl_add_u64 v[232:233], s[30:31], 0, v[136:137]
	s_addc_u32 s29, s29, 0
	s_add_i32 s30, s72, s34
	global_load_lds_dwordx4 v[232:233], off
	s_mov_b32 m0, s30
	s_nop 0
	global_load_lds_dwordx4 v132, s[28:29]
	s_add_i32 m0, s30, 0x2000
	s_nop 0
	global_load_lds_dwordx4 v136, s[28:29]
	s_mov_b32 m0, s43
	s_nop 0
	global_load_lds_dwordx4 v130, s[26:27]
	s_mov_b32 m0, s44
	s_nop 0
	global_load_lds_dwordx4 v134, s[26:27]
	s_waitcnt vmcnt(8)
	s_waitcnt lgkmcnt(0)
	s_setprio 1
	s_barrier
	v_mfma_f32_16x16x32_bf16 v[62:65], v[168:171], v[200:203], v[62:65]
	v_mfma_f32_16x16x32_bf16 v[62:65], v[172:175], v[204:207], v[62:65]
	v_mfma_f32_16x16x32_bf16 v[54:57], v[176:179], v[200:203], v[54:57]
	v_mfma_f32_16x16x32_bf16 v[54:57], v[180:183], v[204:207], v[54:57]
	v_mfma_f32_16x16x32_bf16 v[58:61], v[184:187], v[200:203], v[58:61]
	v_mfma_f32_16x16x32_bf16 v[58:61], v[188:191], v[204:207], v[58:61]
	v_mfma_f32_16x16x32_bf16 v[50:53], v[192:195], v[200:203], v[50:53]
	v_mfma_f32_16x16x32_bf16 v[50:53], v[196:199], v[204:207], v[50:53]
	v_mfma_f32_16x16x32_bf16 v[46:49], v[168:171], v[208:211], v[46:49]
	v_mfma_f32_16x16x32_bf16 v[46:49], v[172:175], v[212:215], v[46:49]
	v_mfma_f32_16x16x32_bf16 v[38:41], v[176:179], v[208:211], v[38:41]
	v_mfma_f32_16x16x32_bf16 v[38:41], v[180:183], v[212:215], v[38:41]
	v_mfma_f32_16x16x32_bf16 v[42:45], v[184:187], v[208:211], v[42:45]
	v_mfma_f32_16x16x32_bf16 v[42:45], v[188:191], v[212:215], v[42:45]
	v_mfma_f32_16x16x32_bf16 v[34:37], v[192:195], v[208:211], v[34:37]
	v_mfma_f32_16x16x32_bf16 v[34:37], v[196:199], v[212:215], v[34:37]
	v_mfma_f32_16x16x32_bf16 v[30:33], v[168:171], v[216:219], v[30:33]
	v_mfma_f32_16x16x32_bf16 v[30:33], v[172:175], v[220:223], v[30:33]
	v_mfma_f32_16x16x32_bf16 v[22:25], v[176:179], v[216:219], v[22:25]
	v_mfma_f32_16x16x32_bf16 v[22:25], v[180:183], v[220:223], v[22:25]
	v_mfma_f32_16x16x32_bf16 v[26:29], v[184:187], v[216:219], v[26:29]
	v_mfma_f32_16x16x32_bf16 v[26:29], v[188:191], v[220:223], v[26:29]
	v_mfma_f32_16x16x32_bf16 v[18:21], v[192:195], v[216:219], v[18:21]
	v_mfma_f32_16x16x32_bf16 v[18:21], v[196:199], v[220:223], v[18:21]
	v_mfma_f32_16x16x32_bf16 v[14:17], v[168:171], v[224:227], v[14:17]
	v_mfma_f32_16x16x32_bf16 v[14:17], v[172:175], v[228:231], v[14:17]
	v_mfma_f32_16x16x32_bf16 v[6:9], v[176:179], v[224:227], v[6:9]
	v_mfma_f32_16x16x32_bf16 v[6:9], v[180:183], v[228:231], v[6:9]
	v_mfma_f32_16x16x32_bf16 v[10:13], v[184:187], v[224:227], v[10:13]
	v_mfma_f32_16x16x32_bf16 v[10:13], v[188:191], v[228:231], v[10:13]
	v_mfma_f32_16x16x32_bf16 v[2:5], v[192:195], v[224:227], v[2:5]
	v_mfma_f32_16x16x32_bf16 v[2:5], v[196:199], v[228:231], v[2:5]
	s_barrier
	s_setprio 0
	s_add_i32 s70, s70, 2
	s_add_u32 s22, s22, 0x10000
	s_addc_u32 s23, s23, 0
	s_add_u32 s63, s63, 0x10000
	s_addc_u32 s69, s69, 0
.LBB0_195:
	ds_read_b128 v[168:171], v164
	ds_read_b128 v[172:175], v164 offset:1024
	ds_read_b128 v[176:179], v164 offset:2048
	ds_read_b128 v[180:183], v164 offset:3072
	ds_read_b128 v[184:187], v165
	ds_read_b128 v[188:191], v165 offset:1024
	ds_read_b128 v[192:195], v165 offset:2048
	ds_read_b128 v[196:199], v165 offset:3072
	s_add_u32 s26, s22, 0x4000
	s_addc_u32 s27, s23, 0
	s_cmp_eq_u32 s70, 60
	s_cselect_b32 s30, s59, s26
	s_cselect_b32 s31, s15, s27
	s_cselect_b32 s28, s62, s63
	s_cselect_b32 s29, s13, s69
	s_add_u32 s26, s30, 0x8000
	s_addc_u32 s27, s31, 0
	s_add_i32 m0, s36, 0xc000
	ds_read_b128 v[200:203], v166
	ds_read_b128 v[204:207], v166 offset:1024
	ds_read_b128 v[208:211], v166 offset:2048
	ds_read_b128 v[212:215], v166 offset:3072
	ds_read_b128 v[216:219], v166 offset:4096
	ds_read_b128 v[220:223], v166 offset:5120
	ds_read_b128 v[224:227], v166 offset:6144
	ds_read_b128 v[228:231], v166 offset:7168
	global_load_lds_dwordx4 v156, s[22:23]
	s_add_i32 m0, s36, 0xe000
	s_nop 0
	global_load_lds_dwordx4 v158, s[22:23]
	s_waitcnt vmcnt(8)
	s_waitcnt lgkmcnt(0)
	s_setprio 1
	s_barrier
; #define PG8_STAGE(bufoff, gbase, voff) do { _Pragma("unroll") for (int _i = 0; _i < 2; ++_i) \
;         __builtin_amdgcn_global_load_lds((const unsigned*)((const char*)(gbase) + (voff)[_i]), (PG8_LAS unsigned*)(lds + (bufoff) + ldsw + _i * 8192), 16, 0, 0); } while (0)
; #define PG8_LDA(dst, b, h) do { _Pragma("unroll") for (int m = 0; m < 4; ++m) _Pragma("unroll") for (int k = 0; k < 2; ++k) dst[m][k] = *(const PG8_LAS bf16x8*)(lds + PG8_SA(b, h) + aoff + m * 2048 + k * 1024); } while (0)
; #define PG8_LDB(dst, b, h) do { _Pragma("unroll") for (int n = 0; n < 2; ++n) _Pragma("unroll") for (int k = 0; k < 2; ++k) dst[n][k] = *(const PG8_LAS bf16x8*)(lds + PG8_SB(b, h) + boff + n * 2048 + k * 1024); } while (0)
; #define PG8_MMA(ai, bj, At, Bt) do { __builtin_amdgcn_s_setprio(1); _Pragma("unroll") for (int m = 0; m < 4; ++m) _Pragma("unroll") for (int n = 0; n < 2; ++n) _Pragma("unroll") for (int k = 0; k < 2; ++k) \
;         acc[ai][bj][m][n] = __builtin_amdgcn_mfma_f32_16x16x32_bf16(Bt[n][k], At[m][k], acc[ai][bj][m][n], 0, 0, 0); __builtin_amdgcn_s_setprio(0); } while (0)
; #define PG8_WAIT_V(n) asm volatile("s_waitcnt vmcnt(" #n ")" ::: "memory")
; #define PG8_WAIT_L(n) asm volatile("s_waitcnt lgkmcnt(" #n ")" ::: "memory")
; #define PG8_BAR __builtin_amdgcn_s_barrier()
; #define PG8_SCHED __builtin_amdgcn_sched_barrier(0)
; template <class Epi, class Sched, bool ALIGN_EPI = false, bool SP2 = false, bool A_TILED = false>
; __device__ __forceinline__ void gemm_phase(PG8_LAS unsigned char* lds, const Gemm g, const Sched& S, const Epi& E) {
;     ...
;             PG8_WAIT_V(8); PG8_WAIT_L(0); PG8_BAR; PG8_MMA(0, 0, At, B0); PG8_MMA(0, 1, At, B1); PG8_BAR; PG8_SCHED;
;             PG8_LDA(At, 0, 1); PG8_STAGE(PG8_SB(0, 0), b2, voffB); PG8_STAGE(PG8_SB(0, 1), b2 + hstepB, voffB); PG8_STAGE(PG8_SA(0, 0), a2, voffA);
;             PG8_WAIT_V(8); PG8_WAIT_L(0); PG8_BAR; PG8_MMA(1, 0, At, B0); PG8_MMA(1, 1, At, B1); PG8_BAR; PG8_SCHED;
;             PG8_LDB(B0, 1, 0); PG8_LDB(B1, 1, 1); PG8_SCHED; PG8_LDA(At, 1, 0); PG8_STAGE(PG8_SA(0, 1), a2 + hstepA, voffA);
;             PG8_WAIT_V(8); PG8_WAIT_L(0); PG8_BAR; PG8_MMA(0, 0, At, B0); PG8_MMA(0, 1, At, B1); PG8_BAR; PG8_SCHED;
	v_mfma_f32_16x16x32_bf16 v[126:129], v[168:171], v[200:203], v[126:129]
	v_mfma_f32_16x16x32_bf16 v[126:129], v[172:175], v[204:207], v[126:129]
	v_mfma_f32_16x16x32_bf16 v[118:121], v[176:179], v[200:203], v[118:121]
	v_mfma_f32_16x16x32_bf16 v[118:121], v[180:183], v[204:207], v[118:121]
	v_mfma_f32_16x16x32_bf16 v[122:125], v[184:187], v[200:203], v[122:125]
	v_mfma_f32_16x16x32_bf16 v[122:125], v[188:191], v[204:207], v[122:125]
	v_mfma_f32_16x16x32_bf16 v[114:117], v[192:195], v[200:203], v[114:117]
	v_mfma_f32_16x16x32_bf16 v[114:117], v[196:199], v[204:207], v[114:117]
	v_mfma_f32_16x16x32_bf16 v[110:113], v[168:171], v[208:211], v[110:113]
	v_mfma_f32_16x16x32_bf16 v[110:113], v[172:175], v[212:215], v[110:113]
	v_mfma_f32_16x16x32_bf16 v[102:105], v[176:179], v[208:211], v[102:105]
	v_mfma_f32_16x16x32_bf16 v[102:105], v[180:183], v[212:215], v[102:105]
	v_mfma_f32_16x16x32_bf16 v[106:109], v[184:187], v[208:211], v[106:109]
	v_mfma_f32_16x16x32_bf16 v[106:109], v[188:191], v[212:215], v[106:109]
	v_mfma_f32_16x16x32_bf16 v[98:101], v[192:195], v[208:211], v[98:101]
	v_mfma_f32_16x16x32_bf16 v[98:101], v[196:199], v[212:215], v[98:101]
	v_mfma_f32_16x16x32_bf16 v[94:97], v[168:171], v[216:219], v[94:97]
	v_mfma_f32_16x16x32_bf16 v[94:97], v[172:175], v[220:223], v[94:97]
	v_mfma_f32_16x16x32_bf16 v[86:89], v[176:179], v[216:219], v[86:89]
	v_mfma_f32_16x16x32_bf16 v[86:89], v[180:183], v[220:223], v[86:89]
	v_mfma_f32_16x16x32_bf16 v[90:93], v[184:187], v[216:219], v[90:93]
	v_mfma_f32_16x16x32_bf16 v[90:93], v[188:191], v[220:223], v[90:93]
	v_mfma_f32_16x16x32_bf16 v[82:85], v[192:195], v[216:219], v[82:85]
	v_mfma_f32_16x16x32_bf16 v[82:85], v[196:199], v[220:223], v[82:85]
	v_mfma_f32_16x16x32_bf16 v[78:81], v[168:171], v[224:227], v[78:81]
	v_mfma_f32_16x16x32_bf16 v[78:81], v[172:175], v[228:231], v[78:81]
	v_mfma_f32_16x16x32_bf16 v[70:73], v[176:179], v[224:227], v[70:73]
	v_mfma_f32_16x16x32_bf16 v[70:73], v[180:183], v[228:231], v[70:73]
	v_mfma_f32_16x16x32_bf16 v[74:77], v[184:187], v[224:227], v[74:77]
	v_mfma_f32_16x16x32_bf16 v[74:77], v[188:191], v[228:231], v[74:77]
	v_mfma_f32_16x16x32_bf16 v[66:69], v[192:195], v[224:227], v[66:69]
	v_mfma_f32_16x16x32_bf16 v[66:69], v[196:199], v[228:231], v[66:69]
	s_barrier
	s_setprio 0
	s_add_i32 s71, s45, s34
	s_mov_b32 m0, s71
	ds_read_b128 v[200:203], v166 offset:16384
	ds_read_b128 v[204:207], v166 offset:17408
	ds_read_b128 v[208:211], v166 offset:18432
	ds_read_b128 v[212:215], v166 offset:19456
	ds_read_b128 v[216:219], v166 offset:20480
	ds_read_b128 v[220:223], v166 offset:21504
	ds_read_b128 v[224:227], v166 offset:22528
	ds_read_b128 v[228:231], v166 offset:23552
	global_load_lds_dwordx4 v132, s[28:29]
	s_add_i32 m0, s71, 0x2000
	s_add_u32 s72, s28, 0x4000
	s_addc_u32 s73, s29, 0
	s_add_i32 s71, s58, s34
	global_load_lds_dwordx4 v136, s[28:29]
	s_mov_b32 m0, s71
	s_nop 0
	global_load_lds_dwordx4 v132, s[72:73]
	s_add_i32 m0, s71, 0x2000
	s_nop 0
	global_load_lds_dwordx4 v136, s[72:73]
	s_mov_b32 m0, s36
	s_nop 0
	global_load_lds_dwordx4 v130, s[30:31]
	s_mov_b32 m0, s37
	s_nop 0
	global_load_lds_dwordx4 v134, s[30:31]
	s_waitcnt vmcnt(8)
	s_waitcnt lgkmcnt(0)
	s_setprio 1
	s_barrier
	v_mfma_f32_16x16x32_bf16 v[62:65], v[168:171], v[200:203], v[62:65]
	v_mfma_f32_16x16x32_bf16 v[62:65], v[172:175], v[204:207], v[62:65]
	v_mfma_f32_16x16x32_bf16 v[54:57], v[176:179], v[200:203], v[54:57]
	v_mfma_f32_16x16x32_bf16 v[54:57], v[180:183], v[204:207], v[54:57]
	v_mfma_f32_16x16x32_bf16 v[58:61], v[184:187], v[200:203], v[58:61]
	v_mfma_f32_16x16x32_bf16 v[58:61], v[188:191], v[204:207], v[58:61]
	v_mfma_f32_16x16x32_bf16 v[50:53], v[192:195], v[200:203], v[50:53]
	v_mfma_f32_16x16x32_bf16 v[50:53], v[196:199], v[204:207], v[50:53]
	v_mfma_f32_16x16x32_bf16 v[46:49], v[168:171], v[208:211], v[46:49]
	v_mfma_f32_16x16x32_bf16 v[46:49], v[172:175], v[212:215], v[46:49]
	v_mfma_f32_16x16x32_bf16 v[38:41], v[176:179], v[208:211], v[38:41]
	v_mfma_f32_16x16x32_bf16 v[38:41], v[180:183], v[212:215], v[38:41]
	v_mfma_f32_16x16x32_bf16 v[42:45], v[184:187], v[208:211], v[42:45]
	v_mfma_f32_16x16x32_bf16 v[42:45], v[188:191], v[212:215], v[42:45]
	v_mfma_f32_16x16x32_bf16 v[34:37], v[192:195], v[208:211], v[34:37]
	v_mfma_f32_16x16x32_bf16 v[34:37], v[196:199], v[212:215], v[34:37]
	v_mfma_f32_16x16x32_bf16 v[30:33], v[168:171], v[216:219], v[30:33]
	v_mfma_f32_16x16x32_bf16 v[30:33], v[172:175], v[220:223], v[30:33]
	v_mfma_f32_16x16x32_bf16 v[22:25], v[176:179], v[216:219], v[22:25]
	v_mfma_f32_16x16x32_bf16 v[22:25], v[180:183], v[220:223], v[22:25]
	v_mfma_f32_16x16x32_bf16 v[26:29], v[184:187], v[216:219], v[26:29]
	v_mfma_f32_16x16x32_bf16 v[26:29], v[188:191], v[220:223], v[26:29]
	v_mfma_f32_16x16x32_bf16 v[18:21], v[192:195], v[216:219], v[18:21]
	v_mfma_f32_16x16x32_bf16 v[18:21], v[196:199], v[220:223], v[18:21]
	v_mfma_f32_16x16x32_bf16 v[14:17], v[168:171], v[224:227], v[14:17]
	v_mfma_f32_16x16x32_bf16 v[14:17], v[172:175], v[228:231], v[14:17]
	v_mfma_f32_16x16x32_bf16 v[6:9], v[176:179], v[224:227], v[6:9]
	v_mfma_f32_16x16x32_bf16 v[6:9], v[180:183], v[228:231], v[6:9]
	v_mfma_f32_16x16x32_bf16 v[10:13], v[184:187], v[224:227], v[10:13]
	v_mfma_f32_16x16x32_bf16 v[10:13], v[188:191], v[228:231], v[10:13]
	v_mfma_f32_16x16x32_bf16 v[2:5], v[192:195], v[224:227], v[2:5]
	v_mfma_f32_16x16x32_bf16 v[2:5], v[196:199], v[228:231], v[2:5]
	s_barrier
; #define PG8_STAGE(bufoff, gbase, voff) do { _Pragma("unroll") for (int _i = 0; _i < 2; ++_i) \
;         __builtin_amdgcn_global_load_lds((const unsigned*)((const char*)(gbase) + (voff)[_i]), (PG8_LAS unsigned*)(lds + (bufoff) + ldsw + _i * 8192), 16, 0, 0); } while (0)
; #define PG8_LDA(dst, b, h) do { _Pragma("unroll") for (int m = 0; m < 4; ++m) _Pragma("unroll") for (int k = 0; k < 2; ++k) dst[m][k] = *(const PG8_LAS bf16x8*)(lds + PG8_SA(b, h) + aoff + m * 2048 + k * 1024); } while (0)
; #define PG8_LDB(dst, b, h) do { _Pragma("unroll") for (int n = 0; n < 2; ++n) _Pragma("unroll") for (int k = 0; k < 2; ++k) dst[n][k] = *(const PG8_LAS bf16x8*)(lds + PG8_SB(b, h) + boff + n * 2048 + k * 1024); } while (0)
; #define PG8_MMA(ai, bj, At, Bt) do { __builtin_amdgcn_s_setprio(1); _Pragma("unroll") for (int m = 0; m < 4; ++m) _Pragma("unroll") for (int n = 0; n < 2; ++n) _Pragma("unroll") for (int k = 0; k < 2; ++k) \
;         acc[ai][bj][m][n] = __builtin_amdgcn_mfma_f32_16x16x32_bf16(Bt[n][k], At[m][k], acc[ai][bj][m][n], 0, 0, 0); __builtin_amdgcn_s_setprio(0); } while (0)
; #define PG8_WAIT_V(n) asm volatile("s_waitcnt vmcnt(" #n ")" ::: "memory")
; #define PG8_WAIT_L(n) asm volatile("s_waitcnt lgkmcnt(" #n ")" ::: "memory")
; #define PG8_BAR __builtin_amdgcn_s_barrier()
; #define PG8_SCHED __builtin_amdgcn_sched_barrier(0)
; template <class Epi, class Sched, bool ALIGN_EPI = false, bool SP2 = false, bool A_TILED = false>
; __device__ __forceinline__ void gemm_phase(PG8_LAS unsigned char* lds, const Gemm g, const Sched& S, const Epi& E) {
;     ...
;             PG8_LDB(B0, 1, 0); PG8_LDB(B1, 1, 1); PG8_SCHED; PG8_LDA(At, 1, 0); PG8_STAGE(PG8_SA(0, 1), a2 + hstepA, voffA);
;             PG8_WAIT_V(8); PG8_WAIT_L(0); PG8_BAR; PG8_MMA(0, 0, At, B0); PG8_MMA(0, 1, At, B1); PG8_BAR; PG8_SCHED;
;             PG8_LDA(At, 1, 1); PG8_STAGE(PG8_SB(1, 0), b3, voffB); PG8_STAGE(PG8_SB(1, 1), b3 + hstepB, voffB); PG8_STAGE(PG8_SA(1, 0), a3, voffA);
;             PG8_WAIT_V(8); PG8_WAIT_L(0); PG8_BAR; PG8_MMA(1, 0, At, B0); PG8_MMA(1, 1, At, B1); PG8_BAR; PG8_SCHED;
	s_setprio 0
	s_add_i32 s71, 0, 0x18000
	s_add_i32 s72, 0, 0x1c000
	ds_read_b128 v[168:171], v164 offset:32768
	ds_read_b128 v[172:175], v164 offset:33792
	ds_read_b128 v[176:179], v164 offset:34816
	ds_read_b128 v[180:183], v164 offset:35840
	ds_read_b128 v[184:187], v164 offset:49152
	ds_read_b128 v[188:191], v164 offset:50176
	ds_read_b128 v[192:195], v164 offset:51200
	ds_read_b128 v[196:199], v164 offset:52224
	s_add_u32 s30, s30, 0x4000
	s_addc_u32 s31, s31, 0
	s_mov_b32 m0, s38
	ds_read_b128 v[200:203], v166 offset:32768
	ds_read_b128 v[204:207], v166 offset:33792
	ds_read_b128 v[208:211], v166 offset:34816
	ds_read_b128 v[212:215], v166 offset:35840
	ds_read_b128 v[216:219], v166 offset:36864
	ds_read_b128 v[220:223], v166 offset:37888
	ds_read_b128 v[224:227], v166 offset:38912
	ds_read_b128 v[228:231], v166 offset:39936
	global_load_lds_dwordx4 v130, s[30:31]
	s_mov_b32 m0, s39
	s_nop 0
	global_load_lds_dwordx4 v134, s[30:31]
	s_waitcnt vmcnt(8)
	s_waitcnt lgkmcnt(0)
	s_setprio 1
	s_barrier
	v_mfma_f32_16x16x32_bf16 v[126:129], v[168:171], v[200:203], v[126:129]
	v_mfma_f32_16x16x32_bf16 v[126:129], v[172:175], v[204:207], v[126:129]
	v_mfma_f32_16x16x32_bf16 v[118:121], v[176:179], v[200:203], v[118:121]
	v_mfma_f32_16x16x32_bf16 v[118:121], v[180:183], v[204:207], v[118:121]
	v_mfma_f32_16x16x32_bf16 v[122:125], v[184:187], v[200:203], v[122:125]
	v_mfma_f32_16x16x32_bf16 v[122:125], v[188:191], v[204:207], v[122:125]
	v_mfma_f32_16x16x32_bf16 v[114:117], v[192:195], v[200:203], v[114:117]
	v_mfma_f32_16x16x32_bf16 v[114:117], v[196:199], v[204:207], v[114:117]
	v_mfma_f32_16x16x32_bf16 v[110:113], v[168:171], v[208:211], v[110:113]
	v_mfma_f32_16x16x32_bf16 v[110:113], v[172:175], v[212:215], v[110:113]
	v_mfma_f32_16x16x32_bf16 v[102:105], v[176:179], v[208:211], v[102:105]
	v_mfma_f32_16x16x32_bf16 v[102:105], v[180:183], v[212:215], v[102:105]
	v_mfma_f32_16x16x32_bf16 v[106:109], v[184:187], v[208:211], v[106:109]
	v_mfma_f32_16x16x32_bf16 v[106:109], v[188:191], v[212:215], v[106:109]
	v_mfma_f32_16x16x32_bf16 v[98:101], v[192:195], v[208:211], v[98:101]
	v_mfma_f32_16x16x32_bf16 v[98:101], v[196:199], v[212:215], v[98:101]
	v_mfma_f32_16x16x32_bf16 v[94:97], v[168:171], v[216:219], v[94:97]
	v_mfma_f32_16x16x32_bf16 v[94:97], v[172:175], v[220:223], v[94:97]
	v_mfma_f32_16x16x32_bf16 v[86:89], v[176:179], v[216:219], v[86:89]
	v_mfma_f32_16x16x32_bf16 v[86:89], v[180:183], v[220:223], v[86:89]
	v_mfma_f32_16x16x32_bf16 v[90:93], v[184:187], v[216:219], v[90:93]
	v_mfma_f32_16x16x32_bf16 v[90:93], v[188:191], v[220:223], v[90:93]
	v_mfma_f32_16x16x32_bf16 v[82:85], v[192:195], v[216:219], v[82:85]
	v_mfma_f32_16x16x32_bf16 v[82:85], v[196:199], v[220:223], v[82:85]
	v_mfma_f32_16x16x32_bf16 v[78:81], v[168:171], v[224:227], v[78:81]
	v_mfma_f32_16x16x32_bf16 v[78:81], v[172:175], v[228:231], v[78:81]
	v_mfma_f32_16x16x32_bf16 v[70:73], v[176:179], v[224:227], v[70:73]
	v_mfma_f32_16x16x32_bf16 v[70:73], v[180:183], v[228:231], v[70:73]
	v_mfma_f32_16x16x32_bf16 v[74:77], v[184:187], v[224:227], v[74:77]
	v_mfma_f32_16x16x32_bf16 v[74:77], v[188:191], v[228:231], v[74:77]
	v_mfma_f32_16x16x32_bf16 v[66:69], v[192:195], v[224:227], v[66:69]
	v_mfma_f32_16x16x32_bf16 v[66:69], v[196:199], v[228:231], v[66:69]
	s_barrier
	s_setprio 0
	s_add_u32 s30, s28, 0x8000
	s_addc_u32 s31, s29, 0
	s_add_i32 s71, s71, s34
	s_mov_b32 m0, s71
	ds_read_b128 v[200:203], v166 offset:49152
	ds_read_b128 v[204:207], v166 offset:50176
	ds_read_b128 v[208:211], v166 offset:51200
	ds_read_b128 v[212:215], v166 offset:52224
	ds_read_b128 v[216:219], v166 offset:53248
	ds_read_b128 v[220:223], v166 offset:54272
	ds_read_b128 v[224:227], v166 offset:55296
	ds_read_b128 v[228:231], v166 offset:56320
	global_load_lds_dwordx4 v132, s[30:31]
	s_add_i32 m0, s71, 0x2000
	s_add_u32 s28, s28, 0xc000
	v_lshl_add_u64 v[232:233], s[30:31], 0, v[136:137]
	s_addc_u32 s29, s29, 0
	s_add_i32 s30, s72, s34
	global_load_lds_dwordx4 v[232:233], off
	s_mov_b32 m0, s30
	s_nop 0
	global_load_lds_dwordx4 v132, s[28:29]
	s_add_i32 m0, s30, 0x2000
	s_nop 0
	global_load_lds_dwordx4 v136, s[28:29]
	s_mov_b32 m0, s43
	s_nop 0
	global_load_lds_dwordx4 v130, s[26:27]
	s_mov_b32 m0, s44
	s_nop 0
	global_load_lds_dwordx4 v134, s[26:27]
	s_waitcnt vmcnt(8)
	s_waitcnt lgkmcnt(0)
	s_setprio 1
	s_barrier
	v_mfma_f32_16x16x32_bf16 v[62:65], v[168:171], v[200:203], v[62:65]
	v_mfma_f32_16x16x32_bf16 v[62:65], v[172:175], v[204:207], v[62:65]
	v_mfma_f32_16x16x32_bf16 v[54:57], v[176:179], v[200:203], v[54:57]
	v_mfma_f32_16x16x32_bf16 v[54:57], v[180:183], v[204:207], v[54:57]
	v_mfma_f32_16x16x32_bf16 v[58:61], v[184:187], v[200:203], v[58:61]
	v_mfma_f32_16x16x32_bf16 v[58:61], v[188:191], v[204:207], v[58:61]
	v_mfma_f32_16x16x32_bf16 v[50:53], v[192:195], v[200:203], v[50:53]
	v_mfma_f32_16x16x32_bf16 v[50:53], v[196:199], v[204:207], v[50:53]
	v_mfma_f32_16x16x32_bf16 v[46:49], v[168:171], v[208:211], v[46:49]
	v_mfma_f32_16x16x32_bf16 v[46:49], v[172:175], v[212:215], v[46:49]
	v_mfma_f32_16x16x32_bf16 v[38:41], v[176:179], v[208:211], v[38:41]
	v_mfma_f32_16x16x32_bf16 v[38:41], v[180:183], v[212:215], v[38:41]
	v_mfma_f32_16x16x32_bf16 v[42:45], v[184:187], v[208:211], v[42:45]
	v_mfma_f32_16x16x32_bf16 v[42:45], v[188:191], v[212:215], v[42:45]
	v_mfma_f32_16x16x32_bf16 v[34:37], v[192:195], v[208:211], v[34:37]
	v_mfma_f32_16x16x32_bf16 v[34:37], v[196:199], v[212:215], v[34:37]
	v_mfma_f32_16x16x32_bf16 v[30:33], v[168:171], v[216:219], v[30:33]
	v_mfma_f32_16x16x32_bf16 v[30:33], v[172:175], v[220:223], v[30:33]
	v_mfma_f32_16x16x32_bf16 v[22:25], v[176:179], v[216:219], v[22:25]
	v_mfma_f32_16x16x32_bf16 v[22:25], v[180:183], v[220:223], v[22:25]
	v_mfma_f32_16x16x32_bf16 v[26:29], v[184:187], v[216:219], v[26:29]
	v_mfma_f32_16x16x32_bf16 v[26:29], v[188:191], v[220:223], v[26:29]
	v_mfma_f32_16x16x32_bf16 v[18:21], v[192:195], v[216:219], v[18:21]
	v_mfma_f32_16x16x32_bf16 v[18:21], v[196:199], v[220:223], v[18:21]
	v_mfma_f32_16x16x32_bf16 v[14:17], v[168:171], v[224:227], v[14:17]
	v_mfma_f32_16x16x32_bf16 v[14:17], v[172:175], v[228:231], v[14:17]
	v_mfma_f32_16x16x32_bf16 v[6:9], v[176:179], v[224:227], v[6:9]
	v_mfma_f32_16x16x32_bf16 v[6:9], v[180:183], v[228:231], v[6:9]
	v_mfma_f32_16x16x32_bf16 v[10:13], v[184:187], v[224:227], v[10:13]
	v_mfma_f32_16x16x32_bf16 v[10:13], v[188:191], v[228:231], v[10:13]
	v_mfma_f32_16x16x32_bf16 v[2:5], v[192:195], v[224:227], v[2:5]
	v_mfma_f32_16x16x32_bf16 v[2:5], v[196:199], v[228:231], v[2:5]
	s_barrier
	s_setprio 0
	s_add_i32 s70, s70, 2
	s_add_u32 s22, s22, 0x10000
	s_addc_u32 s23, s23, 0
	s_add_u32 s63, s63, 0x10000
	s_addc_u32 s69, s69, 0
	s_cmp_gt_u32 s70, 61
	s_cbranch_scc0 .LBB0_195
	s_and_b64 vcc, exec, s[10:11]
	s_cbranch_vccz .LBB0_198
	s_barrier

; #define PG8_STAGE(bufoff, gbase, voff) do { _Pragma("unroll") for (int _i = 0; _i < 2; ++_i) \
;         __builtin_amdgcn_global_load_lds((const unsigned*)((const char*)(gbase) + (voff)[_i]), (PG8_LAS unsigned*)(lds + (bufoff) + ldsw + _i * 8192), 16, 0, 0); } while (0)
; #define PG8_LDA(dst, b, h) do { _Pragma("unroll") for (int m = 0; m < 4; ++m) _Pragma("unroll") for (int k = 0; k < 2; ++k) dst[m][k] = *(const PG8_LAS bf16x8*)(lds + PG8_SA(b, h) + aoff + m * 2048 + k * 1024); } while (0)
; #define PG8_LDB(dst, b, h) do { _Pragma("unroll") for (int n = 0; n < 2; ++n) _Pragma("unroll") for (int k = 0; k < 2; ++k) dst[n][k] = *(const PG8_LAS bf16x8*)(lds + PG8_SB(b, h) + boff + n * 2048 + k * 1024); } while (0)
; #define PG8_WAIT_V(n) asm volatile("s_waitcnt vmcnt(" #n ")" ::: "memory")
; #define PG8_WAIT_L(n) asm volatile("s_waitcnt lgkmcnt(" #n ")" ::: "memory")
; #define PG8_BAR __builtin_amdgcn_s_barrier()
; #define PG8_SCHED __builtin_amdgcn_sched_barrier(0)
; template <class Epi, class Sched, bool ALIGN_EPI = false, bool SP2 = false, bool A_TILED = false>
; __device__ __forceinline__ void gemm_phase(PG8_LAS unsigned char* lds, const Gemm g, const Sched& S, const Epi& E) {
;     ...
;     for (;;) {
;         const bool has_next = S.next(ui + 1, nxt);
;         const char* nA = has_next ? (const char*)g.A + (size_t)nxt.pm * tstepA : cA; const char* nB = has_next ? (const char*)g.Bt + (size_t)nxt.pn * tstepB : cB;
;         for (int t = 0; t < nt; t += 2) {
;             const bool last = (t == nt - 2);
;             const char* a1 = cA + (size_t)(t + 1) * kstepA;
;             const char* a2 = last ? nA : cA + (size_t)(t + 2) * kstepA; const char* b2 = last ? nB : cB + (size_t)(t + 2) * kstepB;
;             const char* a3 = a2 + kstepA; const char* b3 = b2 + kstepB;
;             if (last && has_next) S.a_ready(nxt);
;             if constexpr (SP2) {
;             PG8_LDB(B0, 0, 0); PG8_LDB(B1, 0, 1); PG8_SCHED; PG8_LDA(At, 0, 0); PG8_STAGE(PG8_SA(1, 1), a1 + hstepA, voffA);
;             PG8_WAIT_V(8); PG8_WAIT_L(0); PG8_BAR; PG8_MMA(0, 0, At, B0); PG8_MMA(0, 1, At, B1); PG8_BAR; PG8_SCHED;
;             PG8_LDA(At, 0, 1); PG8_STAGE(PG8_SB(0, 0), b2, voffB); PG8_STAGE(PG8_SB(0, 1), b2 + hstepB, voffB); PG8_STAGE(PG8_SA(0, 0), a2, voffA);
;             PG8_WAIT_V(8); PG8_WAIT_L(0); PG8_BAR; PG8_MMA(1, 0, At, B0); PG8_MMA(1, 1, At, B1); PG8_BAR; PG8_SCHED;
.LBB0_273:
	s_add_u32 s36, s36, 0xc000
	s_addc_u32 s37, s37, 0
	s_add_u32 s33, s38, 0x10000
	v_mov_b32_e32 v2, 0
	s_addc_u32 s35, s39, 0
	s_mov_b32 s70, -2
	s_waitcnt lgkmcnt(0)
	ds_read_b128 v[130:133], v197
	ds_read_b128 v[134:137], v197 offset:1024
	ds_read_b128 v[138:141], v197 offset:2048
	ds_read_b128 v[142:145], v197 offset:3072
	ds_read_b128 v[146:149], v240
	ds_read_b128 v[150:153], v240 offset:1024
	ds_read_b128 v[154:157], v240 offset:2048
	ds_read_b128 v[158:161], v240 offset:3072
	s_add_u32 s38, s36, 0x4000
	s_addc_u32 s39, s37, 0
	s_cmpk_eq_i32 s70, 0xa8
	s_cselect_b32 s42, s4, s38
	s_cselect_b32 s43, s5, s39
	s_cselect_b32 s40, s30, s33
	s_cselect_b32 s41, s31, s35
	s_add_u32 s38, s42, 0x8000
	s_addc_u32 s39, s43, 0
	s_add_i32 m0, s62, 0xc000
	ds_read_b128 v[162:165], v241
	ds_read_b128 v[166:169], v241 offset:1024
	ds_read_b128 v[170:173], v241 offset:2048
	ds_read_b128 v[174:177], v241 offset:3072
	ds_read_b128 v[178:181], v241 offset:4096
	ds_read_b128 v[182:185], v241 offset:5120
	ds_read_b128 v[186:189], v241 offset:6144
	ds_read_b128 v[222:225], v241 offset:7168
	global_load_lds_dwordx4 v214, s[36:37]
	s_add_i32 m0, s62, 0xe000
	s_nop 0
	global_load_lds_dwordx4 v216, s[36:37]
	s_waitcnt vmcnt(8)
	s_waitcnt lgkmcnt(0)
	s_setprio 1
	s_barrier
	v_mfma_f32_16x16x32_bf16 v[90:93], v[130:133], v[162:165], 0
	v_mfma_f32_16x16x32_bf16 v[90:93], v[134:137], v[166:169], v[90:93]
	v_mfma_f32_16x16x32_bf16 v[98:101], v[138:141], v[162:165], 0
	v_mfma_f32_16x16x32_bf16 v[98:101], v[142:145], v[166:169], v[98:101]
	v_mfma_f32_16x16x32_bf16 v[106:109], v[146:149], v[162:165], 0
	v_mfma_f32_16x16x32_bf16 v[106:109], v[150:153], v[166:169], v[106:109]
	v_mfma_f32_16x16x32_bf16 v[114:117], v[154:157], v[162:165], 0
	v_mfma_f32_16x16x32_bf16 v[114:117], v[158:161], v[166:169], v[114:117]
	v_mfma_f32_16x16x32_bf16 v[122:125], v[130:133], v[170:173], 0
	v_mfma_f32_16x16x32_bf16 v[122:125], v[134:137], v[174:177], v[122:125]
	v_mfma_f32_16x16x32_bf16 v[126:129], v[138:141], v[170:173], 0
	v_mfma_f32_16x16x32_bf16 v[126:129], v[142:145], v[174:177], v[126:129]
	v_mfma_f32_16x16x32_bf16 v[118:121], v[146:149], v[170:173], 0
	v_mfma_f32_16x16x32_bf16 v[118:121], v[150:153], v[174:177], v[118:121]
	v_mfma_f32_16x16x32_bf16 v[110:113], v[154:157], v[170:173], 0
	v_mfma_f32_16x16x32_bf16 v[110:113], v[158:161], v[174:177], v[110:113]
	v_mfma_f32_16x16x32_bf16 v[102:105], v[130:133], v[178:181], 0
	v_mfma_f32_16x16x32_bf16 v[102:105], v[134:137], v[182:185], v[102:105]
	v_mfma_f32_16x16x32_bf16 v[94:97], v[138:141], v[178:181], 0
	v_mfma_f32_16x16x32_bf16 v[94:97], v[142:145], v[182:185], v[94:97]
	v_mfma_f32_16x16x32_bf16 v[86:89], v[146:149], v[178:181], 0
	v_mfma_f32_16x16x32_bf16 v[86:89], v[150:153], v[182:185], v[86:89]
	v_mfma_f32_16x16x32_bf16 v[82:85], v[154:157], v[178:181], 0
	v_mfma_f32_16x16x32_bf16 v[82:85], v[158:161], v[182:185], v[82:85]
	v_mfma_f32_16x16x32_bf16 v[78:81], v[130:133], v[186:189], 0
	v_mfma_f32_16x16x32_bf16 v[78:81], v[134:137], v[222:225], v[78:81]
	v_mfma_f32_16x16x32_bf16 v[74:77], v[138:141], v[186:189], 0
	v_mfma_f32_16x16x32_bf16 v[74:77], v[142:145], v[222:225], v[74:77]
	v_mfma_f32_16x16x32_bf16 v[70:73], v[146:149], v[186:189], 0
	v_mfma_f32_16x16x32_bf16 v[70:73], v[150:153], v[222:225], v[70:73]
	v_mfma_f32_16x16x32_bf16 v[66:69], v[154:157], v[186:189], 0
	v_mfma_f32_16x16x32_bf16 v[66:69], v[158:161], v[222:225], v[66:69]
	s_barrier
	s_setprio 0
	s_add_i32 s72, s83, s59
	s_mov_b32 m0, s72
	ds_read_b128 v[162:165], v241 offset:16384
	ds_read_b128 v[166:169], v241 offset:17408
	ds_read_b128 v[170:173], v241 offset:18432
	ds_read_b128 v[174:177], v241 offset:19456
	ds_read_b128 v[178:181], v241 offset:20480
	ds_read_b128 v[182:185], v241 offset:21504
	ds_read_b128 v[186:189], v241 offset:22528
	ds_read_b128 v[222:225], v241 offset:23552
	global_load_lds_dwordx4 v190, s[40:41]
	s_add_i32 m0, s72, 0x2000
	s_add_u32 s72, s40, 0x4000
	s_addc_u32 s73, s41, 0
	s_add_i32 s74, s84, s59
	global_load_lds_dwordx4 v192, s[40:41]
	s_mov_b32 m0, s74
	s_nop 0
	global_load_lds_dwordx4 v190, s[72:73]
	s_add_i32 m0, s74, 0x2000
	s_nop 0
	global_load_lds_dwordx4 v192, s[72:73]
	s_mov_b32 m0, s62
	s_nop 0
	global_load_lds_dwordx4 v190, s[42:43]
	s_mov_b32 m0, s63
	s_nop 0
	global_load_lds_dwordx4 v192, s[42:43]
	s_waitcnt vmcnt(8)
	s_waitcnt lgkmcnt(0)
	s_setprio 1
	s_barrier
	v_mfma_f32_16x16x32_bf16 v[62:65], v[130:133], v[162:165], 0
	v_mfma_f32_16x16x32_bf16 v[62:65], v[134:137], v[166:169], v[62:65]
	v_mfma_f32_16x16x32_bf16 v[58:61], v[138:141], v[162:165], 0
	v_mfma_f32_16x16x32_bf16 v[58:61], v[142:145], v[166:169], v[58:61]
	v_mfma_f32_16x16x32_bf16 v[54:57], v[146:149], v[162:165], 0
	v_mfma_f32_16x16x32_bf16 v[54:57], v[150:153], v[166:169], v[54:57]
	v_mfma_f32_16x16x32_bf16 v[50:53], v[154:157], v[162:165], 0
	v_mfma_f32_16x16x32_bf16 v[50:53], v[158:161], v[166:169], v[50:53]
	v_mfma_f32_16x16x32_bf16 v[46:49], v[130:133], v[170:173], 0
	v_mfma_f32_16x16x32_bf16 v[46:49], v[134:137], v[174:177], v[46:49]
	v_mfma_f32_16x16x32_bf16 v[42:45], v[138:141], v[170:173], 0
	v_mfma_f32_16x16x32_bf16 v[42:45], v[142:145], v[174:177], v[42:45]
	v_mfma_f32_16x16x32_bf16 v[38:41], v[146:149], v[170:173], 0
	v_mfma_f32_16x16x32_bf16 v[38:41], v[150:153], v[174:177], v[38:41]
	v_mfma_f32_16x16x32_bf16 v[34:37], v[154:157], v[170:173], 0
	v_mfma_f32_16x16x32_bf16 v[34:37], v[158:161], v[174:177], v[34:37]
	v_mfma_f32_16x16x32_bf16 v[30:33], v[130:133], v[178:181], 0
	v_mfma_f32_16x16x32_bf16 v[30:33], v[134:137], v[182:185], v[30:33]
	v_mfma_f32_16x16x32_bf16 v[26:29], v[138:141], v[178:181], 0
	v_mfma_f32_16x16x32_bf16 v[26:29], v[142:145], v[182:185], v[26:29]
	v_mfma_f32_16x16x32_bf16 v[22:25], v[146:149], v[178:181], 0
	v_mfma_f32_16x16x32_bf16 v[22:25], v[150:153], v[182:185], v[22:25]
	v_mfma_f32_16x16x32_bf16 v[18:21], v[154:157], v[178:181], 0
	v_mfma_f32_16x16x32_bf16 v[18:21], v[158:161], v[182:185], v[18:21]
	v_mfma_f32_16x16x32_bf16 v[14:17], v[130:133], v[186:189], 0
	v_mfma_f32_16x16x32_bf16 v[14:17], v[134:137], v[222:225], v[14:17]
	v_mfma_f32_16x16x32_bf16 v[10:13], v[138:141], v[186:189], 0
	v_mfma_f32_16x16x32_bf16 v[10:13], v[142:145], v[222:225], v[10:13]
	v_mfma_f32_16x16x32_bf16 v[6:9], v[146:149], v[186:189], 0
	v_mfma_f32_16x16x32_bf16 v[6:9], v[150:153], v[222:225], v[6:9]
	v_mfma_f32_16x16x32_bf16 v[2:5], v[154:157], v[186:189], 0
	v_mfma_f32_16x16x32_bf16 v[2:5], v[158:161], v[222:225], v[2:5]
	s_barrier
; #define PG8_STAGE(bufoff, gbase, voff) do { _Pragma("unroll") for (int _i = 0; _i < 2; ++_i) \
;         __builtin_amdgcn_global_load_lds((const unsigned*)((const char*)(gbase) + (voff)[_i]), (PG8_LAS unsigned*)(lds + (bufoff) + ldsw + _i * 8192), 16, 0, 0); } while (0)
; #define PG8_LDA(dst, b, h) do { _Pragma("unroll") for (int m = 0; m < 4; ++m) _Pragma("unroll") for (int k = 0; k < 2; ++k) dst[m][k] = *(const PG8_LAS bf16x8*)(lds + PG8_SA(b, h) + aoff + m * 2048 + k * 1024); } while (0)
; #define PG8_LDB(dst, b, h) do { _Pragma("unroll") for (int n = 0; n < 2; ++n) _Pragma("unroll") for (int k = 0; k < 2; ++k) dst[n][k] = *(const PG8_LAS bf16x8*)(lds + PG8_SB(b, h) + boff + n * 2048 + k * 1024); } while (0)
; #define PG8_MMA(ai, bj, At, Bt) do { __builtin_amdgcn_s_setprio(1); _Pragma("unroll") for (int m = 0; m < 4; ++m) _Pragma("unroll") for (int n = 0; n < 2; ++n) _Pragma("unroll") for (int k = 0; k < 2; ++k) \
;         acc[ai][bj][m][n] = __builtin_amdgcn_mfma_f32_16x16x32_bf16(Bt[n][k], At[m][k], acc[ai][bj][m][n], 0, 0, 0); __builtin_amdgcn_s_setprio(0); } while (0)
; #define PG8_WAIT_V(n) asm volatile("s_waitcnt vmcnt(" #n ")" ::: "memory")
; #define PG8_WAIT_L(n) asm volatile("s_waitcnt lgkmcnt(" #n ")" ::: "memory")
; #define PG8_BAR __builtin_amdgcn_s_barrier()
; #define PG8_SCHED __builtin_amdgcn_sched_barrier(0)
; template <class Epi, class Sched, bool ALIGN_EPI = false, bool SP2 = false, bool A_TILED = false>
; __device__ __forceinline__ void gemm_phase(PG8_LAS unsigned char* lds, const Gemm g, const Sched& S, const Epi& E) {
;     ...
;             PG8_LDB(B0, 1, 0); PG8_LDB(B1, 1, 1); PG8_SCHED; PG8_LDA(At, 1, 0); PG8_STAGE(PG8_SA(0, 1), a2 + hstepA, voffA);
;             PG8_WAIT_V(8); PG8_WAIT_L(0); PG8_BAR; PG8_MMA(0, 0, At, B0); PG8_MMA(0, 1, At, B1); PG8_BAR; PG8_SCHED;
;             PG8_LDA(At, 1, 1); PG8_STAGE(PG8_SB(1, 0), b3, voffB); PG8_STAGE(PG8_SB(1, 1), b3 + hstepB, voffB); PG8_STAGE(PG8_SA(1, 0), a3, voffA);
;             PG8_WAIT_V(8); PG8_WAIT_L(0); PG8_BAR; PG8_MMA(1, 0, At, B0); PG8_MMA(1, 1, At, B1); PG8_BAR; PG8_SCHED;
	s_setprio 0
	s_add_i32 s72, 0, 0x18000
	s_add_i32 s73, 0, 0x1c000
	ds_read_b128 v[130:133], v197 offset:32768
	ds_read_b128 v[134:137], v197 offset:33792
	ds_read_b128 v[138:141], v197 offset:34816
	ds_read_b128 v[142:145], v197 offset:35840
	ds_read_b128 v[146:149], v197 offset:49152
	ds_read_b128 v[150:153], v197 offset:50176
	ds_read_b128 v[154:157], v197 offset:51200
	ds_read_b128 v[158:161], v197 offset:52224
	s_add_u32 s42, s42, 0x4000
	s_addc_u32 s43, s43, 0
	s_mov_b32 m0, s69
	ds_read_b128 v[162:165], v241 offset:32768
	ds_read_b128 v[166:169], v241 offset:33792
	ds_read_b128 v[170:173], v241 offset:34816
	ds_read_b128 v[174:177], v241 offset:35840
	ds_read_b128 v[178:181], v241 offset:36864
	ds_read_b128 v[182:185], v241 offset:37888
	ds_read_b128 v[186:189], v241 offset:38912
	ds_read_b128 v[222:225], v241 offset:39936
	global_load_lds_dwordx4 v190, s[42:43]
	s_mov_b32 m0, s71
	s_nop 0
	global_load_lds_dwordx4 v192, s[42:43]
	s_waitcnt vmcnt(8)
	s_waitcnt lgkmcnt(0)
	s_setprio 1
	s_barrier
	v_mfma_f32_16x16x32_bf16 v[90:93], v[130:133], v[162:165], v[90:93]
	v_mfma_f32_16x16x32_bf16 v[90:93], v[134:137], v[166:169], v[90:93]
	v_mfma_f32_16x16x32_bf16 v[98:101], v[138:141], v[162:165], v[98:101]
	v_mfma_f32_16x16x32_bf16 v[98:101], v[142:145], v[166:169], v[98:101]
	v_mfma_f32_16x16x32_bf16 v[106:109], v[146:149], v[162:165], v[106:109]
	v_mfma_f32_16x16x32_bf16 v[106:109], v[150:153], v[166:169], v[106:109]
	v_mfma_f32_16x16x32_bf16 v[114:117], v[154:157], v[162:165], v[114:117]
	v_mfma_f32_16x16x32_bf16 v[114:117], v[158:161], v[166:169], v[114:117]
	v_mfma_f32_16x16x32_bf16 v[122:125], v[130:133], v[170:173], v[122:125]
	v_mfma_f32_16x16x32_bf16 v[122:125], v[134:137], v[174:177], v[122:125]
	v_mfma_f32_16x16x32_bf16 v[126:129], v[138:141], v[170:173], v[126:129]
	v_mfma_f32_16x16x32_bf16 v[126:129], v[142:145], v[174:177], v[126:129]
	v_mfma_f32_16x16x32_bf16 v[118:121], v[146:149], v[170:173], v[118:121]
	v_mfma_f32_16x16x32_bf16 v[118:121], v[150:153], v[174:177], v[118:121]
	v_mfma_f32_16x16x32_bf16 v[110:113], v[154:157], v[170:173], v[110:113]
	v_mfma_f32_16x16x32_bf16 v[110:113], v[158:161], v[174:177], v[110:113]
	v_mfma_f32_16x16x32_bf16 v[102:105], v[130:133], v[178:181], v[102:105]
	v_mfma_f32_16x16x32_bf16 v[102:105], v[134:137], v[182:185], v[102:105]
	v_mfma_f32_16x16x32_bf16 v[94:97], v[138:141], v[178:181], v[94:97]
	v_mfma_f32_16x16x32_bf16 v[94:97], v[142:145], v[182:185], v[94:97]
	v_mfma_f32_16x16x32_bf16 v[86:89], v[146:149], v[178:181], v[86:89]
	v_mfma_f32_16x16x32_bf16 v[86:89], v[150:153], v[182:185], v[86:89]
	v_mfma_f32_16x16x32_bf16 v[82:85], v[154:157], v[178:181], v[82:85]
	v_mfma_f32_16x16x32_bf16 v[82:85], v[158:161], v[182:185], v[82:85]
	v_mfma_f32_16x16x32_bf16 v[78:81], v[130:133], v[186:189], v[78:81]
	v_mfma_f32_16x16x32_bf16 v[78:81], v[134:137], v[222:225], v[78:81]
	v_mfma_f32_16x16x32_bf16 v[74:77], v[138:141], v[186:189], v[74:77]
	v_mfma_f32_16x16x32_bf16 v[74:77], v[142:145], v[222:225], v[74:77]
	v_mfma_f32_16x16x32_bf16 v[70:73], v[146:149], v[186:189], v[70:73]
	v_mfma_f32_16x16x32_bf16 v[70:73], v[150:153], v[222:225], v[70:73]
	v_mfma_f32_16x16x32_bf16 v[66:69], v[154:157], v[186:189], v[66:69]
	v_mfma_f32_16x16x32_bf16 v[66:69], v[158:161], v[222:225], v[66:69]
	s_barrier
	s_setprio 0
	s_add_u32 s42, s40, 0x8000
	s_addc_u32 s43, s41, 0
	s_add_i32 s72, s72, s59
	s_mov_b32 m0, s72
	ds_read_b128 v[162:165], v241 offset:49152
	ds_read_b128 v[166:169], v241 offset:50176
	ds_read_b128 v[170:173], v241 offset:51200
	ds_read_b128 v[174:177], v241 offset:52224
	ds_read_b128 v[178:181], v241 offset:53248
	ds_read_b128 v[182:185], v241 offset:54272
	ds_read_b128 v[186:189], v241 offset:55296
	ds_read_b128 v[222:225], v241 offset:56320
	global_load_lds_dwordx4 v190, s[42:43]
	s_add_i32 m0, s72, 0x2000
	s_add_u32 s40, s40, 0xc000
	v_lshl_add_u64 v[226:227], s[42:43], 0, v[192:193]
	s_addc_u32 s41, s41, 0
	s_add_i32 s42, s73, s59
	global_load_lds_dwordx4 v[226:227], off
	s_mov_b32 m0, s42
	s_nop 0
	global_load_lds_dwordx4 v190, s[40:41]
	s_add_i32 m0, s42, 0x2000
	s_nop 0
	global_load_lds_dwordx4 v192, s[40:41]
	s_mov_b32 m0, s80
	s_nop 0
	global_load_lds_dwordx4 v190, s[38:39]
	s_mov_b32 m0, s81
	s_nop 0
	global_load_lds_dwordx4 v192, s[38:39]
	s_waitcnt vmcnt(8)
	s_waitcnt lgkmcnt(0)
	s_setprio 1
	s_barrier
	v_mfma_f32_16x16x32_bf16 v[62:65], v[130:133], v[162:165], v[62:65]
	v_mfma_f32_16x16x32_bf16 v[62:65], v[134:137], v[166:169], v[62:65]
	v_mfma_f32_16x16x32_bf16 v[58:61], v[138:141], v[162:165], v[58:61]
	v_mfma_f32_16x16x32_bf16 v[58:61], v[142:145], v[166:169], v[58:61]
	v_mfma_f32_16x16x32_bf16 v[54:57], v[146:149], v[162:165], v[54:57]
	v_mfma_f32_16x16x32_bf16 v[54:57], v[150:153], v[166:169], v[54:57]
	v_mfma_f32_16x16x32_bf16 v[50:53], v[154:157], v[162:165], v[50:53]
	v_mfma_f32_16x16x32_bf16 v[50:53], v[158:161], v[166:169], v[50:53]
	v_mfma_f32_16x16x32_bf16 v[46:49], v[130:133], v[170:173], v[46:49]
	v_mfma_f32_16x16x32_bf16 v[46:49], v[134:137], v[174:177], v[46:49]
	v_mfma_f32_16x16x32_bf16 v[42:45], v[138:141], v[170:173], v[42:45]
	v_mfma_f32_16x16x32_bf16 v[42:45], v[142:145], v[174:177], v[42:45]
	v_mfma_f32_16x16x32_bf16 v[38:41], v[146:149], v[170:173], v[38:41]
	v_mfma_f32_16x16x32_bf16 v[38:41], v[150:153], v[174:177], v[38:41]
	v_mfma_f32_16x16x32_bf16 v[34:37], v[154:157], v[170:173], v[34:37]
	v_mfma_f32_16x16x32_bf16 v[34:37], v[158:161], v[174:177], v[34:37]
	v_mfma_f32_16x16x32_bf16 v[30:33], v[130:133], v[178:181], v[30:33]
	v_mfma_f32_16x16x32_bf16 v[30:33], v[134:137], v[182:185], v[30:33]
	v_mfma_f32_16x16x32_bf16 v[26:29], v[138:141], v[178:181], v[26:29]
	v_mfma_f32_16x16x32_bf16 v[26:29], v[142:145], v[182:185], v[26:29]
	v_mfma_f32_16x16x32_bf16 v[22:25], v[146:149], v[178:181], v[22:25]
	v_mfma_f32_16x16x32_bf16 v[22:25], v[150:153], v[182:185], v[22:25]
	v_mfma_f32_16x16x32_bf16 v[18:21], v[154:157], v[178:181], v[18:21]
	v_mfma_f32_16x16x32_bf16 v[18:21], v[158:161], v[182:185], v[18:21]
	v_mfma_f32_16x16x32_bf16 v[14:17], v[130:133], v[186:189], v[14:17]
	v_mfma_f32_16x16x32_bf16 v[14:17], v[134:137], v[222:225], v[14:17]
	v_mfma_f32_16x16x32_bf16 v[10:13], v[138:141], v[186:189], v[10:13]
	v_mfma_f32_16x16x32_bf16 v[10:13], v[142:145], v[222:225], v[10:13]
	v_mfma_f32_16x16x32_bf16 v[6:9], v[146:149], v[186:189], v[6:9]
	v_mfma_f32_16x16x32_bf16 v[6:9], v[150:153], v[222:225], v[6:9]
	v_mfma_f32_16x16x32_bf16 v[2:5], v[154:157], v[186:189], v[2:5]
	v_mfma_f32_16x16x32_bf16 v[2:5], v[158:161], v[222:225], v[2:5]
	s_barrier
	s_setprio 0
	s_add_i32 s70, s70, 2
	s_add_u32 s36, s36, 0x10000
	s_addc_u32 s37, s37, 0
	s_add_u32 s33, s33, 0x10000
	s_addc_u32 s35, s35, 0
; #define PG8_STAGE(bufoff, gbase, voff) do { _Pragma("unroll") for (int _i = 0; _i < 2; ++_i) \
;         __builtin_amdgcn_global_load_lds((const unsigned*)((const char*)(gbase) + (voff)[_i]), (PG8_LAS unsigned*)(lds + (bufoff) + ldsw + _i * 8192), 16, 0, 0); } while (0)
; #define PG8_LDA(dst, b, h) do { _Pragma("unroll") for (int m = 0; m < 4; ++m) _Pragma("unroll") for (int k = 0; k < 2; ++k) dst[m][k] = *(const PG8_LAS bf16x8*)(lds + PG8_SA(b, h) + aoff + m * 2048 + k * 1024); } while (0)
; #define PG8_LDB(dst, b, h) do { _Pragma("unroll") for (int n = 0; n < 2; ++n) _Pragma("unroll") for (int k = 0; k < 2; ++k) dst[n][k] = *(const PG8_LAS bf16x8*)(lds + PG8_SB(b, h) + boff + n * 2048 + k * 1024); } while (0)
; #define PG8_MMA(ai, bj, At, Bt) do { __builtin_amdgcn_s_setprio(1); _Pragma("unroll") for (int m = 0; m < 4; ++m) _Pragma("unroll") for (int n = 0; n < 2; ++n) _Pragma("unroll") for (int k = 0; k < 2; ++k) \
;         acc[ai][bj][m][n] = __builtin_amdgcn_mfma_f32_16x16x32_bf16(Bt[n][k], At[m][k], acc[ai][bj][m][n], 0, 0, 0); __builtin_amdgcn_s_setprio(0); } while (0)
; #define PG8_WAIT_V(n) asm volatile("s_waitcnt vmcnt(" #n ")" ::: "memory")
; #define PG8_WAIT_L(n) asm volatile("s_waitcnt lgkmcnt(" #n ")" ::: "memory")
; #define PG8_BAR __builtin_amdgcn_s_barrier()
; #define PG8_SCHED __builtin_amdgcn_sched_barrier(0)
; template <class Epi, class Sched, bool ALIGN_EPI = false, bool SP2 = false, bool A_TILED = false>
; __device__ __forceinline__ void gemm_phase(PG8_LAS unsigned char* lds, const Gemm g, const Sched& S, const Epi& E) {
;     ...
;             PG8_LDB(B0, 0, 0); PG8_LDB(B1, 0, 1); PG8_SCHED; PG8_LDA(At, 0, 0); PG8_STAGE(PG8_SA(1, 1), a1 + hstepA, voffA);
;             PG8_WAIT_V(8); PG8_WAIT_L(0); PG8_BAR; PG8_MMA(0, 0, At, B0); PG8_MMA(0, 1, At, B1); PG8_BAR; PG8_SCHED;
;             PG8_LDA(At, 0, 1); PG8_STAGE(PG8_SB(0, 0), b2, voffB); PG8_STAGE(PG8_SB(0, 1), b2 + hstepB, voffB); PG8_STAGE(PG8_SA(0, 0), a2, voffA);
;             PG8_WAIT_V(8); PG8_WAIT_L(0); PG8_BAR; PG8_MMA(1, 0, At, B0); PG8_MMA(1, 1, At, B1); PG8_BAR; PG8_SCHED;
.LBB0_274:
	ds_read_b128 v[130:133], v197
	ds_read_b128 v[134:137], v197 offset:1024
	ds_read_b128 v[138:141], v197 offset:2048
	ds_read_b128 v[142:145], v197 offset:3072
	ds_read_b128 v[146:149], v240
	ds_read_b128 v[150:153], v240 offset:1024
	ds_read_b128 v[154:157], v240 offset:2048
	ds_read_b128 v[158:161], v240 offset:3072
	s_add_u32 s38, s36, 0x4000
	s_addc_u32 s39, s37, 0
	s_cmpk_eq_i32 s70, 0xa8
	s_cselect_b32 s42, s4, s38
	s_cselect_b32 s43, s5, s39
	s_cselect_b32 s40, s30, s33
	s_cselect_b32 s41, s31, s35
	s_add_u32 s38, s42, 0x8000
	s_addc_u32 s39, s43, 0
	s_add_i32 m0, s62, 0xc000
	ds_read_b128 v[162:165], v241
	ds_read_b128 v[166:169], v241 offset:1024
	ds_read_b128 v[170:173], v241 offset:2048
	ds_read_b128 v[174:177], v241 offset:3072
	ds_read_b128 v[178:181], v241 offset:4096
	ds_read_b128 v[182:185], v241 offset:5120
	ds_read_b128 v[186:189], v241 offset:6144
	ds_read_b128 v[222:225], v241 offset:7168
	global_load_lds_dwordx4 v214, s[36:37]
	s_add_i32 m0, s62, 0xe000
	s_nop 0
	global_load_lds_dwordx4 v216, s[36:37]
	s_waitcnt vmcnt(8)
	s_waitcnt lgkmcnt(0)
	s_setprio 1
	s_barrier
	v_mfma_f32_16x16x32_bf16 v[90:93], v[130:133], v[162:165], v[90:93]
	v_mfma_f32_16x16x32_bf16 v[90:93], v[134:137], v[166:169], v[90:93]
	v_mfma_f32_16x16x32_bf16 v[98:101], v[138:141], v[162:165], v[98:101]
	v_mfma_f32_16x16x32_bf16 v[98:101], v[142:145], v[166:169], v[98:101]
	v_mfma_f32_16x16x32_bf16 v[106:109], v[146:149], v[162:165], v[106:109]
	v_mfma_f32_16x16x32_bf16 v[106:109], v[150:153], v[166:169], v[106:109]
	v_mfma_f32_16x16x32_bf16 v[114:117], v[154:157], v[162:165], v[114:117]
	v_mfma_f32_16x16x32_bf16 v[114:117], v[158:161], v[166:169], v[114:117]
	v_mfma_f32_16x16x32_bf16 v[122:125], v[130:133], v[170:173], v[122:125]
	v_mfma_f32_16x16x32_bf16 v[122:125], v[134:137], v[174:177], v[122:125]
	v_mfma_f32_16x16x32_bf16 v[126:129], v[138:141], v[170:173], v[126:129]
	v_mfma_f32_16x16x32_bf16 v[126:129], v[142:145], v[174:177], v[126:129]
	v_mfma_f32_16x16x32_bf16 v[118:121], v[146:149], v[170:173], v[118:121]
	v_mfma_f32_16x16x32_bf16 v[118:121], v[150:153], v[174:177], v[118:121]
	v_mfma_f32_16x16x32_bf16 v[110:113], v[154:157], v[170:173], v[110:113]
	v_mfma_f32_16x16x32_bf16 v[110:113], v[158:161], v[174:177], v[110:113]
	v_mfma_f32_16x16x32_bf16 v[102:105], v[130:133], v[178:181], v[102:105]
	v_mfma_f32_16x16x32_bf16 v[102:105], v[134:137], v[182:185], v[102:105]
	v_mfma_f32_16x16x32_bf16 v[94:97], v[138:141], v[178:181], v[94:97]
	v_mfma_f32_16x16x32_bf16 v[94:97], v[142:145], v[182:185], v[94:97]
	v_mfma_f32_16x16x32_bf16 v[86:89], v[146:149], v[178:181], v[86:89]
	v_mfma_f32_16x16x32_bf16 v[86:89], v[150:153], v[182:185], v[86:89]
	v_mfma_f32_16x16x32_bf16 v[82:85], v[154:157], v[178:181], v[82:85]
	v_mfma_f32_16x16x32_bf16 v[82:85], v[158:161], v[182:185], v[82:85]
	v_mfma_f32_16x16x32_bf16 v[78:81], v[130:133], v[186:189], v[78:81]
	v_mfma_f32_16x16x32_bf16 v[78:81], v[134:137], v[222:225], v[78:81]
	v_mfma_f32_16x16x32_bf16 v[74:77], v[138:141], v[186:189], v[74:77]
	v_mfma_f32_16x16x32_bf16 v[74:77], v[142:145], v[222:225], v[74:77]
	v_mfma_f32_16x16x32_bf16 v[70:73], v[146:149], v[186:189], v[70:73]
	v_mfma_f32_16x16x32_bf16 v[70:73], v[150:153], v[222:225], v[70:73]
	v_mfma_f32_16x16x32_bf16 v[66:69], v[154:157], v[186:189], v[66:69]
	v_mfma_f32_16x16x32_bf16 v[66:69], v[158:161], v[222:225], v[66:69]
	s_barrier
	s_setprio 0
	s_add_i32 s72, s83, s59
	s_mov_b32 m0, s72
	ds_read_b128 v[162:165], v241 offset:16384
	ds_read_b128 v[166:169], v241 offset:17408
	ds_read_b128 v[170:173], v241 offset:18432
	ds_read_b128 v[174:177], v241 offset:19456
	ds_read_b128 v[178:181], v241 offset:20480
	ds_read_b128 v[182:185], v241 offset:21504
	ds_read_b128 v[186:189], v241 offset:22528
	ds_read_b128 v[222:225], v241 offset:23552
	global_load_lds_dwordx4 v190, s[40:41]
	s_add_i32 m0, s72, 0x2000
	s_add_u32 s72, s40, 0x4000
	s_addc_u32 s73, s41, 0
	s_add_i32 s74, s84, s59
	global_load_lds_dwordx4 v192, s[40:41]
	s_mov_b32 m0, s74
	s_nop 0
	global_load_lds_dwordx4 v190, s[72:73]
	s_add_i32 m0, s74, 0x2000
	s_nop 0
	global_load_lds_dwordx4 v192, s[72:73]
	s_mov_b32 m0, s62
	s_nop 0
	global_load_lds_dwordx4 v190, s[42:43]
	s_mov_b32 m0, s63
	s_nop 0
	global_load_lds_dwordx4 v192, s[42:43]
	s_waitcnt vmcnt(8)
	s_waitcnt lgkmcnt(0)
	s_setprio 1
	s_barrier
	v_mfma_f32_16x16x32_bf16 v[62:65], v[130:133], v[162:165], v[62:65]
	v_mfma_f32_16x16x32_bf16 v[62:65], v[134:137], v[166:169], v[62:65]
	v_mfma_f32_16x16x32_bf16 v[58:61], v[138:141], v[162:165], v[58:61]
	v_mfma_f32_16x16x32_bf16 v[58:61], v[142:145], v[166:169], v[58:61]
	v_mfma_f32_16x16x32_bf16 v[54:57], v[146:149], v[162:165], v[54:57]
	v_mfma_f32_16x16x32_bf16 v[54:57], v[150:153], v[166:169], v[54:57]
	v_mfma_f32_16x16x32_bf16 v[50:53], v[154:157], v[162:165], v[50:53]
	v_mfma_f32_16x16x32_bf16 v[50:53], v[158:161], v[166:169], v[50:53]
	v_mfma_f32_16x16x32_bf16 v[46:49], v[130:133], v[170:173], v[46:49]
	v_mfma_f32_16x16x32_bf16 v[46:49], v[134:137], v[174:177], v[46:49]
	v_mfma_f32_16x16x32_bf16 v[42:45], v[138:141], v[170:173], v[42:45]
	v_mfma_f32_16x16x32_bf16 v[42:45], v[142:145], v[174:177], v[42:45]
	v_mfma_f32_16x16x32_bf16 v[38:41], v[146:149], v[170:173], v[38:41]
	v_mfma_f32_16x16x32_bf16 v[38:41], v[150:153], v[174:177], v[38:41]
	v_mfma_f32_16x16x32_bf16 v[34:37], v[154:157], v[170:173], v[34:37]
	v_mfma_f32_16x16x32_bf16 v[34:37], v[158:161], v[174:177], v[34:37]
	v_mfma_f32_16x16x32_bf16 v[30:33], v[130:133], v[178:181], v[30:33]
	v_mfma_f32_16x16x32_bf16 v[30:33], v[134:137], v[182:185], v[30:33]
	v_mfma_f32_16x16x32_bf16 v[26:29], v[138:141], v[178:181], v[26:29]
	v_mfma_f32_16x16x32_bf16 v[26:29], v[142:145], v[182:185], v[26:29]
	v_mfma_f32_16x16x32_bf16 v[22:25], v[146:149], v[178:181], v[22:25]
	v_mfma_f32_16x16x32_bf16 v[22:25], v[150:153], v[182:185], v[22:25]
	v_mfma_f32_16x16x32_bf16 v[18:21], v[154:157], v[178:181], v[18:21]
	v_mfma_f32_16x16x32_bf16 v[18:21], v[158:161], v[182:185], v[18:21]
	v_mfma_f32_16x16x32_bf16 v[14:17], v[130:133], v[186:189], v[14:17]
	v_mfma_f32_16x16x32_bf16 v[14:17], v[134:137], v[222:225], v[14:17]
	v_mfma_f32_16x16x32_bf16 v[10:13], v[138:141], v[186:189], v[10:13]
	v_mfma_f32_16x16x32_bf16 v[10:13], v[142:145], v[222:225], v[10:13]
	v_mfma_f32_16x16x32_bf16 v[6:9], v[146:149], v[186:189], v[6:9]
	v_mfma_f32_16x16x32_bf16 v[6:9], v[150:153], v[222:225], v[6:9]
	v_mfma_f32_16x16x32_bf16 v[2:5], v[154:157], v[186:189], v[2:5]
	v_mfma_f32_16x16x32_bf16 v[2:5], v[158:161], v[222:225], v[2:5]
	s_barrier
; #define PG8_STAGE(bufoff, gbase, voff) do { _Pragma("unroll") for (int _i = 0; _i < 2; ++_i) \
;         __builtin_amdgcn_global_load_lds((const unsigned*)((const char*)(gbase) + (voff)[_i]), (PG8_LAS unsigned*)(lds + (bufoff) + ldsw + _i * 8192), 16, 0, 0); } while (0)
; #define PG8_LDA(dst, b, h) do { _Pragma("unroll") for (int m = 0; m < 4; ++m) _Pragma("unroll") for (int k = 0; k < 2; ++k) dst[m][k] = *(const PG8_LAS bf16x8*)(lds + PG8_SA(b, h) + aoff + m * 2048 + k * 1024); } while (0)
; #define PG8_LDB(dst, b, h) do { _Pragma("unroll") for (int n = 0; n < 2; ++n) _Pragma("unroll") for (int k = 0; k < 2; ++k) dst[n][k] = *(const PG8_LAS bf16x8*)(lds + PG8_SB(b, h) + boff + n * 2048 + k * 1024); } while (0)
; #define PG8_MMA(ai, bj, At, Bt) do { __builtin_amdgcn_s_setprio(1); _Pragma("unroll") for (int m = 0; m < 4; ++m) _Pragma("unroll") for (int n = 0; n < 2; ++n) _Pragma("unroll") for (int k = 0; k < 2; ++k) \
;         acc[ai][bj][m][n] = __builtin_amdgcn_mfma_f32_16x16x32_bf16(Bt[n][k], At[m][k], acc[ai][bj][m][n], 0, 0, 0); __builtin_amdgcn_s_setprio(0); } while (0)
; #define PG8_WAIT_V(n) asm volatile("s_waitcnt vmcnt(" #n ")" ::: "memory")
; #define PG8_WAIT_L(n) asm volatile("s_waitcnt lgkmcnt(" #n ")" ::: "memory")
; #define PG8_BAR __builtin_amdgcn_s_barrier()
; #define PG8_SCHED __builtin_amdgcn_sched_barrier(0)
; template <class Epi, class Sched, bool ALIGN_EPI = false, bool SP2 = false, bool A_TILED = false>
; __device__ __forceinline__ void gemm_phase(PG8_LAS unsigned char* lds, const Gemm g, const Sched& S, const Epi& E) {
;     ...
;             PG8_LDB(B0, 1, 0); PG8_LDB(B1, 1, 1); PG8_SCHED; PG8_LDA(At, 1, 0); PG8_STAGE(PG8_SA(0, 1), a2 + hstepA, voffA);
;             PG8_WAIT_V(8); PG8_WAIT_L(0); PG8_BAR; PG8_MMA(0, 0, At, B0); PG8_MMA(0, 1, At, B1); PG8_BAR; PG8_SCHED;
;             PG8_LDA(At, 1, 1); PG8_STAGE(PG8_SB(1, 0), b3, voffB); PG8_STAGE(PG8_SB(1, 1), b3 + hstepB, voffB); PG8_STAGE(PG8_SA(1, 0), a3, voffA);
;             PG8_WAIT_V(8); PG8_WAIT_L(0); PG8_BAR; PG8_MMA(1, 0, At, B0); PG8_MMA(1, 1, At, B1); PG8_BAR; PG8_SCHED;
;     ...
;         }
;         if constexpr (ALIGN_EPI) { if (wr == 0) PG8_BAR; }
	s_setprio 0
	s_add_i32 s72, 0, 0x18000
	s_add_i32 s73, 0, 0x1c000
	ds_read_b128 v[130:133], v197 offset:32768
	ds_read_b128 v[134:137], v197 offset:33792
	ds_read_b128 v[138:141], v197 offset:34816
	ds_read_b128 v[142:145], v197 offset:35840
	ds_read_b128 v[146:149], v197 offset:49152
	ds_read_b128 v[150:153], v197 offset:50176
	ds_read_b128 v[154:157], v197 offset:51200
	ds_read_b128 v[158:161], v197 offset:52224
	s_add_u32 s42, s42, 0x4000
	s_addc_u32 s43, s43, 0
	s_mov_b32 m0, s69
	ds_read_b128 v[162:165], v241 offset:32768
	ds_read_b128 v[166:169], v241 offset:33792
	ds_read_b128 v[170:173], v241 offset:34816
	ds_read_b128 v[174:177], v241 offset:35840
	ds_read_b128 v[178:181], v241 offset:36864
	ds_read_b128 v[182:185], v241 offset:37888
	ds_read_b128 v[186:189], v241 offset:38912
	ds_read_b128 v[222:225], v241 offset:39936
	global_load_lds_dwordx4 v190, s[42:43]
	s_mov_b32 m0, s71
	s_nop 0
	global_load_lds_dwordx4 v192, s[42:43]
	s_waitcnt vmcnt(8)
	s_waitcnt lgkmcnt(0)
	s_setprio 1
	s_barrier
	v_mfma_f32_16x16x32_bf16 v[90:93], v[130:133], v[162:165], v[90:93]
	v_mfma_f32_16x16x32_bf16 v[90:93], v[134:137], v[166:169], v[90:93]
	v_mfma_f32_16x16x32_bf16 v[98:101], v[138:141], v[162:165], v[98:101]
	v_mfma_f32_16x16x32_bf16 v[98:101], v[142:145], v[166:169], v[98:101]
	v_mfma_f32_16x16x32_bf16 v[106:109], v[146:149], v[162:165], v[106:109]
	v_mfma_f32_16x16x32_bf16 v[106:109], v[150:153], v[166:169], v[106:109]
	v_mfma_f32_16x16x32_bf16 v[114:117], v[154:157], v[162:165], v[114:117]
	v_mfma_f32_16x16x32_bf16 v[114:117], v[158:161], v[166:169], v[114:117]
	v_mfma_f32_16x16x32_bf16 v[122:125], v[130:133], v[170:173], v[122:125]
	v_mfma_f32_16x16x32_bf16 v[122:125], v[134:137], v[174:177], v[122:125]
	v_mfma_f32_16x16x32_bf16 v[126:129], v[138:141], v[170:173], v[126:129]
	v_mfma_f32_16x16x32_bf16 v[126:129], v[142:145], v[174:177], v[126:129]
	v_mfma_f32_16x16x32_bf16 v[118:121], v[146:149], v[170:173], v[118:121]
	v_mfma_f32_16x16x32_bf16 v[118:121], v[150:153], v[174:177], v[118:121]
	v_mfma_f32_16x16x32_bf16 v[110:113], v[154:157], v[170:173], v[110:113]
	v_mfma_f32_16x16x32_bf16 v[110:113], v[158:161], v[174:177], v[110:113]
	v_mfma_f32_16x16x32_bf16 v[102:105], v[130:133], v[178:181], v[102:105]
	v_mfma_f32_16x16x32_bf16 v[102:105], v[134:137], v[182:185], v[102:105]
	v_mfma_f32_16x16x32_bf16 v[94:97], v[138:141], v[178:181], v[94:97]
	v_mfma_f32_16x16x32_bf16 v[94:97], v[142:145], v[182:185], v[94:97]
	v_mfma_f32_16x16x32_bf16 v[86:89], v[146:149], v[178:181], v[86:89]
	v_mfma_f32_16x16x32_bf16 v[86:89], v[150:153], v[182:185], v[86:89]
	v_mfma_f32_16x16x32_bf16 v[82:85], v[154:157], v[178:181], v[82:85]
	v_mfma_f32_16x16x32_bf16 v[82:85], v[158:161], v[182:185], v[82:85]
	v_mfma_f32_16x16x32_bf16 v[78:81], v[130:133], v[186:189], v[78:81]
	v_mfma_f32_16x16x32_bf16 v[78:81], v[134:137], v[222:225], v[78:81]
	v_mfma_f32_16x16x32_bf16 v[74:77], v[138:141], v[186:189], v[74:77]
	v_mfma_f32_16x16x32_bf16 v[74:77], v[142:145], v[222:225], v[74:77]
	v_mfma_f32_16x16x32_bf16 v[70:73], v[146:149], v[186:189], v[70:73]
	v_mfma_f32_16x16x32_bf16 v[70:73], v[150:153], v[222:225], v[70:73]
	v_mfma_f32_16x16x32_bf16 v[66:69], v[154:157], v[186:189], v[66:69]
	v_mfma_f32_16x16x32_bf16 v[66:69], v[158:161], v[222:225], v[66:69]
	s_barrier
	s_setprio 0
	s_add_u32 s42, s40, 0x8000
	s_addc_u32 s43, s41, 0
	s_add_i32 s72, s72, s59
	s_mov_b32 m0, s72
	ds_read_b128 v[162:165], v241 offset:49152
	ds_read_b128 v[166:169], v241 offset:50176
	ds_read_b128 v[170:173], v241 offset:51200
	ds_read_b128 v[174:177], v241 offset:52224
	ds_read_b128 v[178:181], v241 offset:53248
	ds_read_b128 v[182:185], v241 offset:54272
	ds_read_b128 v[186:189], v241 offset:55296
	ds_read_b128 v[222:225], v241 offset:56320
	global_load_lds_dwordx4 v190, s[42:43]
	s_add_i32 m0, s72, 0x2000
	s_add_u32 s40, s40, 0xc000
	v_lshl_add_u64 v[226:227], s[42:43], 0, v[192:193]
	s_addc_u32 s41, s41, 0
	s_add_i32 s42, s73, s59
	global_load_lds_dwordx4 v[226:227], off
	s_mov_b32 m0, s42
	s_nop 0
	global_load_lds_dwordx4 v190, s[40:41]
	s_add_i32 m0, s42, 0x2000
	s_nop 0
	global_load_lds_dwordx4 v192, s[40:41]
	s_mov_b32 m0, s80
	s_nop 0
	global_load_lds_dwordx4 v190, s[38:39]
	s_mov_b32 m0, s81
	s_nop 0
	global_load_lds_dwordx4 v192, s[38:39]
	s_waitcnt vmcnt(8)
	s_waitcnt lgkmcnt(0)
	s_setprio 1
	s_barrier
	v_mfma_f32_16x16x32_bf16 v[62:65], v[130:133], v[162:165], v[62:65]
	v_mfma_f32_16x16x32_bf16 v[62:65], v[134:137], v[166:169], v[62:65]
	v_mfma_f32_16x16x32_bf16 v[58:61], v[138:141], v[162:165], v[58:61]
	v_mfma_f32_16x16x32_bf16 v[58:61], v[142:145], v[166:169], v[58:61]
	v_mfma_f32_16x16x32_bf16 v[54:57], v[146:149], v[162:165], v[54:57]
	v_mfma_f32_16x16x32_bf16 v[54:57], v[150:153], v[166:169], v[54:57]
	v_mfma_f32_16x16x32_bf16 v[50:53], v[154:157], v[162:165], v[50:53]
	v_mfma_f32_16x16x32_bf16 v[50:53], v[158:161], v[166:169], v[50:53]
	v_mfma_f32_16x16x32_bf16 v[46:49], v[130:133], v[170:173], v[46:49]
	v_mfma_f32_16x16x32_bf16 v[46:49], v[134:137], v[174:177], v[46:49]
	v_mfma_f32_16x16x32_bf16 v[42:45], v[138:141], v[170:173], v[42:45]
	v_mfma_f32_16x16x32_bf16 v[42:45], v[142:145], v[174:177], v[42:45]
	v_mfma_f32_16x16x32_bf16 v[38:41], v[146:149], v[170:173], v[38:41]
	v_mfma_f32_16x16x32_bf16 v[38:41], v[150:153], v[174:177], v[38:41]
	v_mfma_f32_16x16x32_bf16 v[34:37], v[154:157], v[170:173], v[34:37]
	v_mfma_f32_16x16x32_bf16 v[34:37], v[158:161], v[174:177], v[34:37]
	v_mfma_f32_16x16x32_bf16 v[30:33], v[130:133], v[178:181], v[30:33]
	v_mfma_f32_16x16x32_bf16 v[30:33], v[134:137], v[182:185], v[30:33]
	v_mfma_f32_16x16x32_bf16 v[26:29], v[138:141], v[178:181], v[26:29]
	v_mfma_f32_16x16x32_bf16 v[26:29], v[142:145], v[182:185], v[26:29]
	v_mfma_f32_16x16x32_bf16 v[22:25], v[146:149], v[178:181], v[22:25]
	v_mfma_f32_16x16x32_bf16 v[22:25], v[150:153], v[182:185], v[22:25]
	v_mfma_f32_16x16x32_bf16 v[18:21], v[154:157], v[178:181], v[18:21]
	v_mfma_f32_16x16x32_bf16 v[18:21], v[158:161], v[182:185], v[18:21]
	v_mfma_f32_16x16x32_bf16 v[14:17], v[130:133], v[186:189], v[14:17]
	v_mfma_f32_16x16x32_bf16 v[14:17], v[134:137], v[222:225], v[14:17]
	v_mfma_f32_16x16x32_bf16 v[10:13], v[138:141], v[186:189], v[10:13]
	v_mfma_f32_16x16x32_bf16 v[10:13], v[142:145], v[222:225], v[10:13]
	v_mfma_f32_16x16x32_bf16 v[6:9], v[146:149], v[186:189], v[6:9]
	v_mfma_f32_16x16x32_bf16 v[6:9], v[150:153], v[222:225], v[6:9]
	v_mfma_f32_16x16x32_bf16 v[2:5], v[154:157], v[186:189], v[2:5]
	v_mfma_f32_16x16x32_bf16 v[2:5], v[158:161], v[222:225], v[2:5]
	s_barrier
	s_setprio 0
	s_add_i32 s70, s70, 2
	s_add_u32 s36, s36, 0x10000
	s_addc_u32 s37, s37, 0
	s_add_u32 s33, s33, 0x10000
	s_addc_u32 s35, s35, 0
	s_cmpk_gt_u32 s70, 0xa9
	s_cbranch_scc0 .LBB0_274
	s_and_b64 vcc, exec, s[16:17]
	s_cbranch_vccz .LBB0_277
	s_barrier

; #define PG8_STAGE(bufoff, gbase, voff) do { _Pragma("unroll") for (int _i = 0; _i < 2; ++_i) \
;         __builtin_amdgcn_global_load_lds((const unsigned*)((const char*)(gbase) + (voff)[_i]), (PG8_LAS unsigned*)(lds + (bufoff) + ldsw + _i * 8192), 16, 0, 0); } while (0)
; #define PG8_LDA(dst, b, h) do { _Pragma("unroll") for (int m = 0; m < 4; ++m) _Pragma("unroll") for (int k = 0; k < 2; ++k) dst[m][k] = *(const PG8_LAS bf16x8*)(lds + PG8_SA(b, h) + aoff + m * 2048 + k * 1024); } while (0)
; #define PG8_LDB(dst, b, h) do { _Pragma("unroll") for (int n = 0; n < 2; ++n) _Pragma("unroll") for (int k = 0; k < 2; ++k) dst[n][k] = *(const PG8_LAS bf16x8*)(lds + PG8_SB(b, h) + boff + n * 2048 + k * 1024); } while (0)
; #define PG8_WAIT_V(n) asm volatile("s_waitcnt vmcnt(" #n ")" ::: "memory")
; #define PG8_WAIT_L(n) asm volatile("s_waitcnt lgkmcnt(" #n ")" ::: "memory")
; #define PG8_BAR __builtin_amdgcn_s_barrier()
; #define PG8_SCHED __builtin_amdgcn_sched_barrier(0)
; template <class Epi, class Sched, bool ALIGN_EPI = false, bool SP2 = false, bool A_TILED = false>
; __device__ __forceinline__ void gemm_phase(PG8_LAS unsigned char* lds, const Gemm g, const Sched& S, const Epi& E) {
;     ...
;         const bool has_next = S.next(ui + 1, nxt);
;         const char* nA = has_next ? (const char*)g.A + (size_t)nxt.pm * tstepA : cA; const char* nB = has_next ? (const char*)g.Bt + (size_t)nxt.pn * tstepB : cB;
;         for (int t = 0; t < nt; t += 2) {
;             const bool last = (t == nt - 2);
;             const char* a1 = cA + (size_t)(t + 1) * kstepA;
;             const char* a2 = last ? nA : cA + (size_t)(t + 2) * kstepA; const char* b2 = last ? nB : cB + (size_t)(t + 2) * kstepB;
;             const char* a3 = a2 + kstepA; const char* b3 = b2 + kstepB;
;             if (last && has_next) S.a_ready(nxt);
;             if constexpr (SP2) {
;             PG8_LDB(B0, 0, 0); PG8_LDB(B1, 0, 1); PG8_SCHED; PG8_LDA(At, 0, 0); PG8_STAGE(PG8_SA(1, 1), a1 + hstepA, voffA);
;             PG8_WAIT_V(8); PG8_WAIT_L(0); PG8_BAR; PG8_MMA(0, 0, At, B0); PG8_MMA(0, 1, At, B1); PG8_BAR; PG8_SCHED;
;             PG8_LDA(At, 0, 1); PG8_STAGE(PG8_SB(0, 0), b2, voffB); PG8_STAGE(PG8_SB(0, 1), b2 + hstepB, voffB); PG8_STAGE(PG8_SA(0, 0), a2, voffA);
;             PG8_WAIT_V(8); PG8_WAIT_L(0); PG8_BAR; PG8_MMA(1, 0, At, B0); PG8_MMA(1, 1, At, B1); PG8_BAR; PG8_SCHED;
.LBB0_355:
	s_ashr_i32 s39, s38, 31
	s_lshl_b64 s[12:13], s[38:39], 21
	s_add_u32 s40, s78, s12
	s_addc_u32 s41, s79, s13
	s_and_b64 s[12:13], s[0:1], exec
	s_cselect_b32 s3, s41, s9
	s_cselect_b32 s5, s40, s8
	s_ashr_i32 s37, s36, 31
	s_lshl_b64 s[12:13], s[36:37], 21
	s_add_u32 s42, s71, s12
	s_addc_u32 s43, s76, s13
	s_and_b64 s[12:13], s[0:1], exec
	s_cselect_b32 s7, s43, s11
	s_cselect_b32 s33, s42, s10
	s_add_u32 s8, s8, 0xc000
	s_addc_u32 s9, s9, 0
	s_add_u32 s37, s10, 0x10000
	v_mov_b32_e32 v2, 0
	s_addc_u32 s39, s11, 0
	s_mov_b32 s58, -2
	s_waitcnt lgkmcnt(0)
	ds_read_b128 v[156:159], v170
	ds_read_b128 v[160:163], v170 offset:1024
	ds_read_b128 v[164:167], v170 offset:2048
	ds_read_b128 v[176:179], v170 offset:3072
	ds_read_b128 v[180:183], v171
	ds_read_b128 v[184:187], v171 offset:1024
	ds_read_b128 v[188:191], v171 offset:2048
	ds_read_b128 v[192:195], v171 offset:3072
	s_add_u32 s10, s8, 0x4000
	s_addc_u32 s11, s9, 0
	s_cmp_eq_u32 s58, 60
	s_cselect_b32 s44, s5, s10
	s_cselect_b32 s45, s3, s11
	s_cselect_b32 s12, s33, s37
	s_cselect_b32 s13, s7, s39
	s_add_u32 s10, s44, 0x8000
	s_addc_u32 s11, s45, 0
	s_add_i32 m0, s77, 0xc000
	ds_read_b128 v[196:199], v172
	ds_read_b128 v[200:203], v172 offset:1024
	ds_read_b128 v[204:207], v172 offset:2048
	ds_read_b128 v[208:211], v172 offset:3072
	ds_read_b128 v[212:215], v172 offset:4096
	ds_read_b128 v[216:219], v172 offset:5120
	ds_read_b128 v[220:223], v172 offset:6144
	ds_read_b128 v[224:227], v172 offset:7168
	global_load_lds_dwordx4 v148, s[8:9]
	s_add_i32 m0, s77, 0xe000
	s_nop 0
	global_load_lds_dwordx4 v150, s[8:9]
	s_waitcnt vmcnt(8)
	s_waitcnt lgkmcnt(0)
	s_setprio 1
	s_barrier
	v_mfma_f32_16x16x32_bf16 v[126:129], v[156:159], v[196:199], 0
	v_mfma_f32_16x16x32_bf16 v[126:129], v[160:163], v[200:203], v[126:129]
	v_mfma_f32_16x16x32_bf16 v[122:125], v[164:167], v[196:199], 0
	v_mfma_f32_16x16x32_bf16 v[122:125], v[176:179], v[200:203], v[122:125]
	v_mfma_f32_16x16x32_bf16 v[118:121], v[180:183], v[196:199], 0
	v_mfma_f32_16x16x32_bf16 v[118:121], v[184:187], v[200:203], v[118:121]
	v_mfma_f32_16x16x32_bf16 v[114:117], v[188:191], v[196:199], 0
	v_mfma_f32_16x16x32_bf16 v[114:117], v[192:195], v[200:203], v[114:117]
	v_mfma_f32_16x16x32_bf16 v[110:113], v[156:159], v[204:207], 0
	v_mfma_f32_16x16x32_bf16 v[110:113], v[160:163], v[208:211], v[110:113]
	v_mfma_f32_16x16x32_bf16 v[106:109], v[164:167], v[204:207], 0
	v_mfma_f32_16x16x32_bf16 v[106:109], v[176:179], v[208:211], v[106:109]
	v_mfma_f32_16x16x32_bf16 v[102:105], v[180:183], v[204:207], 0
	v_mfma_f32_16x16x32_bf16 v[102:105], v[184:187], v[208:211], v[102:105]
	v_mfma_f32_16x16x32_bf16 v[98:101], v[188:191], v[204:207], 0
	v_mfma_f32_16x16x32_bf16 v[98:101], v[192:195], v[208:211], v[98:101]
	v_mfma_f32_16x16x32_bf16 v[94:97], v[156:159], v[212:215], 0
	v_mfma_f32_16x16x32_bf16 v[94:97], v[160:163], v[216:219], v[94:97]
	v_mfma_f32_16x16x32_bf16 v[90:93], v[164:167], v[212:215], 0
	v_mfma_f32_16x16x32_bf16 v[90:93], v[176:179], v[216:219], v[90:93]
	v_mfma_f32_16x16x32_bf16 v[86:89], v[180:183], v[212:215], 0
	v_mfma_f32_16x16x32_bf16 v[86:89], v[184:187], v[216:219], v[86:89]
	v_mfma_f32_16x16x32_bf16 v[82:85], v[188:191], v[212:215], 0
	v_mfma_f32_16x16x32_bf16 v[82:85], v[192:195], v[216:219], v[82:85]
	v_mfma_f32_16x16x32_bf16 v[78:81], v[156:159], v[220:223], 0
	v_mfma_f32_16x16x32_bf16 v[78:81], v[160:163], v[224:227], v[78:81]
	v_mfma_f32_16x16x32_bf16 v[74:77], v[164:167], v[220:223], 0
	v_mfma_f32_16x16x32_bf16 v[74:77], v[176:179], v[224:227], v[74:77]
	v_mfma_f32_16x16x32_bf16 v[70:73], v[180:183], v[220:223], 0
	v_mfma_f32_16x16x32_bf16 v[70:73], v[184:187], v[224:227], v[70:73]
	v_mfma_f32_16x16x32_bf16 v[66:69], v[188:191], v[220:223], 0
	v_mfma_f32_16x16x32_bf16 v[66:69], v[192:195], v[224:227], v[66:69]
	s_barrier
	s_setprio 0
	s_add_i32 s59, s92, s69
	s_mov_b32 m0, s59
	ds_read_b128 v[196:199], v172 offset:16384
	ds_read_b128 v[200:203], v172 offset:17408
	ds_read_b128 v[204:207], v172 offset:18432
	ds_read_b128 v[208:211], v172 offset:19456
	ds_read_b128 v[212:215], v172 offset:20480
	ds_read_b128 v[216:219], v172 offset:21504
	ds_read_b128 v[220:223], v172 offset:22528
	ds_read_b128 v[224:227], v172 offset:23552
	global_load_lds_dwordx4 v134, s[12:13]
	s_add_i32 m0, s59, 0x2000
	s_add_u32 s62, s12, 0x4000
	s_addc_u32 s63, s13, 0
	s_add_i32 s59, s93, s69
	global_load_lds_dwordx4 v138, s[12:13]
	s_mov_b32 m0, s59
	s_nop 0
	global_load_lds_dwordx4 v134, s[62:63]
	s_add_i32 m0, s59, 0x2000
	s_nop 0
	global_load_lds_dwordx4 v138, s[62:63]
	s_mov_b32 m0, s77
	s_nop 0
	global_load_lds_dwordx4 v132, s[44:45]
	s_mov_b32 m0, s84
	s_nop 0
	global_load_lds_dwordx4 v136, s[44:45]
	s_waitcnt vmcnt(8)
	s_waitcnt lgkmcnt(0)
	s_setprio 1
	s_barrier
; #define PG8_STAGE(bufoff, gbase, voff) do { _Pragma("unroll") for (int _i = 0; _i < 2; ++_i) \
;         __builtin_amdgcn_global_load_lds((const unsigned*)((const char*)(gbase) + (voff)[_i]), (PG8_LAS unsigned*)(lds + (bufoff) + ldsw + _i * 8192), 16, 0, 0); } while (0)
; #define PG8_LDA(dst, b, h) do { _Pragma("unroll") for (int m = 0; m < 4; ++m) _Pragma("unroll") for (int k = 0; k < 2; ++k) dst[m][k] = *(const PG8_LAS bf16x8*)(lds + PG8_SA(b, h) + aoff + m * 2048 + k * 1024); } while (0)
; #define PG8_LDB(dst, b, h) do { _Pragma("unroll") for (int n = 0; n < 2; ++n) _Pragma("unroll") for (int k = 0; k < 2; ++k) dst[n][k] = *(const PG8_LAS bf16x8*)(lds + PG8_SB(b, h) + boff + n * 2048 + k * 1024); } while (0)
; #define PG8_MMA(ai, bj, At, Bt) do { __builtin_amdgcn_s_setprio(1); _Pragma("unroll") for (int m = 0; m < 4; ++m) _Pragma("unroll") for (int n = 0; n < 2; ++n) _Pragma("unroll") for (int k = 0; k < 2; ++k) \
;         acc[ai][bj][m][n] = __builtin_amdgcn_mfma_f32_16x16x32_bf16(Bt[n][k], At[m][k], acc[ai][bj][m][n], 0, 0, 0); __builtin_amdgcn_s_setprio(0); } while (0)
; #define PG8_WAIT_V(n) asm volatile("s_waitcnt vmcnt(" #n ")" ::: "memory")
; #define PG8_WAIT_L(n) asm volatile("s_waitcnt lgkmcnt(" #n ")" ::: "memory")
; #define PG8_BAR __builtin_amdgcn_s_barrier()
; #define PG8_SCHED __builtin_amdgcn_sched_barrier(0)
; template <class Epi, class Sched, bool ALIGN_EPI = false, bool SP2 = false, bool A_TILED = false>
; __device__ __forceinline__ void gemm_phase(PG8_LAS unsigned char* lds, const Gemm g, const Sched& S, const Epi& E) {
;     ...
;             PG8_WAIT_V(8); PG8_WAIT_L(0); PG8_BAR; PG8_MMA(1, 0, At, B0); PG8_MMA(1, 1, At, B1); PG8_BAR; PG8_SCHED;
;             PG8_LDB(B0, 1, 0); PG8_LDB(B1, 1, 1); PG8_SCHED; PG8_LDA(At, 1, 0); PG8_STAGE(PG8_SA(0, 1), a2 + hstepA, voffA);
;             PG8_WAIT_V(8); PG8_WAIT_L(0); PG8_BAR; PG8_MMA(0, 0, At, B0); PG8_MMA(0, 1, At, B1); PG8_BAR; PG8_SCHED;
	v_mfma_f32_16x16x32_bf16 v[62:65], v[156:159], v[196:199], 0
	v_mfma_f32_16x16x32_bf16 v[62:65], v[160:163], v[200:203], v[62:65]
	v_mfma_f32_16x16x32_bf16 v[58:61], v[164:167], v[196:199], 0
	v_mfma_f32_16x16x32_bf16 v[58:61], v[176:179], v[200:203], v[58:61]
	v_mfma_f32_16x16x32_bf16 v[54:57], v[180:183], v[196:199], 0
	v_mfma_f32_16x16x32_bf16 v[54:57], v[184:187], v[200:203], v[54:57]
	v_mfma_f32_16x16x32_bf16 v[50:53], v[188:191], v[196:199], 0
	v_mfma_f32_16x16x32_bf16 v[50:53], v[192:195], v[200:203], v[50:53]
	v_mfma_f32_16x16x32_bf16 v[46:49], v[156:159], v[204:207], 0
	v_mfma_f32_16x16x32_bf16 v[46:49], v[160:163], v[208:211], v[46:49]
	v_mfma_f32_16x16x32_bf16 v[42:45], v[164:167], v[204:207], 0
	v_mfma_f32_16x16x32_bf16 v[42:45], v[176:179], v[208:211], v[42:45]
	v_mfma_f32_16x16x32_bf16 v[38:41], v[180:183], v[204:207], 0
	v_mfma_f32_16x16x32_bf16 v[38:41], v[184:187], v[208:211], v[38:41]
	v_mfma_f32_16x16x32_bf16 v[34:37], v[188:191], v[204:207], 0
	v_mfma_f32_16x16x32_bf16 v[34:37], v[192:195], v[208:211], v[34:37]
	v_mfma_f32_16x16x32_bf16 v[30:33], v[156:159], v[212:215], 0
	v_mfma_f32_16x16x32_bf16 v[30:33], v[160:163], v[216:219], v[30:33]
	v_mfma_f32_16x16x32_bf16 v[26:29], v[164:167], v[212:215], 0
	v_mfma_f32_16x16x32_bf16 v[26:29], v[176:179], v[216:219], v[26:29]
	v_mfma_f32_16x16x32_bf16 v[22:25], v[180:183], v[212:215], 0
	v_mfma_f32_16x16x32_bf16 v[22:25], v[184:187], v[216:219], v[22:25]
	v_mfma_f32_16x16x32_bf16 v[18:21], v[188:191], v[212:215], 0
	v_mfma_f32_16x16x32_bf16 v[18:21], v[192:195], v[216:219], v[18:21]
	v_mfma_f32_16x16x32_bf16 v[14:17], v[156:159], v[220:223], 0
	v_mfma_f32_16x16x32_bf16 v[14:17], v[160:163], v[224:227], v[14:17]
	v_mfma_f32_16x16x32_bf16 v[10:13], v[164:167], v[220:223], 0
	v_mfma_f32_16x16x32_bf16 v[10:13], v[176:179], v[224:227], v[10:13]
	v_mfma_f32_16x16x32_bf16 v[6:9], v[180:183], v[220:223], 0
	v_mfma_f32_16x16x32_bf16 v[6:9], v[184:187], v[224:227], v[6:9]
	v_mfma_f32_16x16x32_bf16 v[2:5], v[188:191], v[220:223], 0
	v_mfma_f32_16x16x32_bf16 v[2:5], v[192:195], v[224:227], v[2:5]
	s_barrier
	s_setprio 0
	s_add_i32 s59, 0, 0x18000
	s_add_i32 s62, 0, 0x1c000
	ds_read_b128 v[156:159], v170 offset:32768
	ds_read_b128 v[160:163], v170 offset:33792
	ds_read_b128 v[164:167], v170 offset:34816
	ds_read_b128 v[176:179], v170 offset:35840
	ds_read_b128 v[180:183], v170 offset:49152
	ds_read_b128 v[184:187], v170 offset:50176
	ds_read_b128 v[188:191], v170 offset:51200
	ds_read_b128 v[192:195], v170 offset:52224
	s_add_u32 s44, s44, 0x4000
	s_addc_u32 s45, s45, 0
	s_mov_b32 m0, s85
	ds_read_b128 v[196:199], v172 offset:32768
	ds_read_b128 v[200:203], v172 offset:33792
	ds_read_b128 v[204:207], v172 offset:34816
	ds_read_b128 v[208:211], v172 offset:35840
	ds_read_b128 v[212:215], v172 offset:36864
	ds_read_b128 v[216:219], v172 offset:37888
	ds_read_b128 v[220:223], v172 offset:38912
	ds_read_b128 v[224:227], v172 offset:39936
	global_load_lds_dwordx4 v132, s[44:45]
	s_mov_b32 m0, s86
	s_nop 0
	global_load_lds_dwordx4 v136, s[44:45]
	s_waitcnt vmcnt(8)
	s_waitcnt lgkmcnt(0)
	s_setprio 1
	s_barrier
	v_mfma_f32_16x16x32_bf16 v[126:129], v[156:159], v[196:199], v[126:129]
	v_mfma_f32_16x16x32_bf16 v[126:129], v[160:163], v[200:203], v[126:129]
	v_mfma_f32_16x16x32_bf16 v[122:125], v[164:167], v[196:199], v[122:125]
	v_mfma_f32_16x16x32_bf16 v[122:125], v[176:179], v[200:203], v[122:125]
	v_mfma_f32_16x16x32_bf16 v[118:121], v[180:183], v[196:199], v[118:121]
	v_mfma_f32_16x16x32_bf16 v[118:121], v[184:187], v[200:203], v[118:121]
	v_mfma_f32_16x16x32_bf16 v[114:117], v[188:191], v[196:199], v[114:117]
	v_mfma_f32_16x16x32_bf16 v[114:117], v[192:195], v[200:203], v[114:117]
	v_mfma_f32_16x16x32_bf16 v[110:113], v[156:159], v[204:207], v[110:113]
	v_mfma_f32_16x16x32_bf16 v[110:113], v[160:163], v[208:211], v[110:113]
	v_mfma_f32_16x16x32_bf16 v[106:109], v[164:167], v[204:207], v[106:109]
	v_mfma_f32_16x16x32_bf16 v[106:109], v[176:179], v[208:211], v[106:109]
	v_mfma_f32_16x16x32_bf16 v[102:105], v[180:183], v[204:207], v[102:105]
	v_mfma_f32_16x16x32_bf16 v[102:105], v[184:187], v[208:211], v[102:105]
	v_mfma_f32_16x16x32_bf16 v[98:101], v[188:191], v[204:207], v[98:101]
	v_mfma_f32_16x16x32_bf16 v[98:101], v[192:195], v[208:211], v[98:101]
	v_mfma_f32_16x16x32_bf16 v[94:97], v[156:159], v[212:215], v[94:97]
	v_mfma_f32_16x16x32_bf16 v[94:97], v[160:163], v[216:219], v[94:97]
	v_mfma_f32_16x16x32_bf16 v[90:93], v[164:167], v[212:215], v[90:93]
	v_mfma_f32_16x16x32_bf16 v[90:93], v[176:179], v[216:219], v[90:93]
	v_mfma_f32_16x16x32_bf16 v[86:89], v[180:183], v[212:215], v[86:89]
	v_mfma_f32_16x16x32_bf16 v[86:89], v[184:187], v[216:219], v[86:89]
	v_mfma_f32_16x16x32_bf16 v[82:85], v[188:191], v[212:215], v[82:85]
	v_mfma_f32_16x16x32_bf16 v[82:85], v[192:195], v[216:219], v[82:85]
	v_mfma_f32_16x16x32_bf16 v[78:81], v[156:159], v[220:223], v[78:81]
	v_mfma_f32_16x16x32_bf16 v[78:81], v[160:163], v[224:227], v[78:81]
	v_mfma_f32_16x16x32_bf16 v[74:77], v[164:167], v[220:223], v[74:77]
	v_mfma_f32_16x16x32_bf16 v[74:77], v[176:179], v[224:227], v[74:77]
	v_mfma_f32_16x16x32_bf16 v[70:73], v[180:183], v[220:223], v[70:73]
	v_mfma_f32_16x16x32_bf16 v[70:73], v[184:187], v[224:227], v[70:73]
	v_mfma_f32_16x16x32_bf16 v[66:69], v[188:191], v[220:223], v[66:69]
	v_mfma_f32_16x16x32_bf16 v[66:69], v[192:195], v[224:227], v[66:69]
	s_barrier
; #define PG8_STAGE(bufoff, gbase, voff) do { _Pragma("unroll") for (int _i = 0; _i < 2; ++_i) \
;         __builtin_amdgcn_global_load_lds((const unsigned*)((const char*)(gbase) + (voff)[_i]), (PG8_LAS unsigned*)(lds + (bufoff) + ldsw + _i * 8192), 16, 0, 0); } while (0)
; #define PG8_LDA(dst, b, h) do { _Pragma("unroll") for (int m = 0; m < 4; ++m) _Pragma("unroll") for (int k = 0; k < 2; ++k) dst[m][k] = *(const PG8_LAS bf16x8*)(lds + PG8_SA(b, h) + aoff + m * 2048 + k * 1024); } while (0)
; #define PG8_LDB(dst, b, h) do { _Pragma("unroll") for (int n = 0; n < 2; ++n) _Pragma("unroll") for (int k = 0; k < 2; ++k) dst[n][k] = *(const PG8_LAS bf16x8*)(lds + PG8_SB(b, h) + boff + n * 2048 + k * 1024); } while (0)
; #define PG8_MMA(ai, bj, At, Bt) do { __builtin_amdgcn_s_setprio(1); _Pragma("unroll") for (int m = 0; m < 4; ++m) _Pragma("unroll") for (int n = 0; n < 2; ++n) _Pragma("unroll") for (int k = 0; k < 2; ++k) \
;         acc[ai][bj][m][n] = __builtin_amdgcn_mfma_f32_16x16x32_bf16(Bt[n][k], At[m][k], acc[ai][bj][m][n], 0, 0, 0); __builtin_amdgcn_s_setprio(0); } while (0)
; #define PG8_WAIT_V(n) asm volatile("s_waitcnt vmcnt(" #n ")" ::: "memory")
; #define PG8_WAIT_L(n) asm volatile("s_waitcnt lgkmcnt(" #n ")" ::: "memory")
; #define PG8_BAR __builtin_amdgcn_s_barrier()
; #define PG8_SCHED __builtin_amdgcn_sched_barrier(0)
; template <class Epi, class Sched, bool ALIGN_EPI = false, bool SP2 = false, bool A_TILED = false>
; __device__ __forceinline__ void gemm_phase(PG8_LAS unsigned char* lds, const Gemm g, const Sched& S, const Epi& E) {
;     ...
;             PG8_LDB(B0, 0, 0); PG8_LDB(B1, 0, 1); PG8_SCHED; PG8_LDA(At, 0, 0); PG8_STAGE(PG8_SA(1, 1), a1 + hstepA, voffA);
;             PG8_WAIT_V(8); PG8_WAIT_L(0); PG8_BAR; PG8_MMA(0, 0, At, B0); PG8_MMA(0, 1, At, B1); PG8_BAR; PG8_SCHED;
;             PG8_LDA(At, 0, 1); PG8_STAGE(PG8_SB(0, 0), b2, voffB); PG8_STAGE(PG8_SB(0, 1), b2 + hstepB, voffB); PG8_STAGE(PG8_SA(0, 0), a2, voffA);
;             PG8_WAIT_V(8); PG8_WAIT_L(0); PG8_BAR; PG8_MMA(1, 0, At, B0); PG8_MMA(1, 1, At, B1); PG8_BAR; PG8_SCHED;
;     ...
;             PG8_LDA(At, 1, 1); PG8_STAGE(PG8_SB(1, 0), b3, voffB); PG8_STAGE(PG8_SB(1, 1), b3 + hstepB, voffB); PG8_STAGE(PG8_SA(1, 0), a3, voffA);
;             PG8_WAIT_V(8); PG8_WAIT_L(0); PG8_BAR; PG8_MMA(1, 0, At, B0); PG8_MMA(1, 1, At, B1); PG8_BAR; PG8_SCHED;
	s_setprio 0
	s_add_u32 s44, s12, 0x8000
	s_addc_u32 s45, s13, 0
	s_add_i32 s59, s59, s69
	s_mov_b32 m0, s59
	ds_read_b128 v[196:199], v172 offset:49152
	ds_read_b128 v[200:203], v172 offset:50176
	ds_read_b128 v[204:207], v172 offset:51200
	ds_read_b128 v[208:211], v172 offset:52224
	ds_read_b128 v[212:215], v172 offset:53248
	ds_read_b128 v[216:219], v172 offset:54272
	ds_read_b128 v[220:223], v172 offset:55296
	ds_read_b128 v[224:227], v172 offset:56320
	global_load_lds_dwordx4 v134, s[44:45]
	s_add_i32 m0, s59, 0x2000
	s_add_u32 s12, s12, 0xc000
	v_lshl_add_u64 v[130:131], s[44:45], 0, v[138:139]
	s_addc_u32 s13, s13, 0
	s_add_i32 s44, s62, s69
	global_load_lds_dwordx4 v[130:131], off
	s_mov_b32 m0, s44
	s_nop 0
	global_load_lds_dwordx4 v134, s[12:13]
	s_add_i32 m0, s44, 0x2000
	s_nop 0
	global_load_lds_dwordx4 v138, s[12:13]
	s_mov_b32 m0, s90
	s_nop 0
	global_load_lds_dwordx4 v132, s[10:11]
	s_mov_b32 m0, s91
	s_nop 0
	global_load_lds_dwordx4 v136, s[10:11]
	s_waitcnt vmcnt(8)
	s_waitcnt lgkmcnt(0)
	s_setprio 1
	s_barrier
	v_mfma_f32_16x16x32_bf16 v[62:65], v[156:159], v[196:199], v[62:65]
	v_mfma_f32_16x16x32_bf16 v[62:65], v[160:163], v[200:203], v[62:65]
	v_mfma_f32_16x16x32_bf16 v[58:61], v[164:167], v[196:199], v[58:61]
	v_mfma_f32_16x16x32_bf16 v[58:61], v[176:179], v[200:203], v[58:61]
	v_mfma_f32_16x16x32_bf16 v[54:57], v[180:183], v[196:199], v[54:57]
	v_mfma_f32_16x16x32_bf16 v[54:57], v[184:187], v[200:203], v[54:57]
	v_mfma_f32_16x16x32_bf16 v[50:53], v[188:191], v[196:199], v[50:53]
	v_mfma_f32_16x16x32_bf16 v[50:53], v[192:195], v[200:203], v[50:53]
	v_mfma_f32_16x16x32_bf16 v[46:49], v[156:159], v[204:207], v[46:49]
	v_mfma_f32_16x16x32_bf16 v[46:49], v[160:163], v[208:211], v[46:49]
	v_mfma_f32_16x16x32_bf16 v[42:45], v[164:167], v[204:207], v[42:45]
	v_mfma_f32_16x16x32_bf16 v[42:45], v[176:179], v[208:211], v[42:45]
	v_mfma_f32_16x16x32_bf16 v[38:41], v[180:183], v[204:207], v[38:41]
	v_mfma_f32_16x16x32_bf16 v[38:41], v[184:187], v[208:211], v[38:41]
	v_mfma_f32_16x16x32_bf16 v[34:37], v[188:191], v[204:207], v[34:37]
	v_mfma_f32_16x16x32_bf16 v[34:37], v[192:195], v[208:211], v[34:37]
	v_mfma_f32_16x16x32_bf16 v[30:33], v[156:159], v[212:215], v[30:33]
	v_mfma_f32_16x16x32_bf16 v[30:33], v[160:163], v[216:219], v[30:33]
	v_mfma_f32_16x16x32_bf16 v[26:29], v[164:167], v[212:215], v[26:29]
	v_mfma_f32_16x16x32_bf16 v[26:29], v[176:179], v[216:219], v[26:29]
	v_mfma_f32_16x16x32_bf16 v[22:25], v[180:183], v[212:215], v[22:25]
	v_mfma_f32_16x16x32_bf16 v[22:25], v[184:187], v[216:219], v[22:25]
	v_mfma_f32_16x16x32_bf16 v[18:21], v[188:191], v[212:215], v[18:21]
	v_mfma_f32_16x16x32_bf16 v[18:21], v[192:195], v[216:219], v[18:21]
	v_mfma_f32_16x16x32_bf16 v[14:17], v[156:159], v[220:223], v[14:17]
	v_mfma_f32_16x16x32_bf16 v[14:17], v[160:163], v[224:227], v[14:17]
	v_mfma_f32_16x16x32_bf16 v[10:13], v[164:167], v[220:223], v[10:13]
	v_mfma_f32_16x16x32_bf16 v[10:13], v[176:179], v[224:227], v[10:13]
	v_mfma_f32_16x16x32_bf16 v[6:9], v[180:183], v[220:223], v[6:9]
	v_mfma_f32_16x16x32_bf16 v[6:9], v[184:187], v[224:227], v[6:9]
	v_mfma_f32_16x16x32_bf16 v[2:5], v[188:191], v[220:223], v[2:5]
	v_mfma_f32_16x16x32_bf16 v[2:5], v[192:195], v[224:227], v[2:5]
	s_barrier
	s_setprio 0
	s_add_i32 s58, s58, 2
	s_add_u32 s8, s8, 0x10000
	s_addc_u32 s9, s9, 0
	s_add_u32 s37, s37, 0x10000
	s_addc_u32 s39, s39, 0
.LBB0_356:
	ds_read_b128 v[156:159], v170
	ds_read_b128 v[160:163], v170 offset:1024
	ds_read_b128 v[164:167], v170 offset:2048
	ds_read_b128 v[176:179], v170 offset:3072
	ds_read_b128 v[180:183], v171
	ds_read_b128 v[184:187], v171 offset:1024
	ds_read_b128 v[188:191], v171 offset:2048
	ds_read_b128 v[192:195], v171 offset:3072
	s_add_u32 s10, s8, 0x4000
	s_addc_u32 s11, s9, 0
	s_cmp_eq_u32 s58, 60
	s_cselect_b32 s44, s5, s10
	s_cselect_b32 s45, s3, s11
	s_cselect_b32 s12, s33, s37
	s_cselect_b32 s13, s7, s39
	s_add_u32 s10, s44, 0x8000
	s_addc_u32 s11, s45, 0
	s_add_i32 m0, s77, 0xc000
	ds_read_b128 v[196:199], v172
	ds_read_b128 v[200:203], v172 offset:1024
	ds_read_b128 v[204:207], v172 offset:2048
	ds_read_b128 v[208:211], v172 offset:3072
	ds_read_b128 v[212:215], v172 offset:4096
	ds_read_b128 v[216:219], v172 offset:5120
	ds_read_b128 v[220:223], v172 offset:6144
	ds_read_b128 v[224:227], v172 offset:7168
	global_load_lds_dwordx4 v148, s[8:9]
	s_add_i32 m0, s77, 0xe000
	s_nop 0
	global_load_lds_dwordx4 v150, s[8:9]
	s_waitcnt vmcnt(8)
	s_waitcnt lgkmcnt(0)
	s_setprio 1
	s_barrier
	v_mfma_f32_16x16x32_bf16 v[126:129], v[156:159], v[196:199], v[126:129]
	v_mfma_f32_16x16x32_bf16 v[126:129], v[160:163], v[200:203], v[126:129]
	v_mfma_f32_16x16x32_bf16 v[122:125], v[164:167], v[196:199], v[122:125]
	v_mfma_f32_16x16x32_bf16 v[122:125], v[176:179], v[200:203], v[122:125]
	v_mfma_f32_16x16x32_bf16 v[118:121], v[180:183], v[196:199], v[118:121]
	v_mfma_f32_16x16x32_bf16 v[118:121], v[184:187], v[200:203], v[118:121]
	v_mfma_f32_16x16x32_bf16 v[114:117], v[188:191], v[196:199], v[114:117]
	v_mfma_f32_16x16x32_bf16 v[114:117], v[192:195], v[200:203], v[114:117]
	v_mfma_f32_16x16x32_bf16 v[110:113], v[156:159], v[204:207], v[110:113]
	v_mfma_f32_16x16x32_bf16 v[110:113], v[160:163], v[208:211], v[110:113]
	v_mfma_f32_16x16x32_bf16 v[106:109], v[164:167], v[204:207], v[106:109]
	v_mfma_f32_16x16x32_bf16 v[106:109], v[176:179], v[208:211], v[106:109]
	v_mfma_f32_16x16x32_bf16 v[102:105], v[180:183], v[204:207], v[102:105]
	v_mfma_f32_16x16x32_bf16 v[102:105], v[184:187], v[208:211], v[102:105]
	v_mfma_f32_16x16x32_bf16 v[98:101], v[188:191], v[204:207], v[98:101]
	v_mfma_f32_16x16x32_bf16 v[98:101], v[192:195], v[208:211], v[98:101]
	v_mfma_f32_16x16x32_bf16 v[94:97], v[156:159], v[212:215], v[94:97]
	v_mfma_f32_16x16x32_bf16 v[94:97], v[160:163], v[216:219], v[94:97]
	v_mfma_f32_16x16x32_bf16 v[90:93], v[164:167], v[212:215], v[90:93]
	v_mfma_f32_16x16x32_bf16 v[90:93], v[176:179], v[216:219], v[90:93]
	v_mfma_f32_16x16x32_bf16 v[86:89], v[180:183], v[212:215], v[86:89]
	v_mfma_f32_16x16x32_bf16 v[86:89], v[184:187], v[216:219], v[86:89]
	v_mfma_f32_16x16x32_bf16 v[82:85], v[188:191], v[212:215], v[82:85]
	v_mfma_f32_16x16x32_bf16 v[82:85], v[192:195], v[216:219], v[82:85]
	v_mfma_f32_16x16x32_bf16 v[78:81], v[156:159], v[220:223], v[78:81]
	v_mfma_f32_16x16x32_bf16 v[78:81], v[160:163], v[224:227], v[78:81]
	v_mfma_f32_16x16x32_bf16 v[74:77], v[164:167], v[220:223], v[74:77]
	v_mfma_f32_16x16x32_bf16 v[74:77], v[176:179], v[224:227], v[74:77]
	v_mfma_f32_16x16x32_bf16 v[70:73], v[180:183], v[220:223], v[70:73]
	v_mfma_f32_16x16x32_bf16 v[70:73], v[184:187], v[224:227], v[70:73]
	v_mfma_f32_16x16x32_bf16 v[66:69], v[188:191], v[220:223], v[66:69]
	v_mfma_f32_16x16x32_bf16 v[66:69], v[192:195], v[224:227], v[66:69]
	s_barrier
; #define PG8_STAGE(bufoff, gbase, voff) do { _Pragma("unroll") for (int _i = 0; _i < 2; ++_i) \
;         __builtin_amdgcn_global_load_lds((const unsigned*)((const char*)(gbase) + (voff)[_i]), (PG8_LAS unsigned*)(lds + (bufoff) + ldsw + _i * 8192), 16, 0, 0); } while (0)
; #define PG8_LDA(dst, b, h) do { _Pragma("unroll") for (int m = 0; m < 4; ++m) _Pragma("unroll") for (int k = 0; k < 2; ++k) dst[m][k] = *(const PG8_LAS bf16x8*)(lds + PG8_SA(b, h) + aoff + m * 2048 + k * 1024); } while (0)
; #define PG8_LDB(dst, b, h) do { _Pragma("unroll") for (int n = 0; n < 2; ++n) _Pragma("unroll") for (int k = 0; k < 2; ++k) dst[n][k] = *(const PG8_LAS bf16x8*)(lds + PG8_SB(b, h) + boff + n * 2048 + k * 1024); } while (0)
; #define PG8_MMA(ai, bj, At, Bt) do { __builtin_amdgcn_s_setprio(1); _Pragma("unroll") for (int m = 0; m < 4; ++m) _Pragma("unroll") for (int n = 0; n < 2; ++n) _Pragma("unroll") for (int k = 0; k < 2; ++k) \
;         acc[ai][bj][m][n] = __builtin_amdgcn_mfma_f32_16x16x32_bf16(Bt[n][k], At[m][k], acc[ai][bj][m][n], 0, 0, 0); __builtin_amdgcn_s_setprio(0); } while (0)
; #define PG8_WAIT_V(n) asm volatile("s_waitcnt vmcnt(" #n ")" ::: "memory")
; #define PG8_WAIT_L(n) asm volatile("s_waitcnt lgkmcnt(" #n ")" ::: "memory")
; #define PG8_BAR __builtin_amdgcn_s_barrier()
; #define PG8_SCHED __builtin_amdgcn_sched_barrier(0)
; template <class Epi, class Sched, bool ALIGN_EPI = false, bool SP2 = false, bool A_TILED = false>
; __device__ __forceinline__ void gemm_phase(PG8_LAS unsigned char* lds, const Gemm g, const Sched& S, const Epi& E) {
;     ...
;             PG8_LDA(At, 0, 1); PG8_STAGE(PG8_SB(0, 0), b2, voffB); PG8_STAGE(PG8_SB(0, 1), b2 + hstepB, voffB); PG8_STAGE(PG8_SA(0, 0), a2, voffA);
;             PG8_WAIT_V(8); PG8_WAIT_L(0); PG8_BAR; PG8_MMA(1, 0, At, B0); PG8_MMA(1, 1, At, B1); PG8_BAR; PG8_SCHED;
;             PG8_LDB(B0, 1, 0); PG8_LDB(B1, 1, 1); PG8_SCHED; PG8_LDA(At, 1, 0); PG8_STAGE(PG8_SA(0, 1), a2 + hstepA, voffA);
;             PG8_WAIT_V(8); PG8_WAIT_L(0); PG8_BAR; PG8_MMA(0, 0, At, B0); PG8_MMA(0, 1, At, B1); PG8_BAR; PG8_SCHED;
	s_setprio 0
	s_add_i32 s59, s92, s69
	s_mov_b32 m0, s59
	ds_read_b128 v[196:199], v172 offset:16384
	ds_read_b128 v[200:203], v172 offset:17408
	ds_read_b128 v[204:207], v172 offset:18432
	ds_read_b128 v[208:211], v172 offset:19456
	ds_read_b128 v[212:215], v172 offset:20480
	ds_read_b128 v[216:219], v172 offset:21504
	ds_read_b128 v[220:223], v172 offset:22528
	ds_read_b128 v[224:227], v172 offset:23552
	global_load_lds_dwordx4 v134, s[12:13]
	s_add_i32 m0, s59, 0x2000
	s_add_u32 s62, s12, 0x4000
	s_addc_u32 s63, s13, 0
	s_add_i32 s59, s93, s69
	global_load_lds_dwordx4 v138, s[12:13]
	s_mov_b32 m0, s59
	s_nop 0
	global_load_lds_dwordx4 v134, s[62:63]
	s_add_i32 m0, s59, 0x2000
	s_nop 0
	global_load_lds_dwordx4 v138, s[62:63]
	s_mov_b32 m0, s77
	s_nop 0
	global_load_lds_dwordx4 v132, s[44:45]
	s_mov_b32 m0, s84
	s_nop 0
	global_load_lds_dwordx4 v136, s[44:45]
	s_waitcnt vmcnt(8)
	s_waitcnt lgkmcnt(0)
	s_setprio 1
	s_barrier
	v_mfma_f32_16x16x32_bf16 v[62:65], v[156:159], v[196:199], v[62:65]
	v_mfma_f32_16x16x32_bf16 v[62:65], v[160:163], v[200:203], v[62:65]
	v_mfma_f32_16x16x32_bf16 v[58:61], v[164:167], v[196:199], v[58:61]
	v_mfma_f32_16x16x32_bf16 v[58:61], v[176:179], v[200:203], v[58:61]
	v_mfma_f32_16x16x32_bf16 v[54:57], v[180:183], v[196:199], v[54:57]
	v_mfma_f32_16x16x32_bf16 v[54:57], v[184:187], v[200:203], v[54:57]
	v_mfma_f32_16x16x32_bf16 v[50:53], v[188:191], v[196:199], v[50:53]
	v_mfma_f32_16x16x32_bf16 v[50:53], v[192:195], v[200:203], v[50:53]
	v_mfma_f32_16x16x32_bf16 v[46:49], v[156:159], v[204:207], v[46:49]
	v_mfma_f32_16x16x32_bf16 v[46:49], v[160:163], v[208:211], v[46:49]
	v_mfma_f32_16x16x32_bf16 v[42:45], v[164:167], v[204:207], v[42:45]
	v_mfma_f32_16x16x32_bf16 v[42:45], v[176:179], v[208:211], v[42:45]
	v_mfma_f32_16x16x32_bf16 v[38:41], v[180:183], v[204:207], v[38:41]
	v_mfma_f32_16x16x32_bf16 v[38:41], v[184:187], v[208:211], v[38:41]
	v_mfma_f32_16x16x32_bf16 v[34:37], v[188:191], v[204:207], v[34:37]
	v_mfma_f32_16x16x32_bf16 v[34:37], v[192:195], v[208:211], v[34:37]
	v_mfma_f32_16x16x32_bf16 v[30:33], v[156:159], v[212:215], v[30:33]
	v_mfma_f32_16x16x32_bf16 v[30:33], v[160:163], v[216:219], v[30:33]
	v_mfma_f32_16x16x32_bf16 v[26:29], v[164:167], v[212:215], v[26:29]
	v_mfma_f32_16x16x32_bf16 v[26:29], v[176:179], v[216:219], v[26:29]
	v_mfma_f32_16x16x32_bf16 v[22:25], v[180:183], v[212:215], v[22:25]
	v_mfma_f32_16x16x32_bf16 v[22:25], v[184:187], v[216:219], v[22:25]
	v_mfma_f32_16x16x32_bf16 v[18:21], v[188:191], v[212:215], v[18:21]
	v_mfma_f32_16x16x32_bf16 v[18:21], v[192:195], v[216:219], v[18:21]
	v_mfma_f32_16x16x32_bf16 v[14:17], v[156:159], v[220:223], v[14:17]
	v_mfma_f32_16x16x32_bf16 v[14:17], v[160:163], v[224:227], v[14:17]
	v_mfma_f32_16x16x32_bf16 v[10:13], v[164:167], v[220:223], v[10:13]
	v_mfma_f32_16x16x32_bf16 v[10:13], v[176:179], v[224:227], v[10:13]
	v_mfma_f32_16x16x32_bf16 v[6:9], v[180:183], v[220:223], v[6:9]
	v_mfma_f32_16x16x32_bf16 v[6:9], v[184:187], v[224:227], v[6:9]
	v_mfma_f32_16x16x32_bf16 v[2:5], v[188:191], v[220:223], v[2:5]
	v_mfma_f32_16x16x32_bf16 v[2:5], v[192:195], v[224:227], v[2:5]
	s_barrier
	s_setprio 0
	s_add_i32 s59, 0, 0x18000
	s_add_i32 s62, 0, 0x1c000
	ds_read_b128 v[156:159], v170 offset:32768
	ds_read_b128 v[160:163], v170 offset:33792
	ds_read_b128 v[164:167], v170 offset:34816
	ds_read_b128 v[176:179], v170 offset:35840
	ds_read_b128 v[180:183], v170 offset:49152
	ds_read_b128 v[184:187], v170 offset:50176
	ds_read_b128 v[188:191], v170 offset:51200
	ds_read_b128 v[192:195], v170 offset:52224
	s_add_u32 s44, s44, 0x4000
	s_addc_u32 s45, s45, 0
	s_mov_b32 m0, s85
	ds_read_b128 v[196:199], v172 offset:32768
	ds_read_b128 v[200:203], v172 offset:33792
	ds_read_b128 v[204:207], v172 offset:34816
	ds_read_b128 v[208:211], v172 offset:35840
	ds_read_b128 v[212:215], v172 offset:36864
	ds_read_b128 v[216:219], v172 offset:37888
	ds_read_b128 v[220:223], v172 offset:38912
	ds_read_b128 v[224:227], v172 offset:39936
	global_load_lds_dwordx4 v132, s[44:45]
	s_mov_b32 m0, s86
	s_nop 0
	global_load_lds_dwordx4 v136, s[44:45]
	s_waitcnt vmcnt(8)
	s_waitcnt lgkmcnt(0)
	s_setprio 1
	s_barrier
; #define PG8_STAGE(bufoff, gbase, voff) do { _Pragma("unroll") for (int _i = 0; _i < 2; ++_i) \
;         __builtin_amdgcn_global_load_lds((const unsigned*)((const char*)(gbase) + (voff)[_i]), (PG8_LAS unsigned*)(lds + (bufoff) + ldsw + _i * 8192), 16, 0, 0); } while (0)
; #define PG8_LDA(dst, b, h) do { _Pragma("unroll") for (int m = 0; m < 4; ++m) _Pragma("unroll") for (int k = 0; k < 2; ++k) dst[m][k] = *(const PG8_LAS bf16x8*)(lds + PG8_SA(b, h) + aoff + m * 2048 + k * 1024); } while (0)
; #define PG8_MMA(ai, bj, At, Bt) do { __builtin_amdgcn_s_setprio(1); _Pragma("unroll") for (int m = 0; m < 4; ++m) _Pragma("unroll") for (int n = 0; n < 2; ++n) _Pragma("unroll") for (int k = 0; k < 2; ++k) \
;         acc[ai][bj][m][n] = __builtin_amdgcn_mfma_f32_16x16x32_bf16(Bt[n][k], At[m][k], acc[ai][bj][m][n], 0, 0, 0); __builtin_amdgcn_s_setprio(0); } while (0)
; #define PG8_WAIT_V(n) asm volatile("s_waitcnt vmcnt(" #n ")" ::: "memory")
; #define PG8_WAIT_L(n) asm volatile("s_waitcnt lgkmcnt(" #n ")" ::: "memory")
; #define PG8_BAR __builtin_amdgcn_s_barrier()
; #define PG8_SCHED __builtin_amdgcn_sched_barrier(0)
; template <class Epi, class Sched, bool ALIGN_EPI = false, bool SP2 = false, bool A_TILED = false>
; __device__ __forceinline__ void gemm_phase(PG8_LAS unsigned char* lds, const Gemm g, const Sched& S, const Epi& E) {
;     ...
;             PG8_WAIT_V(8); PG8_WAIT_L(0); PG8_BAR; PG8_MMA(0, 0, At, B0); PG8_MMA(0, 1, At, B1); PG8_BAR; PG8_SCHED;
;             PG8_LDA(At, 1, 1); PG8_STAGE(PG8_SB(1, 0), b3, voffB); PG8_STAGE(PG8_SB(1, 1), b3 + hstepB, voffB); PG8_STAGE(PG8_SA(1, 0), a3, voffA);
;             PG8_WAIT_V(8); PG8_WAIT_L(0); PG8_BAR; PG8_MMA(1, 0, At, B0); PG8_MMA(1, 1, At, B1); PG8_BAR; PG8_SCHED;
;     ...
;         }
;         if constexpr (ALIGN_EPI) { if (wr == 0) PG8_BAR; }
	v_mfma_f32_16x16x32_bf16 v[126:129], v[156:159], v[196:199], v[126:129]
	v_mfma_f32_16x16x32_bf16 v[126:129], v[160:163], v[200:203], v[126:129]
	v_mfma_f32_16x16x32_bf16 v[122:125], v[164:167], v[196:199], v[122:125]
	v_mfma_f32_16x16x32_bf16 v[122:125], v[176:179], v[200:203], v[122:125]
	v_mfma_f32_16x16x32_bf16 v[118:121], v[180:183], v[196:199], v[118:121]
	v_mfma_f32_16x16x32_bf16 v[118:121], v[184:187], v[200:203], v[118:121]
	v_mfma_f32_16x16x32_bf16 v[114:117], v[188:191], v[196:199], v[114:117]
	v_mfma_f32_16x16x32_bf16 v[114:117], v[192:195], v[200:203], v[114:117]
	v_mfma_f32_16x16x32_bf16 v[110:113], v[156:159], v[204:207], v[110:113]
	v_mfma_f32_16x16x32_bf16 v[110:113], v[160:163], v[208:211], v[110:113]
	v_mfma_f32_16x16x32_bf16 v[106:109], v[164:167], v[204:207], v[106:109]
	v_mfma_f32_16x16x32_bf16 v[106:109], v[176:179], v[208:211], v[106:109]
	v_mfma_f32_16x16x32_bf16 v[102:105], v[180:183], v[204:207], v[102:105]
	v_mfma_f32_16x16x32_bf16 v[102:105], v[184:187], v[208:211], v[102:105]
	v_mfma_f32_16x16x32_bf16 v[98:101], v[188:191], v[204:207], v[98:101]
	v_mfma_f32_16x16x32_bf16 v[98:101], v[192:195], v[208:211], v[98:101]
	v_mfma_f32_16x16x32_bf16 v[94:97], v[156:159], v[212:215], v[94:97]
	v_mfma_f32_16x16x32_bf16 v[94:97], v[160:163], v[216:219], v[94:97]
	v_mfma_f32_16x16x32_bf16 v[90:93], v[164:167], v[212:215], v[90:93]
	v_mfma_f32_16x16x32_bf16 v[90:93], v[176:179], v[216:219], v[90:93]
	v_mfma_f32_16x16x32_bf16 v[86:89], v[180:183], v[212:215], v[86:89]
	v_mfma_f32_16x16x32_bf16 v[86:89], v[184:187], v[216:219], v[86:89]
	v_mfma_f32_16x16x32_bf16 v[82:85], v[188:191], v[212:215], v[82:85]
	v_mfma_f32_16x16x32_bf16 v[82:85], v[192:195], v[216:219], v[82:85]
	v_mfma_f32_16x16x32_bf16 v[78:81], v[156:159], v[220:223], v[78:81]
	v_mfma_f32_16x16x32_bf16 v[78:81], v[160:163], v[224:227], v[78:81]
	v_mfma_f32_16x16x32_bf16 v[74:77], v[164:167], v[220:223], v[74:77]
	v_mfma_f32_16x16x32_bf16 v[74:77], v[176:179], v[224:227], v[74:77]
	v_mfma_f32_16x16x32_bf16 v[70:73], v[180:183], v[220:223], v[70:73]
	v_mfma_f32_16x16x32_bf16 v[70:73], v[184:187], v[224:227], v[70:73]
	v_mfma_f32_16x16x32_bf16 v[66:69], v[188:191], v[220:223], v[66:69]
	v_mfma_f32_16x16x32_bf16 v[66:69], v[192:195], v[224:227], v[66:69]
	s_barrier
	s_setprio 0
	s_add_u32 s44, s12, 0x8000
	s_addc_u32 s45, s13, 0
	s_add_i32 s59, s59, s69
	s_mov_b32 m0, s59
	ds_read_b128 v[196:199], v172 offset:49152
	ds_read_b128 v[200:203], v172 offset:50176
	ds_read_b128 v[204:207], v172 offset:51200
	ds_read_b128 v[208:211], v172 offset:52224
	ds_read_b128 v[212:215], v172 offset:53248
	ds_read_b128 v[216:219], v172 offset:54272
	ds_read_b128 v[220:223], v172 offset:55296
	ds_read_b128 v[224:227], v172 offset:56320
	global_load_lds_dwordx4 v134, s[44:45]
	s_add_i32 m0, s59, 0x2000
	s_add_u32 s12, s12, 0xc000
	v_lshl_add_u64 v[130:131], s[44:45], 0, v[138:139]
	s_addc_u32 s13, s13, 0
	s_add_i32 s44, s62, s69
	global_load_lds_dwordx4 v[130:131], off
	s_mov_b32 m0, s44
	s_nop 0
	global_load_lds_dwordx4 v134, s[12:13]
	s_add_i32 m0, s44, 0x2000
	s_nop 0
	global_load_lds_dwordx4 v138, s[12:13]
	s_mov_b32 m0, s90
	s_nop 0
	global_load_lds_dwordx4 v132, s[10:11]
	s_mov_b32 m0, s91
	s_nop 0
	global_load_lds_dwordx4 v136, s[10:11]
	s_waitcnt vmcnt(8)
	s_waitcnt lgkmcnt(0)
	s_setprio 1
	s_barrier
	v_mfma_f32_16x16x32_bf16 v[62:65], v[156:159], v[196:199], v[62:65]
	v_mfma_f32_16x16x32_bf16 v[62:65], v[160:163], v[200:203], v[62:65]
	v_mfma_f32_16x16x32_bf16 v[58:61], v[164:167], v[196:199], v[58:61]
	v_mfma_f32_16x16x32_bf16 v[58:61], v[176:179], v[200:203], v[58:61]
	v_mfma_f32_16x16x32_bf16 v[54:57], v[180:183], v[196:199], v[54:57]
	v_mfma_f32_16x16x32_bf16 v[54:57], v[184:187], v[200:203], v[54:57]
	v_mfma_f32_16x16x32_bf16 v[50:53], v[188:191], v[196:199], v[50:53]
	v_mfma_f32_16x16x32_bf16 v[50:53], v[192:195], v[200:203], v[50:53]
	v_mfma_f32_16x16x32_bf16 v[46:49], v[156:159], v[204:207], v[46:49]
	v_mfma_f32_16x16x32_bf16 v[46:49], v[160:163], v[208:211], v[46:49]
	v_mfma_f32_16x16x32_bf16 v[42:45], v[164:167], v[204:207], v[42:45]
	v_mfma_f32_16x16x32_bf16 v[42:45], v[176:179], v[208:211], v[42:45]
	v_mfma_f32_16x16x32_bf16 v[38:41], v[180:183], v[204:207], v[38:41]
	v_mfma_f32_16x16x32_bf16 v[38:41], v[184:187], v[208:211], v[38:41]
	v_mfma_f32_16x16x32_bf16 v[34:37], v[188:191], v[204:207], v[34:37]
	v_mfma_f32_16x16x32_bf16 v[34:37], v[192:195], v[208:211], v[34:37]
	v_mfma_f32_16x16x32_bf16 v[30:33], v[156:159], v[212:215], v[30:33]
	v_mfma_f32_16x16x32_bf16 v[30:33], v[160:163], v[216:219], v[30:33]
	v_mfma_f32_16x16x32_bf16 v[26:29], v[164:167], v[212:215], v[26:29]
	v_mfma_f32_16x16x32_bf16 v[26:29], v[176:179], v[216:219], v[26:29]
	v_mfma_f32_16x16x32_bf16 v[22:25], v[180:183], v[212:215], v[22:25]
	v_mfma_f32_16x16x32_bf16 v[22:25], v[184:187], v[216:219], v[22:25]
	v_mfma_f32_16x16x32_bf16 v[18:21], v[188:191], v[212:215], v[18:21]
	v_mfma_f32_16x16x32_bf16 v[18:21], v[192:195], v[216:219], v[18:21]
	v_mfma_f32_16x16x32_bf16 v[14:17], v[156:159], v[220:223], v[14:17]
	v_mfma_f32_16x16x32_bf16 v[14:17], v[160:163], v[224:227], v[14:17]
	v_mfma_f32_16x16x32_bf16 v[10:13], v[164:167], v[220:223], v[10:13]
	v_mfma_f32_16x16x32_bf16 v[10:13], v[176:179], v[224:227], v[10:13]
	v_mfma_f32_16x16x32_bf16 v[6:9], v[180:183], v[220:223], v[6:9]
	v_mfma_f32_16x16x32_bf16 v[6:9], v[184:187], v[224:227], v[6:9]
	v_mfma_f32_16x16x32_bf16 v[2:5], v[188:191], v[220:223], v[2:5]
	v_mfma_f32_16x16x32_bf16 v[2:5], v[192:195], v[224:227], v[2:5]
	s_barrier
	s_setprio 0
	s_add_i32 s58, s58, 2
	s_add_u32 s8, s8, 0x10000
	s_addc_u32 s9, s9, 0
	s_add_u32 s37, s37, 0x10000
	s_addc_u32 s39, s39, 0
	s_cmp_gt_u32 s58, 61
	s_cbranch_scc0 .LBB0_356
	s_and_b64 vcc, exec, s[30:31]
	s_cbranch_vccz .LBB0_359
	s_barrier

; #define PG8_STAGE(bufoff, gbase, voff) do { _Pragma("unroll") for (int _i = 0; _i < 2; ++_i) \
;         __builtin_amdgcn_global_load_lds((const unsigned*)((const char*)(gbase) + (voff)[_i]), (PG8_LAS unsigned*)(lds + (bufoff) + ldsw + _i * 8192), 16, 0, 0); } while (0)
; #define PG8_LDA(dst, b, h) do { _Pragma("unroll") for (int m = 0; m < 4; ++m) _Pragma("unroll") for (int k = 0; k < 2; ++k) dst[m][k] = *(const PG8_LAS bf16x8*)(lds + PG8_SA(b, h) + aoff + m * 2048 + k * 1024); } while (0)
; #define PG8_LDB(dst, b, h) do { _Pragma("unroll") for (int n = 0; n < 2; ++n) _Pragma("unroll") for (int k = 0; k < 2; ++k) dst[n][k] = *(const PG8_LAS bf16x8*)(lds + PG8_SB(b, h) + boff + n * 2048 + k * 1024); } while (0)
; #define PG8_WAIT_V(n) asm volatile("s_waitcnt vmcnt(" #n ")" ::: "memory")
; #define PG8_WAIT_L(n) asm volatile("s_waitcnt lgkmcnt(" #n ")" ::: "memory")
; #define PG8_BAR __builtin_amdgcn_s_barrier()
; #define PG8_SCHED __builtin_amdgcn_sched_barrier(0)
; template <class Epi, class Sched, bool ALIGN_EPI = false, bool SP2 = false, bool A_TILED = false>
; __device__ __forceinline__ void gemm_phase(PG8_LAS unsigned char* lds, const Gemm g, const Sched& S, const Epi& E) {
;     ...
;         const bool has_next = S.next(ui + 1, nxt);
;         const char* nA = has_next ? (const char*)g.A + (size_t)nxt.pm * tstepA : cA; const char* nB = has_next ? (const char*)g.Bt + (size_t)nxt.pn * tstepB : cB;
;         for (int t = 0; t < nt; t += 2) {
;             const bool last = (t == nt - 2);
;             const char* a1 = cA + (size_t)(t + 1) * kstepA;
;             const char* a2 = last ? nA : cA + (size_t)(t + 2) * kstepA; const char* b2 = last ? nB : cB + (size_t)(t + 2) * kstepB;
;             const char* a3 = a2 + kstepA; const char* b3 = b2 + kstepB;
;             if (last && has_next) S.a_ready(nxt);
;             if constexpr (SP2) {
;             PG8_LDB(B0, 0, 0); PG8_LDB(B1, 0, 1); PG8_SCHED; PG8_LDA(At, 0, 0); PG8_STAGE(PG8_SA(1, 1), a1 + hstepA, voffA);
;             PG8_WAIT_V(8); PG8_WAIT_L(0); PG8_BAR; PG8_MMA(0, 0, At, B0); PG8_MMA(0, 1, At, B1); PG8_BAR; PG8_SCHED;
;             PG8_LDA(At, 0, 1); PG8_STAGE(PG8_SB(0, 0), b2, voffB); PG8_STAGE(PG8_SB(0, 1), b2 + hstepB, voffB); PG8_STAGE(PG8_SA(0, 0), a2, voffA);
;             PG8_WAIT_V(8); PG8_WAIT_L(0); PG8_BAR; PG8_MMA(1, 0, At, B0); PG8_MMA(1, 1, At, B1); PG8_BAR; PG8_SCHED;
.LBB0_1171:
	s_ashr_i32 s17, s16, 31
	s_lshl_b64 s[18:19], s[16:17], 21
	s_add_u32 s18, s3, s18
	s_addc_u32 s19, s30, s19
	s_and_b64 s[20:21], s[0:1], exec
	s_cselect_b32 s17, s19, s23
	s_cselect_b32 s33, s18, s22
	s_ashr_i32 s15, s14, 31
	s_lshl_b64 s[20:21], s[14:15], 21
	s_add_u32 s20, s31, s20
	s_addc_u32 s21, s34, s21
	s_and_b64 s[26:27], s[0:1], exec
	s_cselect_b32 s15, s21, s25
	s_cselect_b32 s58, s20, s24
	s_add_u32 s22, s22, 0xc000
	s_addc_u32 s23, s23, 0
	s_add_u32 s59, s24, 0x10000
	v_mov_b32_e32 v2, 0
	s_addc_u32 s60, s25, 0
	s_mov_b32 s61, -2
	ds_read_b128 v[152:155], v141
	ds_read_b128 v[160:163], v141 offset:1024
	ds_read_b128 v[164:167], v141 offset:2048
	ds_read_b128 v[168:171], v141 offset:3072
	ds_read_b128 v[172:175], v156
	ds_read_b128 v[176:179], v156 offset:1024
	ds_read_b128 v[180:183], v156 offset:2048
	ds_read_b128 v[184:187], v156 offset:3072
	s_add_u32 s24, s22, 0x4000
	s_addc_u32 s25, s23, 0
	s_cmp_eq_u32 s61, 60
	s_cselect_b32 s28, s33, s24
	s_cselect_b32 s29, s17, s25
	s_cselect_b32 s26, s58, s59
	s_cselect_b32 s27, s15, s60
	s_add_u32 s24, s28, 0x8000
	s_addc_u32 s25, s29, 0
	s_add_i32 m0, s38, 0xc000
	ds_read_b128 v[188:191], v157
	ds_read_b128 v[192:195], v157 offset:1024
	ds_read_b128 v[196:199], v157 offset:2048
	ds_read_b128 v[200:203], v157 offset:3072
	ds_read_b128 v[204:207], v157 offset:4096
	ds_read_b128 v[208:211], v157 offset:5120
	ds_read_b128 v[212:215], v157 offset:6144
	ds_read_b128 v[216:219], v157 offset:7168
	global_load_lds_dwordx4 v144, s[22:23]
	s_add_i32 m0, s38, 0xe000
	s_nop 0
	global_load_lds_dwordx4 v146, s[22:23]
	s_waitcnt vmcnt(8)
	s_waitcnt lgkmcnt(0)
	s_barrier
	s_setprio 1
	s_waitcnt lgkmcnt(0)
	v_mfma_f32_16x16x32_bf16 v[126:129], v[152:155], v[188:191], 0
	v_mfma_f32_16x16x32_bf16 v[122:125], v[164:167], v[188:191], 0
	v_mfma_f32_16x16x32_bf16 v[110:113], v[152:155], v[196:199], 0
	v_mfma_f32_16x16x32_bf16 v[106:109], v[164:167], v[196:199], 0
	v_mfma_f32_16x16x32_bf16 v[94:97], v[152:155], v[204:207], 0
	v_mfma_f32_16x16x32_bf16 v[90:93], v[164:167], v[204:207], 0
	v_mfma_f32_16x16x32_bf16 v[78:81], v[152:155], v[212:215], 0
	v_mfma_f32_16x16x32_bf16 v[74:77], v[164:167], v[212:215], 0
	v_mfma_f32_16x16x32_bf16 v[126:129], v[160:163], v[192:195], v[126:129]
	v_mfma_f32_16x16x32_bf16 v[122:125], v[168:171], v[192:195], v[122:125]
	v_mfma_f32_16x16x32_bf16 v[110:113], v[160:163], v[200:203], v[110:113]
	v_mfma_f32_16x16x32_bf16 v[106:109], v[168:171], v[200:203], v[106:109]
	v_mfma_f32_16x16x32_bf16 v[94:97], v[160:163], v[208:211], v[94:97]
	v_mfma_f32_16x16x32_bf16 v[90:93], v[168:171], v[208:211], v[90:93]
	v_mfma_f32_16x16x32_bf16 v[78:81], v[160:163], v[216:219], v[78:81]
	v_mfma_f32_16x16x32_bf16 v[74:77], v[168:171], v[216:219], v[74:77]
	s_setprio 0
	s_setprio 1
	v_mfma_f32_16x16x32_bf16 v[118:121], v[172:175], v[188:191], 0
	v_mfma_f32_16x16x32_bf16 v[114:117], v[180:183], v[188:191], 0
	v_mfma_f32_16x16x32_bf16 v[102:105], v[172:175], v[196:199], 0
	v_mfma_f32_16x16x32_bf16 v[98:101], v[180:183], v[196:199], 0
	v_mfma_f32_16x16x32_bf16 v[86:89], v[172:175], v[204:207], 0
	v_mfma_f32_16x16x32_bf16 v[82:85], v[180:183], v[204:207], 0
	v_mfma_f32_16x16x32_bf16 v[70:73], v[172:175], v[212:215], 0
	v_mfma_f32_16x16x32_bf16 v[66:69], v[180:183], v[212:215], 0
	v_mfma_f32_16x16x32_bf16 v[118:121], v[176:179], v[192:195], v[118:121]
	v_mfma_f32_16x16x32_bf16 v[114:117], v[184:187], v[192:195], v[114:117]
	v_mfma_f32_16x16x32_bf16 v[102:105], v[176:179], v[200:203], v[102:105]
	v_mfma_f32_16x16x32_bf16 v[98:101], v[184:187], v[200:203], v[98:101]
	v_mfma_f32_16x16x32_bf16 v[86:89], v[176:179], v[208:211], v[86:89]
	v_mfma_f32_16x16x32_bf16 v[82:85], v[184:187], v[208:211], v[82:85]
	v_mfma_f32_16x16x32_bf16 v[70:73], v[176:179], v[216:219], v[70:73]
	v_mfma_f32_16x16x32_bf16 v[66:69], v[184:187], v[216:219], v[66:69]
	s_setprio 0
	s_barrier
	s_add_i32 s62, s55, s35
	s_mov_b32 m0, s62
	ds_read_b128 v[188:191], v157 offset:16384
	ds_read_b128 v[192:195], v157 offset:17408
	ds_read_b128 v[196:199], v157 offset:18432
	ds_read_b128 v[200:203], v157 offset:19456
	ds_read_b128 v[204:207], v157 offset:20480
	ds_read_b128 v[208:211], v157 offset:21504
	ds_read_b128 v[212:215], v157 offset:22528
	ds_read_b128 v[216:219], v157 offset:23552
	global_load_lds_dwordx4 v132, s[26:27]
	s_add_i32 m0, s62, 0x2000
	s_add_u32 s62, s26, 0x4000
	s_addc_u32 s63, s27, 0
	s_add_i32 s64, s56, s35
	global_load_lds_dwordx4 v136, s[26:27]
	s_mov_b32 m0, s64
	s_nop 0
	global_load_lds_dwordx4 v132, s[62:63]
	s_add_i32 m0, s64, 0x2000
	s_nop 0
	global_load_lds_dwordx4 v136, s[62:63]
	s_mov_b32 m0, s38
	s_nop 0
	global_load_lds_dwordx4 v130, s[28:29]
	s_mov_b32 m0, s39
	s_nop 0
	global_load_lds_dwordx4 v134, s[28:29]
	s_waitcnt vmcnt(8)
	s_waitcnt lgkmcnt(0)
	s_setprio 1
	s_barrier
; #define PG8_STAGE(bufoff, gbase, voff) do { _Pragma("unroll") for (int _i = 0; _i < 2; ++_i) \
;         __builtin_amdgcn_global_load_lds((const unsigned*)((const char*)(gbase) + (voff)[_i]), (PG8_LAS unsigned*)(lds + (bufoff) + ldsw + _i * 8192), 16, 0, 0); } while (0)
; #define PG8_LDA(dst, b, h) do { _Pragma("unroll") for (int m = 0; m < 4; ++m) _Pragma("unroll") for (int k = 0; k < 2; ++k) dst[m][k] = *(const PG8_LAS bf16x8*)(lds + PG8_SA(b, h) + aoff + m * 2048 + k * 1024); } while (0)
; #define PG8_LDB(dst, b, h) do { _Pragma("unroll") for (int n = 0; n < 2; ++n) _Pragma("unroll") for (int k = 0; k < 2; ++k) dst[n][k] = *(const PG8_LAS bf16x8*)(lds + PG8_SB(b, h) + boff + n * 2048 + k * 1024); } while (0)
; #define PG8_MMA(ai, bj, At, Bt) do { __builtin_amdgcn_s_setprio(1); _Pragma("unroll") for (int m = 0; m < 4; ++m) _Pragma("unroll") for (int n = 0; n < 2; ++n) _Pragma("unroll") for (int k = 0; k < 2; ++k) \
;         acc[ai][bj][m][n] = __builtin_amdgcn_mfma_f32_16x16x32_bf16(Bt[n][k], At[m][k], acc[ai][bj][m][n], 0, 0, 0); __builtin_amdgcn_s_setprio(0); } while (0)
; #define PG8_WAIT_V(n) asm volatile("s_waitcnt vmcnt(" #n ")" ::: "memory")
; #define PG8_WAIT_L(n) asm volatile("s_waitcnt lgkmcnt(" #n ")" ::: "memory")
; #define PG8_BAR __builtin_amdgcn_s_barrier()
; #define PG8_SCHED __builtin_amdgcn_sched_barrier(0)
; template <class Epi, class Sched, bool ALIGN_EPI = false, bool SP2 = false, bool A_TILED = false>
; __device__ __forceinline__ void gemm_phase(PG8_LAS unsigned char* lds, const Gemm g, const Sched& S, const Epi& E) {
;     ...
;             PG8_WAIT_V(8); PG8_WAIT_L(0); PG8_BAR; PG8_MMA(1, 0, At, B0); PG8_MMA(1, 1, At, B1); PG8_BAR; PG8_SCHED;
;             PG8_LDB(B0, 1, 0); PG8_LDB(B1, 1, 1); PG8_SCHED; PG8_LDA(At, 1, 0); PG8_STAGE(PG8_SA(0, 1), a2 + hstepA, voffA);
;             PG8_WAIT_V(8); PG8_WAIT_L(0); PG8_BAR; PG8_MMA(0, 0, At, B0); PG8_MMA(0, 1, At, B1); PG8_BAR; PG8_SCHED;
	v_mfma_f32_16x16x32_bf16 v[62:65], v[152:155], v[188:191], 0
	v_mfma_f32_16x16x32_bf16 v[62:65], v[160:163], v[192:195], v[62:65]
	v_mfma_f32_16x16x32_bf16 v[58:61], v[164:167], v[188:191], 0
	v_mfma_f32_16x16x32_bf16 v[58:61], v[168:171], v[192:195], v[58:61]
	v_mfma_f32_16x16x32_bf16 v[54:57], v[172:175], v[188:191], 0
	v_mfma_f32_16x16x32_bf16 v[54:57], v[176:179], v[192:195], v[54:57]
	v_mfma_f32_16x16x32_bf16 v[50:53], v[180:183], v[188:191], 0
	v_mfma_f32_16x16x32_bf16 v[50:53], v[184:187], v[192:195], v[50:53]
	v_mfma_f32_16x16x32_bf16 v[46:49], v[152:155], v[196:199], 0
	v_mfma_f32_16x16x32_bf16 v[46:49], v[160:163], v[200:203], v[46:49]
	v_mfma_f32_16x16x32_bf16 v[42:45], v[164:167], v[196:199], 0
	v_mfma_f32_16x16x32_bf16 v[42:45], v[168:171], v[200:203], v[42:45]
	v_mfma_f32_16x16x32_bf16 v[38:41], v[172:175], v[196:199], 0
	v_mfma_f32_16x16x32_bf16 v[38:41], v[176:179], v[200:203], v[38:41]
	v_mfma_f32_16x16x32_bf16 v[34:37], v[180:183], v[196:199], 0
	v_mfma_f32_16x16x32_bf16 v[34:37], v[184:187], v[200:203], v[34:37]
	v_mfma_f32_16x16x32_bf16 v[30:33], v[152:155], v[204:207], 0
	v_mfma_f32_16x16x32_bf16 v[30:33], v[160:163], v[208:211], v[30:33]
	v_mfma_f32_16x16x32_bf16 v[26:29], v[164:167], v[204:207], 0
	v_mfma_f32_16x16x32_bf16 v[26:29], v[168:171], v[208:211], v[26:29]
	v_mfma_f32_16x16x32_bf16 v[22:25], v[172:175], v[204:207], 0
	v_mfma_f32_16x16x32_bf16 v[22:25], v[176:179], v[208:211], v[22:25]
	v_mfma_f32_16x16x32_bf16 v[18:21], v[180:183], v[204:207], 0
	v_mfma_f32_16x16x32_bf16 v[18:21], v[184:187], v[208:211], v[18:21]
	v_mfma_f32_16x16x32_bf16 v[14:17], v[152:155], v[212:215], 0
	v_mfma_f32_16x16x32_bf16 v[14:17], v[160:163], v[216:219], v[14:17]
	v_mfma_f32_16x16x32_bf16 v[10:13], v[164:167], v[212:215], 0
	v_mfma_f32_16x16x32_bf16 v[10:13], v[168:171], v[216:219], v[10:13]
	v_mfma_f32_16x16x32_bf16 v[6:9], v[172:175], v[212:215], 0
	v_mfma_f32_16x16x32_bf16 v[6:9], v[176:179], v[216:219], v[6:9]
	v_mfma_f32_16x16x32_bf16 v[2:5], v[180:183], v[212:215], 0
	v_mfma_f32_16x16x32_bf16 v[2:5], v[184:187], v[216:219], v[2:5]
	s_barrier
	s_setprio 0
	s_add_i32 s62, 0, 0x18000
	s_add_i32 s63, 0, 0x1c000
	ds_read_b128 v[152:155], v141 offset:32768
	ds_read_b128 v[160:163], v141 offset:33792
	ds_read_b128 v[164:167], v141 offset:34816
	ds_read_b128 v[168:171], v141 offset:35840
	ds_read_b128 v[172:175], v141 offset:49152
	ds_read_b128 v[176:179], v141 offset:50176
	ds_read_b128 v[180:183], v141 offset:51200
	ds_read_b128 v[184:187], v141 offset:52224
	s_add_u32 s28, s28, 0x4000
	s_addc_u32 s29, s29, 0
	s_mov_b32 m0, s40
	ds_read_b128 v[188:191], v157 offset:32768
	ds_read_b128 v[192:195], v157 offset:33792
	ds_read_b128 v[196:199], v157 offset:34816
	ds_read_b128 v[200:203], v157 offset:35840
	ds_read_b128 v[204:207], v157 offset:36864
	ds_read_b128 v[208:211], v157 offset:37888
	ds_read_b128 v[212:215], v157 offset:38912
	ds_read_b128 v[216:219], v157 offset:39936
	global_load_lds_dwordx4 v130, s[28:29]
	s_mov_b32 m0, s41
	s_nop 0
	global_load_lds_dwordx4 v134, s[28:29]
	s_waitcnt vmcnt(8)
	s_waitcnt lgkmcnt(0)
	s_setprio 1
	s_barrier
	v_mfma_f32_16x16x32_bf16 v[126:129], v[152:155], v[188:191], v[126:129]
	v_mfma_f32_16x16x32_bf16 v[126:129], v[160:163], v[192:195], v[126:129]
	v_mfma_f32_16x16x32_bf16 v[122:125], v[164:167], v[188:191], v[122:125]
	v_mfma_f32_16x16x32_bf16 v[122:125], v[168:171], v[192:195], v[122:125]
	v_mfma_f32_16x16x32_bf16 v[118:121], v[172:175], v[188:191], v[118:121]
	v_mfma_f32_16x16x32_bf16 v[118:121], v[176:179], v[192:195], v[118:121]
	v_mfma_f32_16x16x32_bf16 v[114:117], v[180:183], v[188:191], v[114:117]
	v_mfma_f32_16x16x32_bf16 v[114:117], v[184:187], v[192:195], v[114:117]
	v_mfma_f32_16x16x32_bf16 v[110:113], v[152:155], v[196:199], v[110:113]
	v_mfma_f32_16x16x32_bf16 v[110:113], v[160:163], v[200:203], v[110:113]
	v_mfma_f32_16x16x32_bf16 v[106:109], v[164:167], v[196:199], v[106:109]
	v_mfma_f32_16x16x32_bf16 v[106:109], v[168:171], v[200:203], v[106:109]
	v_mfma_f32_16x16x32_bf16 v[102:105], v[172:175], v[196:199], v[102:105]
	v_mfma_f32_16x16x32_bf16 v[102:105], v[176:179], v[200:203], v[102:105]
	v_mfma_f32_16x16x32_bf16 v[98:101], v[180:183], v[196:199], v[98:101]
	v_mfma_f32_16x16x32_bf16 v[98:101], v[184:187], v[200:203], v[98:101]
	v_mfma_f32_16x16x32_bf16 v[94:97], v[152:155], v[204:207], v[94:97]
	v_mfma_f32_16x16x32_bf16 v[94:97], v[160:163], v[208:211], v[94:97]
	v_mfma_f32_16x16x32_bf16 v[90:93], v[164:167], v[204:207], v[90:93]
	v_mfma_f32_16x16x32_bf16 v[90:93], v[168:171], v[208:211], v[90:93]
	v_mfma_f32_16x16x32_bf16 v[86:89], v[172:175], v[204:207], v[86:89]
	v_mfma_f32_16x16x32_bf16 v[86:89], v[176:179], v[208:211], v[86:89]
	v_mfma_f32_16x16x32_bf16 v[82:85], v[180:183], v[204:207], v[82:85]
	v_mfma_f32_16x16x32_bf16 v[82:85], v[184:187], v[208:211], v[82:85]
	v_mfma_f32_16x16x32_bf16 v[78:81], v[152:155], v[212:215], v[78:81]
	v_mfma_f32_16x16x32_bf16 v[78:81], v[160:163], v[216:219], v[78:81]
	v_mfma_f32_16x16x32_bf16 v[74:77], v[164:167], v[212:215], v[74:77]
	v_mfma_f32_16x16x32_bf16 v[74:77], v[168:171], v[216:219], v[74:77]
	v_mfma_f32_16x16x32_bf16 v[70:73], v[172:175], v[212:215], v[70:73]
	v_mfma_f32_16x16x32_bf16 v[70:73], v[176:179], v[216:219], v[70:73]
	v_mfma_f32_16x16x32_bf16 v[66:69], v[180:183], v[212:215], v[66:69]
	v_mfma_f32_16x16x32_bf16 v[66:69], v[184:187], v[216:219], v[66:69]
	s_barrier
; #define PG8_STAGE(bufoff, gbase, voff) do { _Pragma("unroll") for (int _i = 0; _i < 2; ++_i) \
;         __builtin_amdgcn_global_load_lds((const unsigned*)((const char*)(gbase) + (voff)[_i]), (PG8_LAS unsigned*)(lds + (bufoff) + ldsw + _i * 8192), 16, 0, 0); } while (0)
; #define PG8_LDA(dst, b, h) do { _Pragma("unroll") for (int m = 0; m < 4; ++m) _Pragma("unroll") for (int k = 0; k < 2; ++k) dst[m][k] = *(const PG8_LAS bf16x8*)(lds + PG8_SA(b, h) + aoff + m * 2048 + k * 1024); } while (0)
; #define PG8_LDB(dst, b, h) do { _Pragma("unroll") for (int n = 0; n < 2; ++n) _Pragma("unroll") for (int k = 0; k < 2; ++k) dst[n][k] = *(const PG8_LAS bf16x8*)(lds + PG8_SB(b, h) + boff + n * 2048 + k * 1024); } while (0)
; #define PG8_MMA(ai, bj, At, Bt) do { __builtin_amdgcn_s_setprio(1); _Pragma("unroll") for (int m = 0; m < 4; ++m) _Pragma("unroll") for (int n = 0; n < 2; ++n) _Pragma("unroll") for (int k = 0; k < 2; ++k) \
;         acc[ai][bj][m][n] = __builtin_amdgcn_mfma_f32_16x16x32_bf16(Bt[n][k], At[m][k], acc[ai][bj][m][n], 0, 0, 0); __builtin_amdgcn_s_setprio(0); } while (0)
; #define PG8_WAIT_V(n) asm volatile("s_waitcnt vmcnt(" #n ")" ::: "memory")
; #define PG8_WAIT_L(n) asm volatile("s_waitcnt lgkmcnt(" #n ")" ::: "memory")
; #define PG8_BAR __builtin_amdgcn_s_barrier()
; #define PG8_SCHED __builtin_amdgcn_sched_barrier(0)
; template <class Epi, class Sched, bool ALIGN_EPI = false, bool SP2 = false, bool A_TILED = false>
; __device__ __forceinline__ void gemm_phase(PG8_LAS unsigned char* lds, const Gemm g, const Sched& S, const Epi& E) {
;     ...
;             PG8_LDB(B0, 0, 0); PG8_LDB(B1, 0, 1); PG8_SCHED; PG8_LDA(At, 0, 0); PG8_STAGE(PG8_SA(1, 1), a1 + hstepA, voffA);
;             PG8_WAIT_V(8); PG8_WAIT_L(0); PG8_BAR; PG8_MMA(0, 0, At, B0); PG8_MMA(0, 1, At, B1); PG8_BAR; PG8_SCHED;
;             PG8_LDA(At, 0, 1); PG8_STAGE(PG8_SB(0, 0), b2, voffB); PG8_STAGE(PG8_SB(0, 1), b2 + hstepB, voffB); PG8_STAGE(PG8_SA(0, 0), a2, voffA);
;             PG8_WAIT_V(8); PG8_WAIT_L(0); PG8_BAR; PG8_MMA(1, 0, At, B0); PG8_MMA(1, 1, At, B1); PG8_BAR; PG8_SCHED;
;     ...
;             PG8_LDA(At, 1, 1); PG8_STAGE(PG8_SB(1, 0), b3, voffB); PG8_STAGE(PG8_SB(1, 1), b3 + hstepB, voffB); PG8_STAGE(PG8_SA(1, 0), a3, voffA);
;             PG8_WAIT_V(8); PG8_WAIT_L(0); PG8_BAR; PG8_MMA(1, 0, At, B0); PG8_MMA(1, 1, At, B1); PG8_BAR; PG8_SCHED;
	s_setprio 0
	s_add_u32 s28, s26, 0x8000
	s_addc_u32 s29, s27, 0
	s_add_i32 s62, s62, s35
	s_mov_b32 m0, s62
	ds_read_b128 v[188:191], v157 offset:49152
	ds_read_b128 v[192:195], v157 offset:50176
	ds_read_b128 v[196:199], v157 offset:51200
	ds_read_b128 v[200:203], v157 offset:52224
	ds_read_b128 v[204:207], v157 offset:53248
	ds_read_b128 v[208:211], v157 offset:54272
	ds_read_b128 v[212:215], v157 offset:55296
	ds_read_b128 v[216:219], v157 offset:56320
	global_load_lds_dwordx4 v132, s[28:29]
	s_add_i32 m0, s62, 0x2000
	s_add_u32 s26, s26, 0xc000
	v_lshl_add_u64 v[220:221], s[28:29], 0, v[136:137]
	s_addc_u32 s27, s27, 0
	s_add_i32 s28, s63, s35
	global_load_lds_dwordx4 v[220:221], off
	s_mov_b32 m0, s28
	s_nop 0
	global_load_lds_dwordx4 v132, s[26:27]
	s_add_i32 m0, s28, 0x2000
	s_nop 0
	global_load_lds_dwordx4 v136, s[26:27]
	s_mov_b32 m0, s45
	s_nop 0
	global_load_lds_dwordx4 v130, s[24:25]
	s_mov_b32 m0, s54
	s_nop 0
	global_load_lds_dwordx4 v134, s[24:25]
	s_waitcnt vmcnt(8)
	s_waitcnt lgkmcnt(0)
	s_setprio 1
	s_barrier
	v_mfma_f32_16x16x32_bf16 v[62:65], v[152:155], v[188:191], v[62:65]
	v_mfma_f32_16x16x32_bf16 v[62:65], v[160:163], v[192:195], v[62:65]
	v_mfma_f32_16x16x32_bf16 v[58:61], v[164:167], v[188:191], v[58:61]
	v_mfma_f32_16x16x32_bf16 v[58:61], v[168:171], v[192:195], v[58:61]
	v_mfma_f32_16x16x32_bf16 v[54:57], v[172:175], v[188:191], v[54:57]
	v_mfma_f32_16x16x32_bf16 v[54:57], v[176:179], v[192:195], v[54:57]
	v_mfma_f32_16x16x32_bf16 v[50:53], v[180:183], v[188:191], v[50:53]
	v_mfma_f32_16x16x32_bf16 v[50:53], v[184:187], v[192:195], v[50:53]
	v_mfma_f32_16x16x32_bf16 v[46:49], v[152:155], v[196:199], v[46:49]
	v_mfma_f32_16x16x32_bf16 v[46:49], v[160:163], v[200:203], v[46:49]
	v_mfma_f32_16x16x32_bf16 v[42:45], v[164:167], v[196:199], v[42:45]
	v_mfma_f32_16x16x32_bf16 v[42:45], v[168:171], v[200:203], v[42:45]
	v_mfma_f32_16x16x32_bf16 v[38:41], v[172:175], v[196:199], v[38:41]
	v_mfma_f32_16x16x32_bf16 v[38:41], v[176:179], v[200:203], v[38:41]
	v_mfma_f32_16x16x32_bf16 v[34:37], v[180:183], v[196:199], v[34:37]
	v_mfma_f32_16x16x32_bf16 v[34:37], v[184:187], v[200:203], v[34:37]
	v_mfma_f32_16x16x32_bf16 v[30:33], v[152:155], v[204:207], v[30:33]
	v_mfma_f32_16x16x32_bf16 v[30:33], v[160:163], v[208:211], v[30:33]
	v_mfma_f32_16x16x32_bf16 v[26:29], v[164:167], v[204:207], v[26:29]
	v_mfma_f32_16x16x32_bf16 v[26:29], v[168:171], v[208:211], v[26:29]
	v_mfma_f32_16x16x32_bf16 v[22:25], v[172:175], v[204:207], v[22:25]
	v_mfma_f32_16x16x32_bf16 v[22:25], v[176:179], v[208:211], v[22:25]
	v_mfma_f32_16x16x32_bf16 v[18:21], v[180:183], v[204:207], v[18:21]
	v_mfma_f32_16x16x32_bf16 v[18:21], v[184:187], v[208:211], v[18:21]
	v_mfma_f32_16x16x32_bf16 v[14:17], v[152:155], v[212:215], v[14:17]
	v_mfma_f32_16x16x32_bf16 v[14:17], v[160:163], v[216:219], v[14:17]
	v_mfma_f32_16x16x32_bf16 v[10:13], v[164:167], v[212:215], v[10:13]
	v_mfma_f32_16x16x32_bf16 v[10:13], v[168:171], v[216:219], v[10:13]
	v_mfma_f32_16x16x32_bf16 v[6:9], v[172:175], v[212:215], v[6:9]
	v_mfma_f32_16x16x32_bf16 v[6:9], v[176:179], v[216:219], v[6:9]
	v_mfma_f32_16x16x32_bf16 v[2:5], v[180:183], v[212:215], v[2:5]
	v_mfma_f32_16x16x32_bf16 v[2:5], v[184:187], v[216:219], v[2:5]
	s_barrier
	s_setprio 0
	s_add_i32 s61, s61, 2
	s_add_u32 s22, s22, 0x10000
	s_addc_u32 s23, s23, 0
	s_add_u32 s59, s59, 0x10000
	s_addc_u32 s60, s60, 0
.LBB0_1172:
	ds_read_b128 v[152:155], v141
	ds_read_b128 v[160:163], v141 offset:1024
	ds_read_b128 v[164:167], v141 offset:2048
	ds_read_b128 v[168:171], v141 offset:3072
	ds_read_b128 v[172:175], v156
	ds_read_b128 v[176:179], v156 offset:1024
	ds_read_b128 v[180:183], v156 offset:2048
	ds_read_b128 v[184:187], v156 offset:3072
	s_add_u32 s24, s22, 0x4000
	s_addc_u32 s25, s23, 0
	s_cmp_eq_u32 s61, 60
	s_cselect_b32 s28, s33, s24
	s_cselect_b32 s29, s17, s25
	s_cselect_b32 s26, s58, s59
	s_cselect_b32 s27, s15, s60
	s_add_u32 s24, s28, 0x8000
	s_addc_u32 s25, s29, 0
	s_add_i32 m0, s38, 0xc000
	ds_read_b128 v[188:191], v157
	ds_read_b128 v[192:195], v157 offset:1024
	ds_read_b128 v[196:199], v157 offset:2048
	ds_read_b128 v[200:203], v157 offset:3072
	ds_read_b128 v[204:207], v157 offset:4096
	ds_read_b128 v[208:211], v157 offset:5120
	ds_read_b128 v[212:215], v157 offset:6144
	ds_read_b128 v[216:219], v157 offset:7168
	global_load_lds_dwordx4 v144, s[22:23]
	s_add_i32 m0, s38, 0xe000
	s_nop 0
	global_load_lds_dwordx4 v146, s[22:23]
	s_waitcnt vmcnt(8)
	s_waitcnt lgkmcnt(0)
	s_barrier
; #define PG8_STAGE(bufoff, gbase, voff) do { _Pragma("unroll") for (int _i = 0; _i < 2; ++_i) \
;         __builtin_amdgcn_global_load_lds((const unsigned*)((const char*)(gbase) + (voff)[_i]), (PG8_LAS unsigned*)(lds + (bufoff) + ldsw + _i * 8192), 16, 0, 0); } while (0)
; #define PG8_LDA(dst, b, h) do { _Pragma("unroll") for (int m = 0; m < 4; ++m) _Pragma("unroll") for (int k = 0; k < 2; ++k) dst[m][k] = *(const PG8_LAS bf16x8*)(lds + PG8_SA(b, h) + aoff + m * 2048 + k * 1024); } while (0)
; #define PG8_MMA(ai, bj, At, Bt) do { __builtin_amdgcn_s_setprio(1); _Pragma("unroll") for (int m = 0; m < 4; ++m) _Pragma("unroll") for (int n = 0; n < 2; ++n) _Pragma("unroll") for (int k = 0; k < 2; ++k) \
;         acc[ai][bj][m][n] = __builtin_amdgcn_mfma_f32_16x16x32_bf16(Bt[n][k], At[m][k], acc[ai][bj][m][n], 0, 0, 0); __builtin_amdgcn_s_setprio(0); } while (0)
; #define PG8_WAIT_V(n) asm volatile("s_waitcnt vmcnt(" #n ")" ::: "memory")
; #define PG8_WAIT_L(n) asm volatile("s_waitcnt lgkmcnt(" #n ")" ::: "memory")
; #define PG8_BAR __builtin_amdgcn_s_barrier()
; #define PG8_SCHED __builtin_amdgcn_sched_barrier(0)
; template <class Epi, class Sched, bool ALIGN_EPI = false, bool SP2 = false, bool A_TILED = false>
; __device__ __forceinline__ void gemm_phase(PG8_LAS unsigned char* lds, const Gemm g, const Sched& S, const Epi& E) {
;     ...
;             PG8_WAIT_V(8); PG8_WAIT_L(0); PG8_BAR; PG8_MMA(0, 0, At, B0); PG8_MMA(0, 1, At, B1); PG8_BAR; PG8_SCHED;
;             PG8_LDA(At, 0, 1); PG8_STAGE(PG8_SB(0, 0), b2, voffB); PG8_STAGE(PG8_SB(0, 1), b2 + hstepB, voffB); PG8_STAGE(PG8_SA(0, 0), a2, voffA);
;             PG8_WAIT_V(8); PG8_WAIT_L(0); PG8_BAR; PG8_MMA(1, 0, At, B0); PG8_MMA(1, 1, At, B1); PG8_BAR; PG8_SCHED;
	s_setprio 1
	s_waitcnt lgkmcnt(0)
	v_mfma_f32_16x16x32_bf16 v[126:129], v[152:155], v[188:191], v[126:129]
	v_mfma_f32_16x16x32_bf16 v[122:125], v[164:167], v[188:191], v[122:125]
	v_mfma_f32_16x16x32_bf16 v[110:113], v[152:155], v[196:199], v[110:113]
	v_mfma_f32_16x16x32_bf16 v[106:109], v[164:167], v[196:199], v[106:109]
	v_mfma_f32_16x16x32_bf16 v[94:97], v[152:155], v[204:207], v[94:97]
	v_mfma_f32_16x16x32_bf16 v[90:93], v[164:167], v[204:207], v[90:93]
	v_mfma_f32_16x16x32_bf16 v[78:81], v[152:155], v[212:215], v[78:81]
	v_mfma_f32_16x16x32_bf16 v[74:77], v[164:167], v[212:215], v[74:77]
	v_mfma_f32_16x16x32_bf16 v[126:129], v[160:163], v[192:195], v[126:129]
	v_mfma_f32_16x16x32_bf16 v[122:125], v[168:171], v[192:195], v[122:125]
	v_mfma_f32_16x16x32_bf16 v[110:113], v[160:163], v[200:203], v[110:113]
	v_mfma_f32_16x16x32_bf16 v[106:109], v[168:171], v[200:203], v[106:109]
	v_mfma_f32_16x16x32_bf16 v[94:97], v[160:163], v[208:211], v[94:97]
	v_mfma_f32_16x16x32_bf16 v[90:93], v[168:171], v[208:211], v[90:93]
	v_mfma_f32_16x16x32_bf16 v[78:81], v[160:163], v[216:219], v[78:81]
	v_mfma_f32_16x16x32_bf16 v[74:77], v[168:171], v[216:219], v[74:77]
	s_setprio 0
	s_setprio 1
	v_mfma_f32_16x16x32_bf16 v[118:121], v[172:175], v[188:191], v[118:121]
	v_mfma_f32_16x16x32_bf16 v[114:117], v[180:183], v[188:191], v[114:117]
	v_mfma_f32_16x16x32_bf16 v[102:105], v[172:175], v[196:199], v[102:105]
	v_mfma_f32_16x16x32_bf16 v[98:101], v[180:183], v[196:199], v[98:101]
	v_mfma_f32_16x16x32_bf16 v[86:89], v[172:175], v[204:207], v[86:89]
	v_mfma_f32_16x16x32_bf16 v[82:85], v[180:183], v[204:207], v[82:85]
	v_mfma_f32_16x16x32_bf16 v[70:73], v[172:175], v[212:215], v[70:73]
	v_mfma_f32_16x16x32_bf16 v[66:69], v[180:183], v[212:215], v[66:69]
	v_mfma_f32_16x16x32_bf16 v[118:121], v[176:179], v[192:195], v[118:121]
	v_mfma_f32_16x16x32_bf16 v[114:117], v[184:187], v[192:195], v[114:117]
	v_mfma_f32_16x16x32_bf16 v[102:105], v[176:179], v[200:203], v[102:105]
	v_mfma_f32_16x16x32_bf16 v[98:101], v[184:187], v[200:203], v[98:101]
	v_mfma_f32_16x16x32_bf16 v[86:89], v[176:179], v[208:211], v[86:89]
	v_mfma_f32_16x16x32_bf16 v[82:85], v[184:187], v[208:211], v[82:85]
	v_mfma_f32_16x16x32_bf16 v[70:73], v[176:179], v[216:219], v[70:73]
	v_mfma_f32_16x16x32_bf16 v[66:69], v[184:187], v[216:219], v[66:69]
	s_setprio 0
	s_barrier
	s_add_i32 s62, s55, s35
	s_mov_b32 m0, s62
	ds_read_b128 v[188:191], v157 offset:16384
	ds_read_b128 v[192:195], v157 offset:17408
	ds_read_b128 v[196:199], v157 offset:18432
	ds_read_b128 v[200:203], v157 offset:19456
	ds_read_b128 v[204:207], v157 offset:20480
	ds_read_b128 v[208:211], v157 offset:21504
	ds_read_b128 v[212:215], v157 offset:22528
	ds_read_b128 v[216:219], v157 offset:23552
	global_load_lds_dwordx4 v132, s[26:27]
	s_add_i32 m0, s62, 0x2000
	s_add_u32 s62, s26, 0x4000
	s_addc_u32 s63, s27, 0
	s_add_i32 s64, s56, s35
	global_load_lds_dwordx4 v136, s[26:27]
	s_mov_b32 m0, s64
	s_nop 0
	global_load_lds_dwordx4 v132, s[62:63]
	s_add_i32 m0, s64, 0x2000
	s_nop 0
	global_load_lds_dwordx4 v136, s[62:63]
	s_mov_b32 m0, s38
	s_nop 0
	global_load_lds_dwordx4 v130, s[28:29]
	s_mov_b32 m0, s39
	s_nop 0
	global_load_lds_dwordx4 v134, s[28:29]
	s_waitcnt vmcnt(8)
	s_waitcnt lgkmcnt(0)
	s_setprio 1
	s_barrier
	v_mfma_f32_16x16x32_bf16 v[62:65], v[152:155], v[188:191], v[62:65]
	v_mfma_f32_16x16x32_bf16 v[62:65], v[160:163], v[192:195], v[62:65]
	v_mfma_f32_16x16x32_bf16 v[58:61], v[164:167], v[188:191], v[58:61]
	v_mfma_f32_16x16x32_bf16 v[58:61], v[168:171], v[192:195], v[58:61]
	v_mfma_f32_16x16x32_bf16 v[54:57], v[172:175], v[188:191], v[54:57]
	v_mfma_f32_16x16x32_bf16 v[54:57], v[176:179], v[192:195], v[54:57]
	v_mfma_f32_16x16x32_bf16 v[50:53], v[180:183], v[188:191], v[50:53]
	v_mfma_f32_16x16x32_bf16 v[50:53], v[184:187], v[192:195], v[50:53]
	v_mfma_f32_16x16x32_bf16 v[46:49], v[152:155], v[196:199], v[46:49]
	v_mfma_f32_16x16x32_bf16 v[46:49], v[160:163], v[200:203], v[46:49]
	v_mfma_f32_16x16x32_bf16 v[42:45], v[164:167], v[196:199], v[42:45]
	v_mfma_f32_16x16x32_bf16 v[42:45], v[168:171], v[200:203], v[42:45]
	v_mfma_f32_16x16x32_bf16 v[38:41], v[172:175], v[196:199], v[38:41]
	v_mfma_f32_16x16x32_bf16 v[38:41], v[176:179], v[200:203], v[38:41]
	v_mfma_f32_16x16x32_bf16 v[34:37], v[180:183], v[196:199], v[34:37]
	v_mfma_f32_16x16x32_bf16 v[34:37], v[184:187], v[200:203], v[34:37]
	v_mfma_f32_16x16x32_bf16 v[30:33], v[152:155], v[204:207], v[30:33]
	v_mfma_f32_16x16x32_bf16 v[30:33], v[160:163], v[208:211], v[30:33]
	v_mfma_f32_16x16x32_bf16 v[26:29], v[164:167], v[204:207], v[26:29]
	v_mfma_f32_16x16x32_bf16 v[26:29], v[168:171], v[208:211], v[26:29]
	v_mfma_f32_16x16x32_bf16 v[22:25], v[172:175], v[204:207], v[22:25]
	v_mfma_f32_16x16x32_bf16 v[22:25], v[176:179], v[208:211], v[22:25]
	v_mfma_f32_16x16x32_bf16 v[18:21], v[180:183], v[204:207], v[18:21]
	v_mfma_f32_16x16x32_bf16 v[18:21], v[184:187], v[208:211], v[18:21]
	v_mfma_f32_16x16x32_bf16 v[14:17], v[152:155], v[212:215], v[14:17]
	v_mfma_f32_16x16x32_bf16 v[14:17], v[160:163], v[216:219], v[14:17]
	v_mfma_f32_16x16x32_bf16 v[10:13], v[164:167], v[212:215], v[10:13]
	v_mfma_f32_16x16x32_bf16 v[10:13], v[168:171], v[216:219], v[10:13]
	v_mfma_f32_16x16x32_bf16 v[6:9], v[172:175], v[212:215], v[6:9]
	v_mfma_f32_16x16x32_bf16 v[6:9], v[176:179], v[216:219], v[6:9]
	v_mfma_f32_16x16x32_bf16 v[2:5], v[180:183], v[212:215], v[2:5]
	v_mfma_f32_16x16x32_bf16 v[2:5], v[184:187], v[216:219], v[2:5]
	s_barrier
; #define PG8_STAGE(bufoff, gbase, voff) do { _Pragma("unroll") for (int _i = 0; _i < 2; ++_i) \
;         __builtin_amdgcn_global_load_lds((const unsigned*)((const char*)(gbase) + (voff)[_i]), (PG8_LAS unsigned*)(lds + (bufoff) + ldsw + _i * 8192), 16, 0, 0); } while (0)
; #define PG8_LDA(dst, b, h) do { _Pragma("unroll") for (int m = 0; m < 4; ++m) _Pragma("unroll") for (int k = 0; k < 2; ++k) dst[m][k] = *(const PG8_LAS bf16x8*)(lds + PG8_SA(b, h) + aoff + m * 2048 + k * 1024); } while (0)
; #define PG8_LDB(dst, b, h) do { _Pragma("unroll") for (int n = 0; n < 2; ++n) _Pragma("unroll") for (int k = 0; k < 2; ++k) dst[n][k] = *(const PG8_LAS bf16x8*)(lds + PG8_SB(b, h) + boff + n * 2048 + k * 1024); } while (0)
; #define PG8_MMA(ai, bj, At, Bt) do { __builtin_amdgcn_s_setprio(1); _Pragma("unroll") for (int m = 0; m < 4; ++m) _Pragma("unroll") for (int n = 0; n < 2; ++n) _Pragma("unroll") for (int k = 0; k < 2; ++k) \
;         acc[ai][bj][m][n] = __builtin_amdgcn_mfma_f32_16x16x32_bf16(Bt[n][k], At[m][k], acc[ai][bj][m][n], 0, 0, 0); __builtin_amdgcn_s_setprio(0); } while (0)
; #define PG8_WAIT_V(n) asm volatile("s_waitcnt vmcnt(" #n ")" ::: "memory")
; #define PG8_WAIT_L(n) asm volatile("s_waitcnt lgkmcnt(" #n ")" ::: "memory")
; #define PG8_BAR __builtin_amdgcn_s_barrier()
; #define PG8_SCHED __builtin_amdgcn_sched_barrier(0)
; template <class Epi, class Sched, bool ALIGN_EPI = false, bool SP2 = false, bool A_TILED = false>
; __device__ __forceinline__ void gemm_phase(PG8_LAS unsigned char* lds, const Gemm g, const Sched& S, const Epi& E) {
;     ...
;             PG8_LDB(B0, 1, 0); PG8_LDB(B1, 1, 1); PG8_SCHED; PG8_LDA(At, 1, 0); PG8_STAGE(PG8_SA(0, 1), a2 + hstepA, voffA);
;             PG8_WAIT_V(8); PG8_WAIT_L(0); PG8_BAR; PG8_MMA(0, 0, At, B0); PG8_MMA(0, 1, At, B1); PG8_BAR; PG8_SCHED;
;             PG8_LDA(At, 1, 1); PG8_STAGE(PG8_SB(1, 0), b3, voffB); PG8_STAGE(PG8_SB(1, 1), b3 + hstepB, voffB); PG8_STAGE(PG8_SA(1, 0), a3, voffA);
;             PG8_WAIT_V(8); PG8_WAIT_L(0); PG8_BAR; PG8_MMA(1, 0, At, B0); PG8_MMA(1, 1, At, B1); PG8_BAR; PG8_SCHED;
;     ...
;         }
;         if constexpr (ALIGN_EPI) { if (wr == 0) PG8_BAR; }
	s_setprio 0
	s_add_i32 s62, 0, 0x18000
	s_add_i32 s63, 0, 0x1c000
	ds_read_b128 v[152:155], v141 offset:32768
	ds_read_b128 v[160:163], v141 offset:33792
	ds_read_b128 v[164:167], v141 offset:34816
	ds_read_b128 v[168:171], v141 offset:35840
	ds_read_b128 v[172:175], v141 offset:49152
	ds_read_b128 v[176:179], v141 offset:50176
	ds_read_b128 v[180:183], v141 offset:51200
	ds_read_b128 v[184:187], v141 offset:52224
	s_add_u32 s28, s28, 0x4000
	s_addc_u32 s29, s29, 0
	s_mov_b32 m0, s40
	ds_read_b128 v[188:191], v157 offset:32768
	ds_read_b128 v[192:195], v157 offset:33792
	ds_read_b128 v[196:199], v157 offset:34816
	ds_read_b128 v[200:203], v157 offset:35840
	ds_read_b128 v[204:207], v157 offset:36864
	ds_read_b128 v[208:211], v157 offset:37888
	ds_read_b128 v[212:215], v157 offset:38912
	ds_read_b128 v[216:219], v157 offset:39936
	global_load_lds_dwordx4 v130, s[28:29]
	s_mov_b32 m0, s41
	s_nop 0
	global_load_lds_dwordx4 v134, s[28:29]
	s_waitcnt vmcnt(8)
	s_waitcnt lgkmcnt(0)
	s_setprio 1
	s_barrier
	v_mfma_f32_16x16x32_bf16 v[126:129], v[152:155], v[188:191], v[126:129]
	v_mfma_f32_16x16x32_bf16 v[126:129], v[160:163], v[192:195], v[126:129]
	v_mfma_f32_16x16x32_bf16 v[122:125], v[164:167], v[188:191], v[122:125]
	v_mfma_f32_16x16x32_bf16 v[122:125], v[168:171], v[192:195], v[122:125]
	v_mfma_f32_16x16x32_bf16 v[118:121], v[172:175], v[188:191], v[118:121]
	v_mfma_f32_16x16x32_bf16 v[118:121], v[176:179], v[192:195], v[118:121]
	v_mfma_f32_16x16x32_bf16 v[114:117], v[180:183], v[188:191], v[114:117]
	v_mfma_f32_16x16x32_bf16 v[114:117], v[184:187], v[192:195], v[114:117]
	v_mfma_f32_16x16x32_bf16 v[110:113], v[152:155], v[196:199], v[110:113]
	v_mfma_f32_16x16x32_bf16 v[110:113], v[160:163], v[200:203], v[110:113]
	v_mfma_f32_16x16x32_bf16 v[106:109], v[164:167], v[196:199], v[106:109]
	v_mfma_f32_16x16x32_bf16 v[106:109], v[168:171], v[200:203], v[106:109]
	v_mfma_f32_16x16x32_bf16 v[102:105], v[172:175], v[196:199], v[102:105]
	v_mfma_f32_16x16x32_bf16 v[102:105], v[176:179], v[200:203], v[102:105]
	v_mfma_f32_16x16x32_bf16 v[98:101], v[180:183], v[196:199], v[98:101]
	v_mfma_f32_16x16x32_bf16 v[98:101], v[184:187], v[200:203], v[98:101]
	v_mfma_f32_16x16x32_bf16 v[94:97], v[152:155], v[204:207], v[94:97]
	v_mfma_f32_16x16x32_bf16 v[94:97], v[160:163], v[208:211], v[94:97]
	v_mfma_f32_16x16x32_bf16 v[90:93], v[164:167], v[204:207], v[90:93]
	v_mfma_f32_16x16x32_bf16 v[90:93], v[168:171], v[208:211], v[90:93]
	v_mfma_f32_16x16x32_bf16 v[86:89], v[172:175], v[204:207], v[86:89]
	v_mfma_f32_16x16x32_bf16 v[86:89], v[176:179], v[208:211], v[86:89]
	v_mfma_f32_16x16x32_bf16 v[82:85], v[180:183], v[204:207], v[82:85]
	v_mfma_f32_16x16x32_bf16 v[82:85], v[184:187], v[208:211], v[82:85]
	v_mfma_f32_16x16x32_bf16 v[78:81], v[152:155], v[212:215], v[78:81]
	v_mfma_f32_16x16x32_bf16 v[78:81], v[160:163], v[216:219], v[78:81]
	v_mfma_f32_16x16x32_bf16 v[74:77], v[164:167], v[212:215], v[74:77]
	v_mfma_f32_16x16x32_bf16 v[74:77], v[168:171], v[216:219], v[74:77]
	v_mfma_f32_16x16x32_bf16 v[70:73], v[172:175], v[212:215], v[70:73]
	v_mfma_f32_16x16x32_bf16 v[70:73], v[176:179], v[216:219], v[70:73]
	v_mfma_f32_16x16x32_bf16 v[66:69], v[180:183], v[212:215], v[66:69]
	v_mfma_f32_16x16x32_bf16 v[66:69], v[184:187], v[216:219], v[66:69]
	s_barrier
	s_setprio 0
	s_add_u32 s28, s26, 0x8000
	s_addc_u32 s29, s27, 0
	s_add_i32 s62, s62, s35
	s_mov_b32 m0, s62
	ds_read_b128 v[188:191], v157 offset:49152
	ds_read_b128 v[192:195], v157 offset:50176
	ds_read_b128 v[196:199], v157 offset:51200
	ds_read_b128 v[200:203], v157 offset:52224
	ds_read_b128 v[204:207], v157 offset:53248
	ds_read_b128 v[208:211], v157 offset:54272
	ds_read_b128 v[212:215], v157 offset:55296
	ds_read_b128 v[216:219], v157 offset:56320
	global_load_lds_dwordx4 v132, s[28:29]
	s_add_i32 m0, s62, 0x2000
	s_add_u32 s26, s26, 0xc000
	v_lshl_add_u64 v[220:221], s[28:29], 0, v[136:137]
	s_addc_u32 s27, s27, 0
	s_add_i32 s28, s63, s35
	global_load_lds_dwordx4 v[220:221], off
	s_mov_b32 m0, s28
	s_nop 0
	global_load_lds_dwordx4 v132, s[26:27]
	s_add_i32 m0, s28, 0x2000
	s_nop 0
	global_load_lds_dwordx4 v136, s[26:27]
	s_mov_b32 m0, s45
	s_nop 0
	global_load_lds_dwordx4 v130, s[24:25]
	s_mov_b32 m0, s54
	s_nop 0
	global_load_lds_dwordx4 v134, s[24:25]
	s_waitcnt vmcnt(8)
	s_waitcnt lgkmcnt(0)
	s_setprio 1
	s_barrier
	v_mfma_f32_16x16x32_bf16 v[62:65], v[152:155], v[188:191], v[62:65]
	v_mfma_f32_16x16x32_bf16 v[62:65], v[160:163], v[192:195], v[62:65]
	v_mfma_f32_16x16x32_bf16 v[58:61], v[164:167], v[188:191], v[58:61]
	v_mfma_f32_16x16x32_bf16 v[58:61], v[168:171], v[192:195], v[58:61]
	v_mfma_f32_16x16x32_bf16 v[54:57], v[172:175], v[188:191], v[54:57]
	v_mfma_f32_16x16x32_bf16 v[54:57], v[176:179], v[192:195], v[54:57]
	v_mfma_f32_16x16x32_bf16 v[50:53], v[180:183], v[188:191], v[50:53]
	v_mfma_f32_16x16x32_bf16 v[50:53], v[184:187], v[192:195], v[50:53]
	v_mfma_f32_16x16x32_bf16 v[46:49], v[152:155], v[196:199], v[46:49]
	v_mfma_f32_16x16x32_bf16 v[46:49], v[160:163], v[200:203], v[46:49]
	v_mfma_f32_16x16x32_bf16 v[42:45], v[164:167], v[196:199], v[42:45]
	v_mfma_f32_16x16x32_bf16 v[42:45], v[168:171], v[200:203], v[42:45]
	v_mfma_f32_16x16x32_bf16 v[38:41], v[172:175], v[196:199], v[38:41]
	v_mfma_f32_16x16x32_bf16 v[38:41], v[176:179], v[200:203], v[38:41]
	v_mfma_f32_16x16x32_bf16 v[34:37], v[180:183], v[196:199], v[34:37]
	v_mfma_f32_16x16x32_bf16 v[34:37], v[184:187], v[200:203], v[34:37]
	v_mfma_f32_16x16x32_bf16 v[30:33], v[152:155], v[204:207], v[30:33]
	v_mfma_f32_16x16x32_bf16 v[30:33], v[160:163], v[208:211], v[30:33]
	v_mfma_f32_16x16x32_bf16 v[26:29], v[164:167], v[204:207], v[26:29]
	v_mfma_f32_16x16x32_bf16 v[26:29], v[168:171], v[208:211], v[26:29]
	v_mfma_f32_16x16x32_bf16 v[22:25], v[172:175], v[204:207], v[22:25]
	v_mfma_f32_16x16x32_bf16 v[22:25], v[176:179], v[208:211], v[22:25]
	v_mfma_f32_16x16x32_bf16 v[18:21], v[180:183], v[204:207], v[18:21]
	v_mfma_f32_16x16x32_bf16 v[18:21], v[184:187], v[208:211], v[18:21]
	v_mfma_f32_16x16x32_bf16 v[14:17], v[152:155], v[212:215], v[14:17]
	v_mfma_f32_16x16x32_bf16 v[14:17], v[160:163], v[216:219], v[14:17]
	v_mfma_f32_16x16x32_bf16 v[10:13], v[164:167], v[212:215], v[10:13]
	v_mfma_f32_16x16x32_bf16 v[10:13], v[168:171], v[216:219], v[10:13]
	v_mfma_f32_16x16x32_bf16 v[6:9], v[172:175], v[212:215], v[6:9]
	v_mfma_f32_16x16x32_bf16 v[6:9], v[176:179], v[216:219], v[6:9]
	v_mfma_f32_16x16x32_bf16 v[2:5], v[180:183], v[212:215], v[2:5]
	v_mfma_f32_16x16x32_bf16 v[2:5], v[184:187], v[216:219], v[2:5]
	s_barrier
	s_setprio 0
	s_add_i32 s61, s61, 2
	s_add_u32 s22, s22, 0x10000
	s_addc_u32 s23, s23, 0
	s_add_u32 s59, s59, 0x10000
	s_addc_u32 s60, s60, 0
	s_cmp_gt_u32 s61, 61
	s_cbranch_scc0 .LBB0_1172
	s_and_b64 vcc, exec, s[12:13]
	s_cbranch_vccz .LBB0_1175
	s_barrier

; #define PG8_STAGE(bufoff, gbase, voff) do { _Pragma("unroll") for (int _i = 0; _i < 2; ++_i) \
;         __builtin_amdgcn_global_load_lds((const unsigned*)((const char*)(gbase) + (voff)[_i]), (PG8_LAS unsigned*)(lds + (bufoff) + ldsw + _i * 8192), 16, 0, 0); } while (0)
; #define PG8_LDA(dst, b, h) do { _Pragma("unroll") for (int m = 0; m < 4; ++m) _Pragma("unroll") for (int k = 0; k < 2; ++k) dst[m][k] = *(const PG8_LAS bf16x8*)(lds + PG8_SA(b, h) + aoff + m * 2048 + k * 1024); } while (0)
; #define PG8_LDB(dst, b, h) do { _Pragma("unroll") for (int n = 0; n < 2; ++n) _Pragma("unroll") for (int k = 0; k < 2; ++k) dst[n][k] = *(const PG8_LAS bf16x8*)(lds + PG8_SB(b, h) + boff + n * 2048 + k * 1024); } while (0)
; #define PG8_WAIT_V(n) asm volatile("s_waitcnt vmcnt(" #n ")" ::: "memory")
; #define PG8_WAIT_L(n) asm volatile("s_waitcnt lgkmcnt(" #n ")" ::: "memory")
; #define PG8_BAR __builtin_amdgcn_s_barrier()
; #define PG8_SCHED __builtin_amdgcn_sched_barrier(0)
; template <class Epi, class Sched, bool ALIGN_EPI = false, bool SP2 = false, bool A_TILED = false>
; __device__ __forceinline__ void gemm_phase(PG8_LAS unsigned char* lds, const Gemm g, const Sched& S, const Epi& E) {
;     ...
;         const bool has_next = S.next(ui + 1, nxt);
;         const char* nA = has_next ? (const char*)g.A + (size_t)nxt.pm * tstepA : cA; const char* nB = has_next ? (const char*)g.Bt + (size_t)nxt.pn * tstepB : cB;
;         for (int t = 0; t < nt; t += 2) {
;             const bool last = (t == nt - 2);
;             const char* a1 = cA + (size_t)(t + 1) * kstepA;
;             const char* a2 = last ? nA : cA + (size_t)(t + 2) * kstepA; const char* b2 = last ? nB : cB + (size_t)(t + 2) * kstepB;
;             const char* a3 = a2 + kstepA; const char* b3 = b2 + kstepB;
;             if (last && has_next) S.a_ready(nxt);
;             if constexpr (SP2) {
;             PG8_LDB(B0, 0, 0); PG8_LDB(B1, 0, 1); PG8_SCHED; PG8_LDA(At, 0, 0); PG8_STAGE(PG8_SA(1, 1), a1 + hstepA, voffA);
;             PG8_WAIT_V(8); PG8_WAIT_L(0); PG8_BAR; PG8_MMA(0, 0, At, B0); PG8_MMA(0, 1, At, B1); PG8_BAR; PG8_SCHED;
;             PG8_LDA(At, 0, 1); PG8_STAGE(PG8_SB(0, 0), b2, voffB); PG8_STAGE(PG8_SB(0, 1), b2 + hstepB, voffB); PG8_STAGE(PG8_SA(0, 0), a2, voffA);
;             PG8_WAIT_V(8); PG8_WAIT_L(0); PG8_BAR; PG8_MMA(1, 0, At, B0); PG8_MMA(1, 1, At, B1); PG8_BAR; PG8_SCHED;
.LBB0_1246:
	s_add_u32 s22, s22, 0xc000
	s_addc_u32 s23, s23, 0
	s_add_u32 s56, s24, 0x10000
	v_mov_b32_e32 v2, 0
	s_addc_u32 s57, s25, 0
	s_mov_b32 s58, -2
	ds_read_b128 v[142:145], v156
	ds_read_b128 v[146:149], v156 offset:1024
	ds_read_b128 v[150:153], v156 offset:2048
	ds_read_b128 v[160:163], v156 offset:3072
	ds_read_b128 v[164:167], v157
	ds_read_b128 v[168:171], v157 offset:1024
	ds_read_b128 v[172:175], v157 offset:2048
	ds_read_b128 v[176:179], v157 offset:3072
	s_add_u32 s24, s22, 0x4000
	s_addc_u32 s25, s23, 0
	s_cmpk_eq_i32 s58, 0xa8
	s_cselect_b32 s28, s4, s24
	s_cselect_b32 s29, s5, s25
	s_cselect_b32 s26, s20, s56
	s_cselect_b32 s27, s21, s57
	s_add_u32 s24, s28, 0x8000
	s_addc_u32 s25, s29, 0
	s_add_i32 m0, s35, 0xc000
	ds_read_b128 v[180:183], v158
	ds_read_b128 v[184:187], v158 offset:1024
	ds_read_b128 v[188:191], v158 offset:2048
	ds_read_b128 v[192:195], v158 offset:3072
	ds_read_b128 v[196:199], v158 offset:4096
	ds_read_b128 v[200:203], v158 offset:5120
	ds_read_b128 v[204:207], v158 offset:6144
	ds_read_b128 v[208:211], v158 offset:7168
	global_load_lds_dwordx4 v134, s[22:23]
	s_add_i32 m0, s35, 0xe000
	s_nop 0
	global_load_lds_dwordx4 v136, s[22:23]
	s_waitcnt vmcnt(8)
	s_waitcnt lgkmcnt(0)
	s_barrier
	s_setprio 1
	s_waitcnt lgkmcnt(0)
	v_mfma_f32_16x16x32_bf16 v[126:129], v[142:145], v[180:183], 0
	v_mfma_f32_16x16x32_bf16 v[122:125], v[150:153], v[180:183], 0
	v_mfma_f32_16x16x32_bf16 v[118:121], v[142:145], v[188:191], 0
	v_mfma_f32_16x16x32_bf16 v[114:117], v[150:153], v[188:191], 0
	v_mfma_f32_16x16x32_bf16 v[94:97], v[142:145], v[196:199], 0
	v_mfma_f32_16x16x32_bf16 v[90:93], v[150:153], v[196:199], 0
	v_mfma_f32_16x16x32_bf16 v[86:89], v[142:145], v[204:207], 0
	v_mfma_f32_16x16x32_bf16 v[82:85], v[150:153], v[204:207], 0
	v_mfma_f32_16x16x32_bf16 v[126:129], v[146:149], v[184:187], v[126:129]
	v_mfma_f32_16x16x32_bf16 v[122:125], v[160:163], v[184:187], v[122:125]
	v_mfma_f32_16x16x32_bf16 v[118:121], v[146:149], v[192:195], v[118:121]
	v_mfma_f32_16x16x32_bf16 v[114:117], v[160:163], v[192:195], v[114:117]
	v_mfma_f32_16x16x32_bf16 v[94:97], v[146:149], v[200:203], v[94:97]
	v_mfma_f32_16x16x32_bf16 v[90:93], v[160:163], v[200:203], v[90:93]
	v_mfma_f32_16x16x32_bf16 v[86:89], v[146:149], v[208:211], v[86:89]
	v_mfma_f32_16x16x32_bf16 v[82:85], v[160:163], v[208:211], v[82:85]
	s_setprio 0
	s_setprio 1
	v_mfma_f32_16x16x32_bf16 v[110:113], v[164:167], v[180:183], 0
	v_mfma_f32_16x16x32_bf16 v[106:109], v[172:175], v[180:183], 0
	v_mfma_f32_16x16x32_bf16 v[102:105], v[164:167], v[188:191], 0
	v_mfma_f32_16x16x32_bf16 v[98:101], v[172:175], v[188:191], 0
	v_mfma_f32_16x16x32_bf16 v[78:81], v[164:167], v[196:199], 0
	v_mfma_f32_16x16x32_bf16 v[74:77], v[172:175], v[196:199], 0
	v_mfma_f32_16x16x32_bf16 v[70:73], v[164:167], v[204:207], 0
	v_mfma_f32_16x16x32_bf16 v[66:69], v[172:175], v[204:207], 0
	v_mfma_f32_16x16x32_bf16 v[110:113], v[168:171], v[184:187], v[110:113]
	v_mfma_f32_16x16x32_bf16 v[106:109], v[176:179], v[184:187], v[106:109]
	v_mfma_f32_16x16x32_bf16 v[102:105], v[168:171], v[192:195], v[102:105]
	v_mfma_f32_16x16x32_bf16 v[98:101], v[176:179], v[192:195], v[98:101]
	v_mfma_f32_16x16x32_bf16 v[78:81], v[168:171], v[200:203], v[78:81]
	v_mfma_f32_16x16x32_bf16 v[74:77], v[176:179], v[200:203], v[74:77]
	v_mfma_f32_16x16x32_bf16 v[70:73], v[168:171], v[208:211], v[70:73]
	v_mfma_f32_16x16x32_bf16 v[66:69], v[176:179], v[208:211], v[66:69]
	s_setprio 0
	s_barrier
	s_add_i32 s59, s42, s31
	s_mov_b32 m0, s59
	ds_read_b128 v[180:183], v158 offset:16384
	ds_read_b128 v[184:187], v158 offset:17408
	ds_read_b128 v[188:191], v158 offset:18432
	ds_read_b128 v[192:195], v158 offset:19456
	ds_read_b128 v[196:199], v158 offset:20480
	ds_read_b128 v[200:203], v158 offset:21504
	ds_read_b128 v[204:207], v158 offset:22528
	ds_read_b128 v[208:211], v158 offset:23552
	global_load_lds_dwordx4 v130, s[26:27]
	s_add_i32 m0, s59, 0x2000
	s_add_u32 s60, s26, 0x4000
	s_addc_u32 s61, s27, 0
	s_add_i32 s59, s43, s31
	global_load_lds_dwordx4 v132, s[26:27]
	s_mov_b32 m0, s59
	s_nop 0
	global_load_lds_dwordx4 v130, s[60:61]
	s_add_i32 m0, s59, 0x2000
	s_nop 0
	global_load_lds_dwordx4 v132, s[60:61]
	s_mov_b32 m0, s35
	s_nop 0
	global_load_lds_dwordx4 v130, s[28:29]
	s_mov_b32 m0, s36
	s_nop 0
	global_load_lds_dwordx4 v132, s[28:29]
	s_waitcnt vmcnt(8)
	s_waitcnt lgkmcnt(0)
	s_setprio 1
	s_barrier
	v_mfma_f32_16x16x32_bf16 v[62:65], v[142:145], v[180:183], 0
	v_mfma_f32_16x16x32_bf16 v[62:65], v[146:149], v[184:187], v[62:65]
	v_mfma_f32_16x16x32_bf16 v[58:61], v[150:153], v[180:183], 0
	v_mfma_f32_16x16x32_bf16 v[58:61], v[160:163], v[184:187], v[58:61]
	v_mfma_f32_16x16x32_bf16 v[50:53], v[164:167], v[180:183], 0
	v_mfma_f32_16x16x32_bf16 v[50:53], v[168:171], v[184:187], v[50:53]
	v_mfma_f32_16x16x32_bf16 v[42:45], v[172:175], v[180:183], 0
	v_mfma_f32_16x16x32_bf16 v[42:45], v[176:179], v[184:187], v[42:45]
	v_mfma_f32_16x16x32_bf16 v[54:57], v[142:145], v[188:191], 0
	v_mfma_f32_16x16x32_bf16 v[54:57], v[146:149], v[192:195], v[54:57]
	v_mfma_f32_16x16x32_bf16 v[46:49], v[150:153], v[188:191], 0
	v_mfma_f32_16x16x32_bf16 v[46:49], v[160:163], v[192:195], v[46:49]
	v_mfma_f32_16x16x32_bf16 v[34:37], v[164:167], v[188:191], 0
	v_mfma_f32_16x16x32_bf16 v[34:37], v[168:171], v[192:195], v[34:37]
	v_mfma_f32_16x16x32_bf16 v[26:29], v[172:175], v[188:191], 0
	v_mfma_f32_16x16x32_bf16 v[26:29], v[176:179], v[192:195], v[26:29]
	v_mfma_f32_16x16x32_bf16 v[38:41], v[142:145], v[196:199], 0
	v_mfma_f32_16x16x32_bf16 v[38:41], v[146:149], v[200:203], v[38:41]
	v_mfma_f32_16x16x32_bf16 v[30:33], v[150:153], v[196:199], 0
	v_mfma_f32_16x16x32_bf16 v[30:33], v[160:163], v[200:203], v[30:33]
	v_mfma_f32_16x16x32_bf16 v[18:21], v[164:167], v[196:199], 0
	v_mfma_f32_16x16x32_bf16 v[18:21], v[168:171], v[200:203], v[18:21]
	v_mfma_f32_16x16x32_bf16 v[10:13], v[172:175], v[196:199], 0
	v_mfma_f32_16x16x32_bf16 v[10:13], v[176:179], v[200:203], v[10:13]
	v_mfma_f32_16x16x32_bf16 v[22:25], v[142:145], v[204:207], 0
	v_mfma_f32_16x16x32_bf16 v[22:25], v[146:149], v[208:211], v[22:25]
	v_mfma_f32_16x16x32_bf16 v[14:17], v[150:153], v[204:207], 0
	v_mfma_f32_16x16x32_bf16 v[14:17], v[160:163], v[208:211], v[14:17]
	v_mfma_f32_16x16x32_bf16 v[6:9], v[164:167], v[204:207], 0
	v_mfma_f32_16x16x32_bf16 v[6:9], v[168:171], v[208:211], v[6:9]
	v_mfma_f32_16x16x32_bf16 v[2:5], v[172:175], v[204:207], 0
	v_mfma_f32_16x16x32_bf16 v[2:5], v[176:179], v[208:211], v[2:5]
	s_barrier
; #define PG8_STAGE(bufoff, gbase, voff) do { _Pragma("unroll") for (int _i = 0; _i < 2; ++_i) \
;         __builtin_amdgcn_global_load_lds((const unsigned*)((const char*)(gbase) + (voff)[_i]), (PG8_LAS unsigned*)(lds + (bufoff) + ldsw + _i * 8192), 16, 0, 0); } while (0)
; #define PG8_LDA(dst, b, h) do { _Pragma("unroll") for (int m = 0; m < 4; ++m) _Pragma("unroll") for (int k = 0; k < 2; ++k) dst[m][k] = *(const PG8_LAS bf16x8*)(lds + PG8_SA(b, h) + aoff + m * 2048 + k * 1024); } while (0)
; #define PG8_LDB(dst, b, h) do { _Pragma("unroll") for (int n = 0; n < 2; ++n) _Pragma("unroll") for (int k = 0; k < 2; ++k) dst[n][k] = *(const PG8_LAS bf16x8*)(lds + PG8_SB(b, h) + boff + n * 2048 + k * 1024); } while (0)
; #define PG8_MMA(ai, bj, At, Bt) do { __builtin_amdgcn_s_setprio(1); _Pragma("unroll") for (int m = 0; m < 4; ++m) _Pragma("unroll") for (int n = 0; n < 2; ++n) _Pragma("unroll") for (int k = 0; k < 2; ++k) \
;         acc[ai][bj][m][n] = __builtin_amdgcn_mfma_f32_16x16x32_bf16(Bt[n][k], At[m][k], acc[ai][bj][m][n], 0, 0, 0); __builtin_amdgcn_s_setprio(0); } while (0)
; #define PG8_WAIT_V(n) asm volatile("s_waitcnt vmcnt(" #n ")" ::: "memory")
; #define PG8_WAIT_L(n) asm volatile("s_waitcnt lgkmcnt(" #n ")" ::: "memory")
; #define PG8_BAR __builtin_amdgcn_s_barrier()
; #define PG8_SCHED __builtin_amdgcn_sched_barrier(0)
; template <class Epi, class Sched, bool ALIGN_EPI = false, bool SP2 = false, bool A_TILED = false>
; __device__ __forceinline__ void gemm_phase(PG8_LAS unsigned char* lds, const Gemm g, const Sched& S, const Epi& E) {
;     ...
;             PG8_LDB(B0, 1, 0); PG8_LDB(B1, 1, 1); PG8_SCHED; PG8_LDA(At, 1, 0); PG8_STAGE(PG8_SA(0, 1), a2 + hstepA, voffA);
;             PG8_WAIT_V(8); PG8_WAIT_L(0); PG8_BAR; PG8_MMA(0, 0, At, B0); PG8_MMA(0, 1, At, B1); PG8_BAR; PG8_SCHED;
;             PG8_LDA(At, 1, 1); PG8_STAGE(PG8_SB(1, 0), b3, voffB); PG8_STAGE(PG8_SB(1, 1), b3 + hstepB, voffB); PG8_STAGE(PG8_SA(1, 0), a3, voffA);
;             PG8_WAIT_V(8); PG8_WAIT_L(0); PG8_BAR; PG8_MMA(1, 0, At, B0); PG8_MMA(1, 1, At, B1); PG8_BAR; PG8_SCHED;
	s_setprio 0
	s_add_i32 s59, 0, 0x18000
	s_add_i32 s60, 0, 0x1c000
	ds_read_b128 v[142:145], v156 offset:32768
	ds_read_b128 v[146:149], v156 offset:33792
	ds_read_b128 v[150:153], v156 offset:34816
	ds_read_b128 v[160:163], v156 offset:35840
	ds_read_b128 v[164:167], v156 offset:49152
	ds_read_b128 v[168:171], v156 offset:50176
	ds_read_b128 v[172:175], v156 offset:51200
	ds_read_b128 v[176:179], v156 offset:52224
	s_add_u32 s28, s28, 0x4000
	s_addc_u32 s29, s29, 0
	s_mov_b32 m0, s37
	ds_read_b128 v[180:183], v158 offset:32768
	ds_read_b128 v[184:187], v158 offset:33792
	ds_read_b128 v[188:191], v158 offset:34816
	ds_read_b128 v[192:195], v158 offset:35840
	ds_read_b128 v[196:199], v158 offset:36864
	ds_read_b128 v[200:203], v158 offset:37888
	ds_read_b128 v[204:207], v158 offset:38912
	ds_read_b128 v[208:211], v158 offset:39936
	global_load_lds_dwordx4 v130, s[28:29]
	s_mov_b32 m0, s38
	s_nop 0
	global_load_lds_dwordx4 v132, s[28:29]
	s_waitcnt vmcnt(8)
	s_waitcnt lgkmcnt(0)
	s_setprio 1
	s_barrier
	v_mfma_f32_16x16x32_bf16 v[126:129], v[142:145], v[180:183], v[126:129]
	v_mfma_f32_16x16x32_bf16 v[126:129], v[146:149], v[184:187], v[126:129]
	v_mfma_f32_16x16x32_bf16 v[122:125], v[150:153], v[180:183], v[122:125]
	v_mfma_f32_16x16x32_bf16 v[122:125], v[160:163], v[184:187], v[122:125]
	v_mfma_f32_16x16x32_bf16 v[110:113], v[164:167], v[180:183], v[110:113]
	v_mfma_f32_16x16x32_bf16 v[110:113], v[168:171], v[184:187], v[110:113]
	v_mfma_f32_16x16x32_bf16 v[106:109], v[172:175], v[180:183], v[106:109]
	v_mfma_f32_16x16x32_bf16 v[106:109], v[176:179], v[184:187], v[106:109]
	v_mfma_f32_16x16x32_bf16 v[118:121], v[142:145], v[188:191], v[118:121]
	v_mfma_f32_16x16x32_bf16 v[118:121], v[146:149], v[192:195], v[118:121]
	v_mfma_f32_16x16x32_bf16 v[114:117], v[150:153], v[188:191], v[114:117]
	v_mfma_f32_16x16x32_bf16 v[114:117], v[160:163], v[192:195], v[114:117]
	v_mfma_f32_16x16x32_bf16 v[102:105], v[164:167], v[188:191], v[102:105]
	v_mfma_f32_16x16x32_bf16 v[102:105], v[168:171], v[192:195], v[102:105]
	v_mfma_f32_16x16x32_bf16 v[98:101], v[172:175], v[188:191], v[98:101]
	v_mfma_f32_16x16x32_bf16 v[98:101], v[176:179], v[192:195], v[98:101]
	v_mfma_f32_16x16x32_bf16 v[94:97], v[142:145], v[196:199], v[94:97]
	v_mfma_f32_16x16x32_bf16 v[94:97], v[146:149], v[200:203], v[94:97]
	v_mfma_f32_16x16x32_bf16 v[90:93], v[150:153], v[196:199], v[90:93]
	v_mfma_f32_16x16x32_bf16 v[90:93], v[160:163], v[200:203], v[90:93]
	v_mfma_f32_16x16x32_bf16 v[78:81], v[164:167], v[196:199], v[78:81]
	v_mfma_f32_16x16x32_bf16 v[78:81], v[168:171], v[200:203], v[78:81]
	v_mfma_f32_16x16x32_bf16 v[74:77], v[172:175], v[196:199], v[74:77]
	v_mfma_f32_16x16x32_bf16 v[74:77], v[176:179], v[200:203], v[74:77]
	v_mfma_f32_16x16x32_bf16 v[86:89], v[142:145], v[204:207], v[86:89]
	v_mfma_f32_16x16x32_bf16 v[86:89], v[146:149], v[208:211], v[86:89]
	v_mfma_f32_16x16x32_bf16 v[82:85], v[150:153], v[204:207], v[82:85]
	v_mfma_f32_16x16x32_bf16 v[82:85], v[160:163], v[208:211], v[82:85]
	v_mfma_f32_16x16x32_bf16 v[70:73], v[164:167], v[204:207], v[70:73]
	v_mfma_f32_16x16x32_bf16 v[70:73], v[168:171], v[208:211], v[70:73]
	v_mfma_f32_16x16x32_bf16 v[66:69], v[172:175], v[204:207], v[66:69]
	v_mfma_f32_16x16x32_bf16 v[66:69], v[176:179], v[208:211], v[66:69]
	s_barrier
	s_setprio 0
	s_add_u32 s28, s26, 0x8000
	s_addc_u32 s29, s27, 0
	s_add_i32 s59, s59, s31
	s_mov_b32 m0, s59
	ds_read_b128 v[180:183], v158 offset:49152
	ds_read_b128 v[184:187], v158 offset:50176
	ds_read_b128 v[188:191], v158 offset:51200
	ds_read_b128 v[192:195], v158 offset:52224
	ds_read_b128 v[196:199], v158 offset:53248
	ds_read_b128 v[200:203], v158 offset:54272
	ds_read_b128 v[204:207], v158 offset:55296
	ds_read_b128 v[208:211], v158 offset:56320
	global_load_lds_dwordx4 v130, s[28:29]
	s_add_i32 m0, s59, 0x2000
	s_add_u32 s26, s26, 0xc000
	v_lshl_add_u64 v[212:213], s[28:29], 0, v[132:133]
	s_addc_u32 s27, s27, 0
	s_add_i32 s28, s60, s31
	global_load_lds_dwordx4 v[212:213], off
	s_mov_b32 m0, s28
	s_nop 0
	global_load_lds_dwordx4 v130, s[26:27]
	s_add_i32 m0, s28, 0x2000
	s_nop 0
	global_load_lds_dwordx4 v132, s[26:27]
	s_mov_b32 m0, s40
	s_nop 0
	global_load_lds_dwordx4 v130, s[24:25]
	s_mov_b32 m0, s41
	s_nop 0
	global_load_lds_dwordx4 v132, s[24:25]
	s_waitcnt vmcnt(8)
	s_waitcnt lgkmcnt(0)
	s_setprio 1
	s_barrier
	v_mfma_f32_16x16x32_bf16 v[62:65], v[142:145], v[180:183], v[62:65]
	v_mfma_f32_16x16x32_bf16 v[62:65], v[146:149], v[184:187], v[62:65]
	v_mfma_f32_16x16x32_bf16 v[58:61], v[150:153], v[180:183], v[58:61]
	v_mfma_f32_16x16x32_bf16 v[58:61], v[160:163], v[184:187], v[58:61]
	v_mfma_f32_16x16x32_bf16 v[50:53], v[164:167], v[180:183], v[50:53]
	v_mfma_f32_16x16x32_bf16 v[50:53], v[168:171], v[184:187], v[50:53]
	v_mfma_f32_16x16x32_bf16 v[42:45], v[172:175], v[180:183], v[42:45]
	v_mfma_f32_16x16x32_bf16 v[42:45], v[176:179], v[184:187], v[42:45]
	v_mfma_f32_16x16x32_bf16 v[54:57], v[142:145], v[188:191], v[54:57]
	v_mfma_f32_16x16x32_bf16 v[54:57], v[146:149], v[192:195], v[54:57]
	v_mfma_f32_16x16x32_bf16 v[46:49], v[150:153], v[188:191], v[46:49]
	v_mfma_f32_16x16x32_bf16 v[46:49], v[160:163], v[192:195], v[46:49]
	v_mfma_f32_16x16x32_bf16 v[34:37], v[164:167], v[188:191], v[34:37]
	v_mfma_f32_16x16x32_bf16 v[34:37], v[168:171], v[192:195], v[34:37]
	v_mfma_f32_16x16x32_bf16 v[26:29], v[172:175], v[188:191], v[26:29]
	v_mfma_f32_16x16x32_bf16 v[26:29], v[176:179], v[192:195], v[26:29]
	v_mfma_f32_16x16x32_bf16 v[38:41], v[142:145], v[196:199], v[38:41]
	v_mfma_f32_16x16x32_bf16 v[38:41], v[146:149], v[200:203], v[38:41]
	v_mfma_f32_16x16x32_bf16 v[30:33], v[150:153], v[196:199], v[30:33]
	v_mfma_f32_16x16x32_bf16 v[30:33], v[160:163], v[200:203], v[30:33]
	v_mfma_f32_16x16x32_bf16 v[18:21], v[164:167], v[196:199], v[18:21]
	v_mfma_f32_16x16x32_bf16 v[18:21], v[168:171], v[200:203], v[18:21]
	v_mfma_f32_16x16x32_bf16 v[10:13], v[172:175], v[196:199], v[10:13]
	v_mfma_f32_16x16x32_bf16 v[10:13], v[176:179], v[200:203], v[10:13]
	v_mfma_f32_16x16x32_bf16 v[22:25], v[142:145], v[204:207], v[22:25]
	v_mfma_f32_16x16x32_bf16 v[22:25], v[146:149], v[208:211], v[22:25]
	v_mfma_f32_16x16x32_bf16 v[14:17], v[150:153], v[204:207], v[14:17]
	v_mfma_f32_16x16x32_bf16 v[14:17], v[160:163], v[208:211], v[14:17]
	v_mfma_f32_16x16x32_bf16 v[6:9], v[164:167], v[204:207], v[6:9]
	v_mfma_f32_16x16x32_bf16 v[6:9], v[168:171], v[208:211], v[6:9]
	v_mfma_f32_16x16x32_bf16 v[2:5], v[172:175], v[204:207], v[2:5]
	v_mfma_f32_16x16x32_bf16 v[2:5], v[176:179], v[208:211], v[2:5]
	s_barrier
	s_setprio 0
	s_add_i32 s58, s58, 2
	s_add_u32 s22, s22, 0x10000
	s_addc_u32 s23, s23, 0
	s_add_u32 s56, s56, 0x10000
	s_addc_u32 s57, s57, 0
; #define PG8_STAGE(bufoff, gbase, voff) do { _Pragma("unroll") for (int _i = 0; _i < 2; ++_i) \
;         __builtin_amdgcn_global_load_lds((const unsigned*)((const char*)(gbase) + (voff)[_i]), (PG8_LAS unsigned*)(lds + (bufoff) + ldsw + _i * 8192), 16, 0, 0); } while (0)
; #define PG8_LDA(dst, b, h) do { _Pragma("unroll") for (int m = 0; m < 4; ++m) _Pragma("unroll") for (int k = 0; k < 2; ++k) dst[m][k] = *(const PG8_LAS bf16x8*)(lds + PG8_SA(b, h) + aoff + m * 2048 + k * 1024); } while (0)
; #define PG8_LDB(dst, b, h) do { _Pragma("unroll") for (int n = 0; n < 2; ++n) _Pragma("unroll") for (int k = 0; k < 2; ++k) dst[n][k] = *(const PG8_LAS bf16x8*)(lds + PG8_SB(b, h) + boff + n * 2048 + k * 1024); } while (0)
; #define PG8_MMA(ai, bj, At, Bt) do { __builtin_amdgcn_s_setprio(1); _Pragma("unroll") for (int m = 0; m < 4; ++m) _Pragma("unroll") for (int n = 0; n < 2; ++n) _Pragma("unroll") for (int k = 0; k < 2; ++k) \
;         acc[ai][bj][m][n] = __builtin_amdgcn_mfma_f32_16x16x32_bf16(Bt[n][k], At[m][k], acc[ai][bj][m][n], 0, 0, 0); __builtin_amdgcn_s_setprio(0); } while (0)
; #define PG8_WAIT_V(n) asm volatile("s_waitcnt vmcnt(" #n ")" ::: "memory")
; #define PG8_WAIT_L(n) asm volatile("s_waitcnt lgkmcnt(" #n ")" ::: "memory")
; #define PG8_BAR __builtin_amdgcn_s_barrier()
; #define PG8_SCHED __builtin_amdgcn_sched_barrier(0)
; template <class Epi, class Sched, bool ALIGN_EPI = false, bool SP2 = false, bool A_TILED = false>
; __device__ __forceinline__ void gemm_phase(PG8_LAS unsigned char* lds, const Gemm g, const Sched& S, const Epi& E) {
;     ...
;             PG8_LDB(B0, 0, 0); PG8_LDB(B1, 0, 1); PG8_SCHED; PG8_LDA(At, 0, 0); PG8_STAGE(PG8_SA(1, 1), a1 + hstepA, voffA);
;             PG8_WAIT_V(8); PG8_WAIT_L(0); PG8_BAR; PG8_MMA(0, 0, At, B0); PG8_MMA(0, 1, At, B1); PG8_BAR; PG8_SCHED;
;             PG8_LDA(At, 0, 1); PG8_STAGE(PG8_SB(0, 0), b2, voffB); PG8_STAGE(PG8_SB(0, 1), b2 + hstepB, voffB); PG8_STAGE(PG8_SA(0, 0), a2, voffA);
;             PG8_WAIT_V(8); PG8_WAIT_L(0); PG8_BAR; PG8_MMA(1, 0, At, B0); PG8_MMA(1, 1, At, B1); PG8_BAR; PG8_SCHED;
.LBB0_1247:
	ds_read_b128 v[142:145], v156
	ds_read_b128 v[146:149], v156 offset:1024
	ds_read_b128 v[150:153], v156 offset:2048
	ds_read_b128 v[160:163], v156 offset:3072
	ds_read_b128 v[164:167], v157
	ds_read_b128 v[168:171], v157 offset:1024
	ds_read_b128 v[172:175], v157 offset:2048
	ds_read_b128 v[176:179], v157 offset:3072
	s_add_u32 s24, s22, 0x4000
	s_addc_u32 s25, s23, 0
	s_cmpk_eq_i32 s58, 0xa8
	s_cselect_b32 s28, s4, s24
	s_cselect_b32 s29, s5, s25
	s_cselect_b32 s26, s20, s56
	s_cselect_b32 s27, s21, s57
	s_add_u32 s24, s28, 0x8000
	s_addc_u32 s25, s29, 0
	s_add_i32 m0, s35, 0xc000
	ds_read_b128 v[180:183], v158
	ds_read_b128 v[184:187], v158 offset:1024
	ds_read_b128 v[188:191], v158 offset:2048
	ds_read_b128 v[192:195], v158 offset:3072
	ds_read_b128 v[196:199], v158 offset:4096
	ds_read_b128 v[200:203], v158 offset:5120
	ds_read_b128 v[204:207], v158 offset:6144
	ds_read_b128 v[208:211], v158 offset:7168
	global_load_lds_dwordx4 v134, s[22:23]
	s_add_i32 m0, s35, 0xe000
	s_nop 0
	global_load_lds_dwordx4 v136, s[22:23]
	s_waitcnt vmcnt(8)
	s_waitcnt lgkmcnt(0)
	s_barrier
	s_setprio 1
	s_waitcnt lgkmcnt(0)
	v_mfma_f32_16x16x32_bf16 v[126:129], v[142:145], v[180:183], v[126:129]
	v_mfma_f32_16x16x32_bf16 v[122:125], v[150:153], v[180:183], v[122:125]
	v_mfma_f32_16x16x32_bf16 v[118:121], v[142:145], v[188:191], v[118:121]
	v_mfma_f32_16x16x32_bf16 v[114:117], v[150:153], v[188:191], v[114:117]
	v_mfma_f32_16x16x32_bf16 v[94:97], v[142:145], v[196:199], v[94:97]
	v_mfma_f32_16x16x32_bf16 v[90:93], v[150:153], v[196:199], v[90:93]
	v_mfma_f32_16x16x32_bf16 v[86:89], v[142:145], v[204:207], v[86:89]
	v_mfma_f32_16x16x32_bf16 v[82:85], v[150:153], v[204:207], v[82:85]
	v_mfma_f32_16x16x32_bf16 v[126:129], v[146:149], v[184:187], v[126:129]
	v_mfma_f32_16x16x32_bf16 v[122:125], v[160:163], v[184:187], v[122:125]
	v_mfma_f32_16x16x32_bf16 v[118:121], v[146:149], v[192:195], v[118:121]
	v_mfma_f32_16x16x32_bf16 v[114:117], v[160:163], v[192:195], v[114:117]
	v_mfma_f32_16x16x32_bf16 v[94:97], v[146:149], v[200:203], v[94:97]
	v_mfma_f32_16x16x32_bf16 v[90:93], v[160:163], v[200:203], v[90:93]
	v_mfma_f32_16x16x32_bf16 v[86:89], v[146:149], v[208:211], v[86:89]
	v_mfma_f32_16x16x32_bf16 v[82:85], v[160:163], v[208:211], v[82:85]
	s_setprio 0
	s_setprio 1
	v_mfma_f32_16x16x32_bf16 v[110:113], v[164:167], v[180:183], v[110:113]
	v_mfma_f32_16x16x32_bf16 v[106:109], v[172:175], v[180:183], v[106:109]
	v_mfma_f32_16x16x32_bf16 v[102:105], v[164:167], v[188:191], v[102:105]
	v_mfma_f32_16x16x32_bf16 v[98:101], v[172:175], v[188:191], v[98:101]
	v_mfma_f32_16x16x32_bf16 v[78:81], v[164:167], v[196:199], v[78:81]
	v_mfma_f32_16x16x32_bf16 v[74:77], v[172:175], v[196:199], v[74:77]
	v_mfma_f32_16x16x32_bf16 v[70:73], v[164:167], v[204:207], v[70:73]
	v_mfma_f32_16x16x32_bf16 v[66:69], v[172:175], v[204:207], v[66:69]
	v_mfma_f32_16x16x32_bf16 v[110:113], v[168:171], v[184:187], v[110:113]
	v_mfma_f32_16x16x32_bf16 v[106:109], v[176:179], v[184:187], v[106:109]
	v_mfma_f32_16x16x32_bf16 v[102:105], v[168:171], v[192:195], v[102:105]
	v_mfma_f32_16x16x32_bf16 v[98:101], v[176:179], v[192:195], v[98:101]
	v_mfma_f32_16x16x32_bf16 v[78:81], v[168:171], v[200:203], v[78:81]
	v_mfma_f32_16x16x32_bf16 v[74:77], v[176:179], v[200:203], v[74:77]
	v_mfma_f32_16x16x32_bf16 v[70:73], v[168:171], v[208:211], v[70:73]
	v_mfma_f32_16x16x32_bf16 v[66:69], v[176:179], v[208:211], v[66:69]
	s_setprio 0
	s_barrier
	s_add_i32 s59, s42, s31
	s_mov_b32 m0, s59
	ds_read_b128 v[180:183], v158 offset:16384
	ds_read_b128 v[184:187], v158 offset:17408
	ds_read_b128 v[188:191], v158 offset:18432
	ds_read_b128 v[192:195], v158 offset:19456
	ds_read_b128 v[196:199], v158 offset:20480
	ds_read_b128 v[200:203], v158 offset:21504
	ds_read_b128 v[204:207], v158 offset:22528
	ds_read_b128 v[208:211], v158 offset:23552
	global_load_lds_dwordx4 v130, s[26:27]
	s_add_i32 m0, s59, 0x2000
	s_add_u32 s60, s26, 0x4000
	s_addc_u32 s61, s27, 0
	s_add_i32 s59, s43, s31
	global_load_lds_dwordx4 v132, s[26:27]
	s_mov_b32 m0, s59
	s_nop 0
	global_load_lds_dwordx4 v130, s[60:61]
	s_add_i32 m0, s59, 0x2000
	s_nop 0
	global_load_lds_dwordx4 v132, s[60:61]
	s_mov_b32 m0, s35
	s_nop 0
	global_load_lds_dwordx4 v130, s[28:29]
	s_mov_b32 m0, s36
	s_nop 0
	global_load_lds_dwordx4 v132, s[28:29]
	s_waitcnt vmcnt(8)
	s_waitcnt lgkmcnt(0)
	s_setprio 1
	s_barrier
	v_mfma_f32_16x16x32_bf16 v[62:65], v[142:145], v[180:183], v[62:65]
	v_mfma_f32_16x16x32_bf16 v[62:65], v[146:149], v[184:187], v[62:65]
	v_mfma_f32_16x16x32_bf16 v[58:61], v[150:153], v[180:183], v[58:61]
	v_mfma_f32_16x16x32_bf16 v[58:61], v[160:163], v[184:187], v[58:61]
	v_mfma_f32_16x16x32_bf16 v[50:53], v[164:167], v[180:183], v[50:53]
	v_mfma_f32_16x16x32_bf16 v[50:53], v[168:171], v[184:187], v[50:53]
	v_mfma_f32_16x16x32_bf16 v[42:45], v[172:175], v[180:183], v[42:45]
	v_mfma_f32_16x16x32_bf16 v[42:45], v[176:179], v[184:187], v[42:45]
	v_mfma_f32_16x16x32_bf16 v[54:57], v[142:145], v[188:191], v[54:57]
	v_mfma_f32_16x16x32_bf16 v[54:57], v[146:149], v[192:195], v[54:57]
	v_mfma_f32_16x16x32_bf16 v[46:49], v[150:153], v[188:191], v[46:49]
	v_mfma_f32_16x16x32_bf16 v[46:49], v[160:163], v[192:195], v[46:49]
	v_mfma_f32_16x16x32_bf16 v[34:37], v[164:167], v[188:191], v[34:37]
	v_mfma_f32_16x16x32_bf16 v[34:37], v[168:171], v[192:195], v[34:37]
	v_mfma_f32_16x16x32_bf16 v[26:29], v[172:175], v[188:191], v[26:29]
	v_mfma_f32_16x16x32_bf16 v[26:29], v[176:179], v[192:195], v[26:29]
	v_mfma_f32_16x16x32_bf16 v[38:41], v[142:145], v[196:199], v[38:41]
	v_mfma_f32_16x16x32_bf16 v[38:41], v[146:149], v[200:203], v[38:41]
	v_mfma_f32_16x16x32_bf16 v[30:33], v[150:153], v[196:199], v[30:33]
	v_mfma_f32_16x16x32_bf16 v[30:33], v[160:163], v[200:203], v[30:33]
	v_mfma_f32_16x16x32_bf16 v[18:21], v[164:167], v[196:199], v[18:21]
	v_mfma_f32_16x16x32_bf16 v[18:21], v[168:171], v[200:203], v[18:21]
	v_mfma_f32_16x16x32_bf16 v[10:13], v[172:175], v[196:199], v[10:13]
	v_mfma_f32_16x16x32_bf16 v[10:13], v[176:179], v[200:203], v[10:13]
	v_mfma_f32_16x16x32_bf16 v[22:25], v[142:145], v[204:207], v[22:25]
	v_mfma_f32_16x16x32_bf16 v[22:25], v[146:149], v[208:211], v[22:25]
	v_mfma_f32_16x16x32_bf16 v[14:17], v[150:153], v[204:207], v[14:17]
	v_mfma_f32_16x16x32_bf16 v[14:17], v[160:163], v[208:211], v[14:17]
	v_mfma_f32_16x16x32_bf16 v[6:9], v[164:167], v[204:207], v[6:9]
	v_mfma_f32_16x16x32_bf16 v[6:9], v[168:171], v[208:211], v[6:9]
	v_mfma_f32_16x16x32_bf16 v[2:5], v[172:175], v[204:207], v[2:5]
	v_mfma_f32_16x16x32_bf16 v[2:5], v[176:179], v[208:211], v[2:5]
	s_barrier
; #define PG8_STAGE(bufoff, gbase, voff) do { _Pragma("unroll") for (int _i = 0; _i < 2; ++_i) \
;         __builtin_amdgcn_global_load_lds((const unsigned*)((const char*)(gbase) + (voff)[_i]), (PG8_LAS unsigned*)(lds + (bufoff) + ldsw + _i * 8192), 16, 0, 0); } while (0)
; #define PG8_LDA(dst, b, h) do { _Pragma("unroll") for (int m = 0; m < 4; ++m) _Pragma("unroll") for (int k = 0; k < 2; ++k) dst[m][k] = *(const PG8_LAS bf16x8*)(lds + PG8_SA(b, h) + aoff + m * 2048 + k * 1024); } while (0)
; #define PG8_LDB(dst, b, h) do { _Pragma("unroll") for (int n = 0; n < 2; ++n) _Pragma("unroll") for (int k = 0; k < 2; ++k) dst[n][k] = *(const PG8_LAS bf16x8*)(lds + PG8_SB(b, h) + boff + n * 2048 + k * 1024); } while (0)
; #define PG8_MMA(ai, bj, At, Bt) do { __builtin_amdgcn_s_setprio(1); _Pragma("unroll") for (int m = 0; m < 4; ++m) _Pragma("unroll") for (int n = 0; n < 2; ++n) _Pragma("unroll") for (int k = 0; k < 2; ++k) \
;         acc[ai][bj][m][n] = __builtin_amdgcn_mfma_f32_16x16x32_bf16(Bt[n][k], At[m][k], acc[ai][bj][m][n], 0, 0, 0); __builtin_amdgcn_s_setprio(0); } while (0)
; #define PG8_WAIT_V(n) asm volatile("s_waitcnt vmcnt(" #n ")" ::: "memory")
; #define PG8_WAIT_L(n) asm volatile("s_waitcnt lgkmcnt(" #n ")" ::: "memory")
; #define PG8_BAR __builtin_amdgcn_s_barrier()
; #define PG8_SCHED __builtin_amdgcn_sched_barrier(0)
; template <class Epi, class Sched, bool ALIGN_EPI = false, bool SP2 = false, bool A_TILED = false>
; __device__ __forceinline__ void gemm_phase(PG8_LAS unsigned char* lds, const Gemm g, const Sched& S, const Epi& E) {
;     ...
;             PG8_LDB(B0, 1, 0); PG8_LDB(B1, 1, 1); PG8_SCHED; PG8_LDA(At, 1, 0); PG8_STAGE(PG8_SA(0, 1), a2 + hstepA, voffA);
;             PG8_WAIT_V(8); PG8_WAIT_L(0); PG8_BAR; PG8_MMA(0, 0, At, B0); PG8_MMA(0, 1, At, B1); PG8_BAR; PG8_SCHED;
;             PG8_LDA(At, 1, 1); PG8_STAGE(PG8_SB(1, 0), b3, voffB); PG8_STAGE(PG8_SB(1, 1), b3 + hstepB, voffB); PG8_STAGE(PG8_SA(1, 0), a3, voffA);
;             PG8_WAIT_V(8); PG8_WAIT_L(0); PG8_BAR; PG8_MMA(1, 0, At, B0); PG8_MMA(1, 1, At, B1); PG8_BAR; PG8_SCHED;
;     ...
;         }
;         if constexpr (ALIGN_EPI) { if (wr == 0) PG8_BAR; }
	s_setprio 0
	s_add_i32 s59, 0, 0x18000
	s_add_i32 s60, 0, 0x1c000
	ds_read_b128 v[142:145], v156 offset:32768
	ds_read_b128 v[146:149], v156 offset:33792
	ds_read_b128 v[150:153], v156 offset:34816
	ds_read_b128 v[160:163], v156 offset:35840
	ds_read_b128 v[164:167], v156 offset:49152
	ds_read_b128 v[168:171], v156 offset:50176
	ds_read_b128 v[172:175], v156 offset:51200
	ds_read_b128 v[176:179], v156 offset:52224
	s_add_u32 s28, s28, 0x4000
	s_addc_u32 s29, s29, 0
	s_mov_b32 m0, s37
	ds_read_b128 v[180:183], v158 offset:32768
	ds_read_b128 v[184:187], v158 offset:33792
	ds_read_b128 v[188:191], v158 offset:34816
	ds_read_b128 v[192:195], v158 offset:35840
	ds_read_b128 v[196:199], v158 offset:36864
	ds_read_b128 v[200:203], v158 offset:37888
	ds_read_b128 v[204:207], v158 offset:38912
	ds_read_b128 v[208:211], v158 offset:39936
	global_load_lds_dwordx4 v130, s[28:29]
	s_mov_b32 m0, s38
	s_nop 0
	global_load_lds_dwordx4 v132, s[28:29]
	s_waitcnt vmcnt(8)
	s_waitcnt lgkmcnt(0)
	s_setprio 1
	s_barrier
	v_mfma_f32_16x16x32_bf16 v[126:129], v[142:145], v[180:183], v[126:129]
	v_mfma_f32_16x16x32_bf16 v[126:129], v[146:149], v[184:187], v[126:129]
	v_mfma_f32_16x16x32_bf16 v[122:125], v[150:153], v[180:183], v[122:125]
	v_mfma_f32_16x16x32_bf16 v[122:125], v[160:163], v[184:187], v[122:125]
	v_mfma_f32_16x16x32_bf16 v[110:113], v[164:167], v[180:183], v[110:113]
	v_mfma_f32_16x16x32_bf16 v[110:113], v[168:171], v[184:187], v[110:113]
	v_mfma_f32_16x16x32_bf16 v[106:109], v[172:175], v[180:183], v[106:109]
	v_mfma_f32_16x16x32_bf16 v[106:109], v[176:179], v[184:187], v[106:109]
	v_mfma_f32_16x16x32_bf16 v[118:121], v[142:145], v[188:191], v[118:121]
	v_mfma_f32_16x16x32_bf16 v[118:121], v[146:149], v[192:195], v[118:121]
	v_mfma_f32_16x16x32_bf16 v[114:117], v[150:153], v[188:191], v[114:117]
	v_mfma_f32_16x16x32_bf16 v[114:117], v[160:163], v[192:195], v[114:117]
	v_mfma_f32_16x16x32_bf16 v[102:105], v[164:167], v[188:191], v[102:105]
	v_mfma_f32_16x16x32_bf16 v[102:105], v[168:171], v[192:195], v[102:105]
	v_mfma_f32_16x16x32_bf16 v[98:101], v[172:175], v[188:191], v[98:101]
	v_mfma_f32_16x16x32_bf16 v[98:101], v[176:179], v[192:195], v[98:101]
	v_mfma_f32_16x16x32_bf16 v[94:97], v[142:145], v[196:199], v[94:97]
	v_mfma_f32_16x16x32_bf16 v[94:97], v[146:149], v[200:203], v[94:97]
	v_mfma_f32_16x16x32_bf16 v[90:93], v[150:153], v[196:199], v[90:93]
	v_mfma_f32_16x16x32_bf16 v[90:93], v[160:163], v[200:203], v[90:93]
	v_mfma_f32_16x16x32_bf16 v[78:81], v[164:167], v[196:199], v[78:81]
	v_mfma_f32_16x16x32_bf16 v[78:81], v[168:171], v[200:203], v[78:81]
	v_mfma_f32_16x16x32_bf16 v[74:77], v[172:175], v[196:199], v[74:77]
	v_mfma_f32_16x16x32_bf16 v[74:77], v[176:179], v[200:203], v[74:77]
	v_mfma_f32_16x16x32_bf16 v[86:89], v[142:145], v[204:207], v[86:89]
	v_mfma_f32_16x16x32_bf16 v[86:89], v[146:149], v[208:211], v[86:89]
	v_mfma_f32_16x16x32_bf16 v[82:85], v[150:153], v[204:207], v[82:85]
	v_mfma_f32_16x16x32_bf16 v[82:85], v[160:163], v[208:211], v[82:85]
	v_mfma_f32_16x16x32_bf16 v[70:73], v[164:167], v[204:207], v[70:73]
	v_mfma_f32_16x16x32_bf16 v[70:73], v[168:171], v[208:211], v[70:73]
	v_mfma_f32_16x16x32_bf16 v[66:69], v[172:175], v[204:207], v[66:69]
	v_mfma_f32_16x16x32_bf16 v[66:69], v[176:179], v[208:211], v[66:69]
	s_barrier
	s_setprio 0
	s_add_u32 s28, s26, 0x8000
	s_addc_u32 s29, s27, 0
	s_add_i32 s59, s59, s31
	s_mov_b32 m0, s59
	ds_read_b128 v[180:183], v158 offset:49152
	ds_read_b128 v[184:187], v158 offset:50176
	ds_read_b128 v[188:191], v158 offset:51200
	ds_read_b128 v[192:195], v158 offset:52224
	ds_read_b128 v[196:199], v158 offset:53248
	ds_read_b128 v[200:203], v158 offset:54272
	ds_read_b128 v[204:207], v158 offset:55296
	ds_read_b128 v[208:211], v158 offset:56320
	global_load_lds_dwordx4 v130, s[28:29]
	s_add_i32 m0, s59, 0x2000
	s_add_u32 s26, s26, 0xc000
	v_lshl_add_u64 v[212:213], s[28:29], 0, v[132:133]
	s_addc_u32 s27, s27, 0
	s_add_i32 s28, s60, s31
	global_load_lds_dwordx4 v[212:213], off
	s_mov_b32 m0, s28
	s_nop 0
	global_load_lds_dwordx4 v130, s[26:27]
	s_add_i32 m0, s28, 0x2000
	s_nop 0
	global_load_lds_dwordx4 v132, s[26:27]
	s_mov_b32 m0, s40
	s_nop 0
	global_load_lds_dwordx4 v130, s[24:25]
	s_mov_b32 m0, s41
	s_nop 0
	global_load_lds_dwordx4 v132, s[24:25]
	s_waitcnt vmcnt(8)
	s_waitcnt lgkmcnt(0)
	s_setprio 1
	s_barrier
	v_mfma_f32_16x16x32_bf16 v[62:65], v[142:145], v[180:183], v[62:65]
	v_mfma_f32_16x16x32_bf16 v[62:65], v[146:149], v[184:187], v[62:65]
	v_mfma_f32_16x16x32_bf16 v[58:61], v[150:153], v[180:183], v[58:61]
	v_mfma_f32_16x16x32_bf16 v[58:61], v[160:163], v[184:187], v[58:61]
	v_mfma_f32_16x16x32_bf16 v[50:53], v[164:167], v[180:183], v[50:53]
	v_mfma_f32_16x16x32_bf16 v[50:53], v[168:171], v[184:187], v[50:53]
	v_mfma_f32_16x16x32_bf16 v[42:45], v[172:175], v[180:183], v[42:45]
	v_mfma_f32_16x16x32_bf16 v[42:45], v[176:179], v[184:187], v[42:45]
	v_mfma_f32_16x16x32_bf16 v[54:57], v[142:145], v[188:191], v[54:57]
	v_mfma_f32_16x16x32_bf16 v[54:57], v[146:149], v[192:195], v[54:57]
	v_mfma_f32_16x16x32_bf16 v[46:49], v[150:153], v[188:191], v[46:49]
	v_mfma_f32_16x16x32_bf16 v[46:49], v[160:163], v[192:195], v[46:49]
	v_mfma_f32_16x16x32_bf16 v[34:37], v[164:167], v[188:191], v[34:37]
	v_mfma_f32_16x16x32_bf16 v[34:37], v[168:171], v[192:195], v[34:37]
	v_mfma_f32_16x16x32_bf16 v[26:29], v[172:175], v[188:191], v[26:29]
	v_mfma_f32_16x16x32_bf16 v[26:29], v[176:179], v[192:195], v[26:29]
	v_mfma_f32_16x16x32_bf16 v[38:41], v[142:145], v[196:199], v[38:41]
	v_mfma_f32_16x16x32_bf16 v[38:41], v[146:149], v[200:203], v[38:41]
	v_mfma_f32_16x16x32_bf16 v[30:33], v[150:153], v[196:199], v[30:33]
	v_mfma_f32_16x16x32_bf16 v[30:33], v[160:163], v[200:203], v[30:33]
	v_mfma_f32_16x16x32_bf16 v[18:21], v[164:167], v[196:199], v[18:21]
	v_mfma_f32_16x16x32_bf16 v[18:21], v[168:171], v[200:203], v[18:21]
	v_mfma_f32_16x16x32_bf16 v[10:13], v[172:175], v[196:199], v[10:13]
	v_mfma_f32_16x16x32_bf16 v[10:13], v[176:179], v[200:203], v[10:13]
	v_mfma_f32_16x16x32_bf16 v[22:25], v[142:145], v[204:207], v[22:25]
	v_mfma_f32_16x16x32_bf16 v[22:25], v[146:149], v[208:211], v[22:25]
	v_mfma_f32_16x16x32_bf16 v[14:17], v[150:153], v[204:207], v[14:17]
	v_mfma_f32_16x16x32_bf16 v[14:17], v[160:163], v[208:211], v[14:17]
	v_mfma_f32_16x16x32_bf16 v[6:9], v[164:167], v[204:207], v[6:9]
	v_mfma_f32_16x16x32_bf16 v[6:9], v[168:171], v[208:211], v[6:9]
	v_mfma_f32_16x16x32_bf16 v[2:5], v[172:175], v[204:207], v[2:5]
	v_mfma_f32_16x16x32_bf16 v[2:5], v[176:179], v[208:211], v[2:5]
	s_barrier
	s_setprio 0
	s_add_i32 s58, s58, 2
	s_add_u32 s22, s22, 0x10000
	s_addc_u32 s23, s23, 0
	s_add_u32 s56, s56, 0x10000
	s_addc_u32 s57, s57, 0
	s_cmpk_gt_u32 s58, 0xa9
	s_cbranch_scc0 .LBB0_1247
	s_and_b64 vcc, exec, s[10:11]
	s_cbranch_vccz .LBB0_1250
	s_barrier
